# wide-store prompt xattn epilogue, rcp for sigmoid/gelu denominators, sattn K loads both maps in flight + page row, 1 sample-attn unit before prompt attn on CUs>=128, rms gain loads hoisted, S5 C stagi
# speedup vs baseline: 1.0209x; 1.0209x over previous
; #define GAS __attribute__((address_space(1)))
; __device__ __forceinline__ unsigned pk2(float lo, float hi) { const f32x2pk v = {lo, hi}; return __builtin_bit_cast(unsigned, __builtin_convertvector(v, bf16x2pk)); }
; __device__ __forceinline__ void rms_row_to_bf16(const float* xrow, const float* g, bf16* orow, int lane) {
;     const GAS f32x4* xr = (const GAS f32x4*)xrow + lane; const GAS f32x4* gr = (const GAS f32x4*)g + lane;
;     f32x4 v[4]; float s = 0.f;
; #pragma unroll
;     for (int j = 0; j < 4; ++j) { v[j] = xr[64 * j]; s += (v[j].x * v[j].x + v[j].y * v[j].y) + (v[j].z * v[j].z + v[j].w * v[j].w); }
;     const float rinv = 1.f / sqrtf(wave_sum(s) * (1.f / DMODEL) + EPS);
;     GAS unsigned long long* o8 = (GAS unsigned long long*)orow + lane;
; #pragma unroll
;     for (int j = 0; j < 4; ++j) { const f32x4 gg = gr[64 * j]; const f32x4 y = v[j] * rinv * gg;
;         o8[64 * j] = (unsigned long long)pk2(y.x, y.y) | ((unsigned long long)pk2(y.z, y.w) << 32); }
; }
; __global__ void __launch_bounds__(512, 2) mk_fwd(Args a) {
;     ...
;         for (int m = gw; m < MTOT + MMEM; m += NGW) {
;             if (m < MP) rms_row_to_bf16(INF(I_XP) + (size_t)m * DMODEL, INF(I_LN1), (bf16*)(ws + WS_XN1) + (size_t)m * DMODEL, lane);
;             else if (m < MTOT) rms_row_to_bf16(INF(I_XS) + (size_t)(m - MP) * DMODEL, INF(I_LN1), (bf16*)(ws + WS_XN1) + (size_t)m * DMODEL, lane);
;             else rms_row_to_bf16(INF(I_MEM) + (size_t)(m - MTOT) * DMODEL, INF(I_MEMG), (bf16*)(ws + WS_MN) + (size_t)(m - MTOT) * DMODEL, lane);
;         }
.LBB0_124:
	s_add_i32 s3, s2, 0x4200
	s_cmpk_gt_i32 s3, 0x3fff
	s_mov_b64 s[0:1], -1
	s_cbranch_scc0 .LBB0_130
	s_cmpk_gt_u32 s3, 0x41ff
	s_cbranch_scc0 .LBB0_127
	s_mov_b32 s3, s11
	s_lshl_b64 s[0:1], s[2:3], 12
	v_lshl_add_u64 v[22:23], v[6:7], 0, s[0:1]
	global_load_dwordx4 v[2:5], v[22:23], off
	global_load_dwordx4 v[26:29], v[22:23], off offset:1024
	global_load_dwordx4 v[30:33], v[22:23], off offset:2048
	global_load_dwordx4 v[34:37], v[22:23], off offset:3072
	global_load_dwordx4 v[38:41], v[8:9], off
	global_load_dwordx4 v[130:133], v[8:9], off offset:1024
	global_load_dwordx4 v[134:137], v[8:9], off offset:2048
	global_load_dwordx4 v[138:141], v[8:9], off offset:3072
	v_mov_b32_e32 v22, 0
	v_mov_b32_e32 v23, 0
	s_lshl_b64 s[20:21], s[2:3], 11
	s_waitcnt vmcnt(7)
	v_mul_f32_e32 v42, v3, v3
	v_mul_f32_e32 v43, v5, v5
	s_waitcnt vmcnt(6)
	v_mul_f32_e32 v44, v27, v27
	v_mul_f32_e32 v45, v29, v29
	s_waitcnt vmcnt(5)
	v_mul_f32_e32 v46, v31, v31
	v_mul_f32_e32 v47, v33, v33
	v_fmac_f32_e32 v42, v2, v2
	v_fmac_f32_e32 v43, v4, v4
	v_fmac_f32_e32 v44, v26, v26
	v_fmac_f32_e32 v45, v28, v28
	s_waitcnt vmcnt(4)
	v_mul_f32_e32 v48, v35, v35
	v_mul_f32_e32 v49, v37, v37
	v_fmac_f32_e32 v46, v30, v30
	v_fmac_f32_e32 v47, v32, v32
	v_add_f32_e32 v42, v42, v43
	v_add_f32_e32 v43, v44, v45
	v_fmac_f32_e32 v48, v34, v34
	v_fmac_f32_e32 v49, v36, v36
	v_add_f32_e32 v44, v46, v47
	v_add_f32_e32 v42, v42, v43
	v_add_f32_e32 v45, v48, v49
	v_add_f32_e32 v42, v42, v44
	v_add_f32_e32 v42, v42, v45
	s_nop 1
	v_add_f32_dpp v42, v42, v42 row_shr:1 row_mask:0xf bank_mask:0xf bound_ctrl:1
	s_nop 1
	v_add_f32_dpp v42, v42, v42 row_shr:2 row_mask:0xf bank_mask:0xf bound_ctrl:1
	s_nop 1
	v_add_f32_dpp v42, v42, v42 row_shr:4 row_mask:0xf bank_mask:0xf bound_ctrl:1
	s_nop 1
	v_add_f32_dpp v42, v42, v42 row_shr:8 row_mask:0xf bank_mask:0xf bound_ctrl:1
	s_nop 1
	v_mov_b32_dpp v22, v42 row_bcast:15 row_mask:0xa bank_mask:0xf
	v_add_f32_e32 v22, v42, v22
	s_nop 1
	v_mov_b32_dpp v23, v22 row_bcast:31 row_mask:0xc bank_mask:0xf
	v_add_f32_e32 v22, v22, v23
	s_nop 0
	v_readlane_b32 s0, v22, 63
	s_nop 1
	v_fma_f32 v22, s0, v25, v1
	v_mul_f32_e32 v23, 0x4f800000, v22
	v_cmp_gt_f32_e32 vcc, s13, v22
	s_nop 1
	v_cndmask_b32_e32 v22, v22, v23, vcc
	v_sqrt_f32_e32 v23, v22
	s_nop 0
	v_add_u32_e32 v42, -1, v23
	v_add_u32_e32 v43, 1, v23
	v_fma_f32 v44, -v42, v23, v22
	v_fma_f32 v45, -v43, v23, v22
	v_cmp_ge_f32_e64 s[0:1], 0, v44
	s_nop 1
	v_cndmask_b32_e64 v23, v23, v42, s[0:1]
	v_cmp_lt_f32_e64 s[0:1], 0, v45
	s_nop 1
	v_cndmask_b32_e64 v23, v23, v43, s[0:1]
	v_mul_f32_e32 v42, 0x37800000, v23
	v_cndmask_b32_e32 v23, v23, v42, vcc
	v_cmp_class_f32_e32 vcc, v22, v24
	s_nop 1
	v_cndmask_b32_e32 v42, v23, v22, vcc
	v_div_scale_f32 v43, s[0:1], v42, v42, 1.0
	v_rcp_f32_e32 v44, v43
	v_div_scale_f32 v45, vcc, 1.0, v42, 1.0
	v_lshl_add_u64 v[22:23], v[10:11], 0, s[20:21]
	v_fma_f32 v46, -v43, v44, 1.0
	v_fmac_f32_e32 v44, v46, v44
	v_mul_f32_e32 v46, v45, v44
	v_fma_f32 v47, -v43, v46, v45
	v_fmac_f32_e32 v46, v47, v44
	v_fma_f32 v43, -v43, v46, v45
	v_div_fmas_f32 v43, v43, v44, v46
	v_div_fixup_f32 v42, v43, v42, 1.0
	v_pk_mul_f32 v[2:3], v[2:3], v[42:43] op_sel_hi:[1,0]
	v_pk_mul_f32 v[4:5], v[4:5], v[42:43] op_sel_hi:[1,0]
	s_waitcnt vmcnt(3)
	v_pk_mul_f32 v[2:3], v[38:39], v[2:3]
	v_pk_mul_f32 v[4:5], v[40:41], v[4:5]
	v_cvt_pk_bf16_f32 v2, v2, v3
	v_cvt_pk_bf16_f32 v3, v4, v5
	global_store_dwordx2 v[22:23], v[2:3], off
	v_pk_mul_f32 v[26:27], v[26:27], v[42:43] op_sel_hi:[1,0]
	v_pk_mul_f32 v[28:29], v[28:29], v[42:43] op_sel_hi:[1,0]
	s_mov_b64 s[0:1], 0
	s_waitcnt vmcnt(3)
	v_pk_mul_f32 v[4:5], v[132:133], v[28:29]
	v_pk_mul_f32 v[2:3], v[130:131], v[26:27]
	v_pk_mul_f32 v[26:27], v[30:31], v[42:43] op_sel_hi:[1,0]
	v_cvt_pk_bf16_f32 v2, v2, v3
	v_cvt_pk_bf16_f32 v3, v4, v5
	global_store_dwordx2 v[22:23], v[2:3], off offset:512
	v_pk_mul_f32 v[28:29], v[32:33], v[42:43] op_sel_hi:[1,0]
	s_waitcnt vmcnt(3)
	v_pk_mul_f32 v[2:3], v[134:135], v[26:27]
	v_pk_mul_f32 v[4:5], v[136:137], v[28:29]
	v_cvt_pk_bf16_f32 v2, v2, v3
	v_cvt_pk_bf16_f32 v3, v4, v5
	global_store_dwordx2 v[22:23], v[2:3], off offset:1024
	v_pk_mul_f32 v[26:27], v[36:37], v[42:43] op_sel_hi:[1,0]
	v_pk_mul_f32 v[28:29], v[34:35], v[42:43] op_sel_hi:[1,0]
	s_waitcnt vmcnt(3)
	v_pk_mul_f32 v[4:5], v[26:27], v[140:141]
	v_pk_mul_f32 v[2:3], v[28:29], v[138:139]
; #define GAS __attribute__((address_space(1)))
; __device__ __forceinline__ unsigned pk2(float lo, float hi) { const f32x2pk v = {lo, hi}; return __builtin_bit_cast(unsigned, __builtin_convertvector(v, bf16x2pk)); }
; __device__ __forceinline__ void rms_row_to_bf16(const float* xrow, const float* g, bf16* orow, int lane) {
;     const GAS f32x4* xr = (const GAS f32x4*)xrow + lane; const GAS f32x4* gr = (const GAS f32x4*)g + lane;
;     f32x4 v[4]; float s = 0.f;
; #pragma unroll
;     for (int j = 0; j < 4; ++j) { v[j] = xr[64 * j]; s += (v[j].x * v[j].x + v[j].y * v[j].y) + (v[j].z * v[j].z + v[j].w * v[j].w); }
;     const float rinv = 1.f / sqrtf(wave_sum(s) * (1.f / DMODEL) + EPS);
;     GAS unsigned long long* o8 = (GAS unsigned long long*)orow + lane;
; #pragma unroll
;     for (int j = 0; j < 4; ++j) { const f32x4 gg = gr[64 * j]; const f32x4 y = v[j] * rinv * gg;
;         o8[64 * j] = (unsigned long long)pk2(y.x, y.y) | ((unsigned long long)pk2(y.z, y.w) << 32); }
; }
.LBB0_127:
	s_andn2_b64 vcc, exec, s[0:1]
	s_cbranch_vccnz .LBB0_129
	s_add_i32 s10, s2, 0x200
	s_lshl_b64 s[0:1], s[10:11], 12
	v_lshl_add_u64 v[22:23], v[12:13], 0, s[0:1]
	global_load_dwordx4 v[2:5], v[22:23], off
	global_load_dwordx4 v[26:29], v[22:23], off offset:1024
	global_load_dwordx4 v[30:33], v[22:23], off offset:2048
	global_load_dwordx4 v[34:37], v[22:23], off offset:3072
	global_load_dwordx4 v[38:41], v[14:15], off
	global_load_dwordx4 v[130:133], v[14:15], off offset:1024
	global_load_dwordx4 v[134:137], v[14:15], off offset:2048
	global_load_dwordx4 v[138:141], v[14:15], off offset:3072
	v_mov_b32_e32 v22, 0
	v_mov_b32_e32 v23, 0
	s_mov_b32 s5, s11
	s_waitcnt vmcnt(7)
	v_mul_f32_e32 v42, v3, v3
	v_mul_f32_e32 v43, v5, v5
	s_waitcnt vmcnt(6)
	v_mul_f32_e32 v44, v27, v27
	v_mul_f32_e32 v45, v29, v29
	s_waitcnt vmcnt(5)
	v_mul_f32_e32 v46, v31, v31
	v_mul_f32_e32 v47, v33, v33
	v_fmac_f32_e32 v42, v2, v2
	v_fmac_f32_e32 v43, v4, v4
	v_fmac_f32_e32 v44, v26, v26
	v_fmac_f32_e32 v45, v28, v28
	s_waitcnt vmcnt(4)
	v_mul_f32_e32 v48, v35, v35
	v_mul_f32_e32 v49, v37, v37
	v_fmac_f32_e32 v46, v30, v30
	v_fmac_f32_e32 v47, v32, v32
	v_add_f32_e32 v42, v42, v43
	v_add_f32_e32 v43, v44, v45
	v_fmac_f32_e32 v48, v34, v34
	v_fmac_f32_e32 v49, v36, v36
	v_add_f32_e32 v44, v46, v47
	v_add_f32_e32 v42, v42, v43
	v_add_f32_e32 v45, v48, v49
	v_add_f32_e32 v42, v42, v44
	v_add_f32_e32 v42, v42, v45
	s_nop 1
	v_add_f32_dpp v42, v42, v42 row_shr:1 row_mask:0xf bank_mask:0xf bound_ctrl:1
	s_nop 1
	v_add_f32_dpp v42, v42, v42 row_shr:2 row_mask:0xf bank_mask:0xf bound_ctrl:1
	s_nop 1
	v_add_f32_dpp v42, v42, v42 row_shr:4 row_mask:0xf bank_mask:0xf bound_ctrl:1
	s_nop 1
	v_add_f32_dpp v42, v42, v42 row_shr:8 row_mask:0xf bank_mask:0xf bound_ctrl:1
	s_nop 1
	v_mov_b32_dpp v22, v42 row_bcast:15 row_mask:0xa bank_mask:0xf
	v_add_f32_e32 v22, v42, v22
	s_nop 1
	v_mov_b32_dpp v23, v22 row_bcast:31 row_mask:0xc bank_mask:0xf
	v_add_f32_e32 v22, v22, v23
	s_nop 0
	v_readlane_b32 s0, v22, 63
	s_nop 1
	v_fma_f32 v22, s0, v25, v1
	v_mul_f32_e32 v23, 0x4f800000, v22
	v_cmp_gt_f32_e32 vcc, s13, v22
	s_nop 1
	v_cndmask_b32_e32 v22, v22, v23, vcc
	v_sqrt_f32_e32 v23, v22
	s_nop 0
	v_add_u32_e32 v42, -1, v23
	v_add_u32_e32 v43, 1, v23
	v_fma_f32 v44, -v42, v23, v22
	v_fma_f32 v45, -v43, v23, v22
	v_cmp_ge_f32_e64 s[0:1], 0, v44
	s_nop 1
	v_cndmask_b32_e64 v23, v23, v42, s[0:1]
	v_cmp_lt_f32_e64 s[0:1], 0, v45
	s_nop 1
	v_cndmask_b32_e64 v23, v23, v43, s[0:1]
	v_mul_f32_e32 v42, 0x37800000, v23
	v_cndmask_b32_e32 v23, v23, v42, vcc
	v_cmp_class_f32_e32 vcc, v22, v24
	s_nop 1
	v_cndmask_b32_e32 v42, v23, v22, vcc
	v_div_scale_f32 v43, s[0:1], v42, v42, 1.0
	v_rcp_f32_e32 v44, v43
	v_div_scale_f32 v45, vcc, 1.0, v42, 1.0
	v_lshl_add_u64 v[22:23], v[16:17], 0, s[4:5]
	v_fma_f32 v46, -v43, v44, 1.0
	v_fmac_f32_e32 v44, v46, v44
	v_mul_f32_e32 v46, v45, v44
	v_fma_f32 v47, -v43, v46, v45
	v_fmac_f32_e32 v46, v47, v44
	v_fma_f32 v43, -v43, v46, v45
	v_div_fmas_f32 v43, v43, v44, v46
	v_div_fixup_f32 v42, v43, v42, 1.0
	v_pk_mul_f32 v[2:3], v[2:3], v[42:43] op_sel_hi:[1,0]
	v_pk_mul_f32 v[4:5], v[4:5], v[42:43] op_sel_hi:[1,0]
	s_waitcnt vmcnt(3)
	v_pk_mul_f32 v[2:3], v[38:39], v[2:3]
	v_pk_mul_f32 v[4:5], v[40:41], v[4:5]
	v_cvt_pk_bf16_f32 v2, v2, v3
	v_cvt_pk_bf16_f32 v3, v4, v5
	global_store_dwordx2 v[22:23], v[2:3], off
	v_pk_mul_f32 v[26:27], v[26:27], v[42:43] op_sel_hi:[1,0]
	v_pk_mul_f32 v[28:29], v[28:29], v[42:43] op_sel_hi:[1,0]
	s_waitcnt vmcnt(3)
	v_pk_mul_f32 v[2:3], v[130:131], v[26:27]
	v_pk_mul_f32 v[4:5], v[132:133], v[28:29]
	v_cvt_pk_bf16_f32 v2, v2, v3
	v_cvt_pk_bf16_f32 v3, v4, v5
	global_store_dwordx2 v[22:23], v[2:3], off offset:512
	v_pk_mul_f32 v[26:27], v[30:31], v[42:43] op_sel_hi:[1,0]
	v_pk_mul_f32 v[28:29], v[32:33], v[42:43] op_sel_hi:[1,0]
	s_waitcnt vmcnt(3)
	v_pk_mul_f32 v[2:3], v[134:135], v[26:27]
	v_pk_mul_f32 v[4:5], v[136:137], v[28:29]
	v_cvt_pk_bf16_f32 v2, v2, v3
	v_cvt_pk_bf16_f32 v3, v4, v5
	global_store_dwordx2 v[22:23], v[2:3], off offset:1024
	v_pk_mul_f32 v[26:27], v[36:37], v[42:43] op_sel_hi:[1,0]
	v_pk_mul_f32 v[28:29], v[34:35], v[42:43] op_sel_hi:[1,0]
	s_waitcnt vmcnt(3)
	v_pk_mul_f32 v[4:5], v[26:27], v[140:141]
	v_pk_mul_f32 v[2:3], v[28:29], v[138:139]

; #define GAS __attribute__((address_space(1)))
; __device__ __forceinline__ unsigned pk2(float lo, float hi) { const f32x2pk v = {lo, hi}; return __builtin_bit_cast(unsigned, __builtin_convertvector(v, bf16x2pk)); }
; __device__ __forceinline__ void rms_row_to_bf16(const float* xrow, const float* g, bf16* orow, int lane) {
;     const GAS f32x4* xr = (const GAS f32x4*)xrow + lane; const GAS f32x4* gr = (const GAS f32x4*)g + lane;
;     f32x4 v[4]; float s = 0.f;
; #pragma unroll
;     for (int j = 0; j < 4; ++j) { v[j] = xr[64 * j]; s += (v[j].x * v[j].x + v[j].y * v[j].y) + (v[j].z * v[j].z + v[j].w * v[j].w); }
;     const float rinv = 1.f / sqrtf(wave_sum(s) * (1.f / DMODEL) + EPS);
;     GAS unsigned long long* o8 = (GAS unsigned long long*)orow + lane;
; #pragma unroll
;     for (int j = 0; j < 4; ++j) { const f32x4 gg = gr[64 * j]; const f32x4 y = v[j] * rinv * gg;
;         o8[64 * j] = (unsigned long long)pk2(y.x, y.y) | ((unsigned long long)pk2(y.z, y.w) << 32); }
; }
.LBB0_130:
	s_andn2_b64 vcc, exec, s[0:1]
	s_cbranch_vccnz .LBB0_123
	global_load_dwordx4 v[2:5], v[20:21], off offset:-3072
	global_load_dwordx4 v[26:29], v[20:21], off offset:-2048
	global_load_dwordx4 v[30:33], v[20:21], off offset:-1024
	global_load_dwordx4 v[34:37], v[20:21], off
	global_load_dwordx4 v[38:41], v[14:15], off
	global_load_dwordx4 v[130:133], v[14:15], off offset:1024
	global_load_dwordx4 v[134:137], v[14:15], off offset:2048
	global_load_dwordx4 v[138:141], v[14:15], off offset:3072
	v_mov_b32_e32 v22, 0
	v_mov_b32_e32 v23, 0
	s_waitcnt vmcnt(7)
	v_mul_f32_e32 v42, v3, v3
	v_mul_f32_e32 v43, v5, v5
	s_waitcnt vmcnt(6)
	v_mul_f32_e32 v44, v27, v27
	v_mul_f32_e32 v45, v29, v29
	s_waitcnt vmcnt(5)
	v_mul_f32_e32 v46, v31, v31
	v_mul_f32_e32 v47, v33, v33
	v_fmac_f32_e32 v42, v2, v2
	v_fmac_f32_e32 v43, v4, v4
	v_fmac_f32_e32 v44, v26, v26
	v_fmac_f32_e32 v45, v28, v28
	s_waitcnt vmcnt(4)
	v_mul_f32_e32 v48, v35, v35
	v_mul_f32_e32 v49, v37, v37
	v_fmac_f32_e32 v46, v30, v30
	v_fmac_f32_e32 v47, v32, v32
	v_add_f32_e32 v42, v42, v43
	v_add_f32_e32 v43, v44, v45
	v_fmac_f32_e32 v48, v34, v34
	v_fmac_f32_e32 v49, v36, v36
	v_add_f32_e32 v44, v46, v47
	v_add_f32_e32 v42, v42, v43
	v_add_f32_e32 v45, v48, v49
	v_add_f32_e32 v42, v42, v44
	v_add_f32_e32 v42, v42, v45
	s_nop 1
	v_add_f32_dpp v42, v42, v42 row_shr:1 row_mask:0xf bank_mask:0xf bound_ctrl:1
	s_nop 1
	v_add_f32_dpp v42, v42, v42 row_shr:2 row_mask:0xf bank_mask:0xf bound_ctrl:1
	s_nop 1
	v_add_f32_dpp v42, v42, v42 row_shr:4 row_mask:0xf bank_mask:0xf bound_ctrl:1
	s_nop 1
	v_add_f32_dpp v42, v42, v42 row_shr:8 row_mask:0xf bank_mask:0xf bound_ctrl:1
	s_nop 1
	v_mov_b32_dpp v22, v42 row_bcast:15 row_mask:0xa bank_mask:0xf
	v_add_f32_e32 v22, v42, v22
	s_nop 1
	v_mov_b32_dpp v23, v22 row_bcast:31 row_mask:0xc bank_mask:0xf
	v_add_f32_e32 v22, v22, v23
	s_nop 0
	v_readlane_b32 s0, v22, 63
	s_nop 1
	v_fma_f32 v22, s0, v25, v1
	v_mul_f32_e32 v23, 0x4f800000, v22
	v_cmp_gt_f32_e32 vcc, s13, v22
	s_nop 1
	v_cndmask_b32_e32 v22, v22, v23, vcc
	v_sqrt_f32_e32 v23, v22
	s_nop 0
	v_add_u32_e32 v42, -1, v23
	v_add_u32_e32 v43, 1, v23
	v_fma_f32 v44, -v42, v23, v22
	v_fma_f32 v45, -v43, v23, v22
	v_cmp_ge_f32_e64 s[0:1], 0, v44
	s_nop 1
	v_cndmask_b32_e64 v23, v23, v42, s[0:1]
	v_cmp_lt_f32_e64 s[0:1], 0, v45
	s_nop 1
	v_cndmask_b32_e64 v23, v23, v43, s[0:1]
	v_mul_f32_e32 v42, 0x37800000, v23
	v_cndmask_b32_e32 v23, v23, v42, vcc
	v_cmp_class_f32_e32 vcc, v22, v24
	s_nop 1
	v_cndmask_b32_e32 v22, v23, v22, vcc
	v_div_scale_f32 v23, s[0:1], v22, v22, 1.0
	v_rcp_f32_e32 v42, v23
	v_div_scale_f32 v43, vcc, 1.0, v22, 1.0
	v_fma_f32 v44, -v23, v42, 1.0
	v_fmac_f32_e32 v42, v44, v42
	v_mul_f32_e32 v44, v43, v42
	v_fma_f32 v45, -v23, v44, v43
	v_fmac_f32_e32 v44, v45, v42
	v_fma_f32 v23, -v23, v44, v43
	v_div_fmas_f32 v23, v23, v42, v44
	v_div_fixup_f32 v22, v23, v22, 1.0
	v_pk_mul_f32 v[2:3], v[2:3], v[22:23] op_sel_hi:[1,0]
	v_pk_mul_f32 v[4:5], v[4:5], v[22:23] op_sel_hi:[1,0]
	s_waitcnt vmcnt(3)
	v_pk_mul_f32 v[2:3], v[38:39], v[2:3]
	v_pk_mul_f32 v[4:5], v[40:41], v[4:5]
	v_cvt_pk_bf16_f32 v2, v2, v3
	v_cvt_pk_bf16_f32 v3, v4, v5
	global_store_dwordx2 v[18:19], v[2:3], off
	v_pk_mul_f32 v[26:27], v[26:27], v[22:23] op_sel_hi:[1,0]
	v_pk_mul_f32 v[28:29], v[28:29], v[22:23] op_sel_hi:[1,0]
	s_waitcnt vmcnt(3)
	v_pk_mul_f32 v[2:3], v[130:131], v[26:27]
	v_pk_mul_f32 v[4:5], v[132:133], v[28:29]
	v_cvt_pk_bf16_f32 v2, v2, v3
	v_cvt_pk_bf16_f32 v3, v4, v5
	global_store_dwordx2 v[18:19], v[2:3], off offset:512
	v_pk_mul_f32 v[26:27], v[30:31], v[22:23] op_sel_hi:[1,0]
	v_pk_mul_f32 v[28:29], v[32:33], v[22:23] op_sel_hi:[1,0]
	s_waitcnt vmcnt(3)
	v_pk_mul_f32 v[2:3], v[134:135], v[26:27]
	v_pk_mul_f32 v[4:5], v[136:137], v[28:29]
	v_cvt_pk_bf16_f32 v2, v2, v3
	v_cvt_pk_bf16_f32 v3, v4, v5
	global_store_dwordx2 v[18:19], v[2:3], off offset:1024
	v_pk_mul_f32 v[26:27], v[36:37], v[22:23] op_sel_hi:[1,0]
	v_pk_mul_f32 v[22:23], v[34:35], v[22:23] op_sel_hi:[1,0]
	s_waitcnt vmcnt(3)
	v_pk_mul_f32 v[4:5], v[26:27], v[140:141]
	v_pk_mul_f32 v[2:3], v[22:23], v[138:139]
	v_mov_b64_e32 v[22:23], v[18:19]
	s_branch .LBB0_123

; __global__ void __launch_bounds__(512, 2) mk_fwd(Args a) {
;     ...
;     if (IN(2)) {
;         __syncthreads();
;         { pg8::Gemm g{(const bf16*)(ws + WS_MN), (const bf16*)(ws + WS_WKV), MMEM, 2048, DMODEL}; pg8::StaticOrder S; S.init(MMEM, 2048, G, (bid + G - G / 2) % G);
.LBB0_319:
	s_mov_b32 s0, 0
	v_writelane_b32 v255, s0, 50
	s_cmp_lt_i32 s10, 3
	s_cselect_b64 s[0:1], -1, 0
	s_cmp_gt_i32 s11, 2
	s_cselect_b64 s[2:3], -1, 0
	s_and_b64 s[0:1], s[0:1], s[2:3]
	s_andn2_b64 vcc, exec, s[0:1]
	s_cbranch_vccnz .LBB0_561
	s_abs_i32 s0, s75
	v_cvt_f32_u32_e32 v1, s0
	s_lshr_b32 s2, s75, 31
	s_add_i32 s2, s75, s2
	s_sub_i32 s3, 0, s0
	v_rcp_iflag_f32_e32 v1, v1
	s_add_i32 s1, s75, s96
	s_ashr_i32 s2, s2, 1
	s_sub_i32 s1, s1, s2
	v_mul_f32_e32 v1, 0x4f7ffffe, v1
	v_cvt_u32_f32_e32 v1, v1
	s_ashr_i32 s2, s1, 31
	s_abs_i32 s1, s1
	v_readfirstlane_b32 s10, v0
	v_readfirstlane_b32 s4, v1
	s_mul_i32 s3, s3, s4
	s_mul_hi_u32 s3, s4, s3
	s_add_i32 s4, s4, s3
	s_mul_hi_u32 s3, s1, s4
	s_mul_i32 s3, s3, s0
	s_sub_i32 s1, s1, s3
	s_sub_i32 s3, s1, s0
	s_cmp_ge_u32 s1, s0
	s_cselect_b32 s1, s3, s1
	s_sub_i32 s3, s1, s0
	s_cmp_ge_u32 s1, s0
	s_cselect_b32 s0, s3, s1
	s_xor_b32 s0, s0, s2
	s_sub_i32 s13, s0, s2
	s_cmp_lt_i32 s13, 32
	s_cselect_b64 s[0:1], -1, 0
	s_cmp_gt_i32 s13, 31
	s_waitcnt lgkmcnt(0)
	s_barrier
	s_cbranch_scc1 .LBB0_326
	s_ashr_i32 s2, s13, 31
	s_lshr_b32 s2, s2, 29
	s_add_i32 s6, s13, s2
	s_and_b32 s2, s6, -8
	s_sub_i32 s4, s13, s2
	s_cmp_gt_i32 s4, -1
	s_cbranch_scc0 .LBB0_323
	s_lshl_b32 s5, s4, 2
	s_ashr_i32 s2, s6, 3
	s_cbranch_execz .LBB0_324
	s_branch .LBB0_325

; __device__ __forceinline__ unsigned pk2(float lo, float hi) { const f32x2pk v = {lo, hi}; return __builtin_bit_cast(unsigned, __builtin_convertvector(v, bf16x2pk)); }
; __device__ __forceinline__ float gelu_tanh(float x) {
;     const float z = 0.7978845608028654f * (x + 0.044715f * x * x * x);
;     return x / (1.f + __builtin_amdgcn_exp2f(-2.f * LOG2E * z));
; }
; __device__ __forceinline__ void ssm_prompt_item(const bf16* UG, const bf16* TQ, const bf16* PM, const float* SF, bf16* Gb, float* out, int b, int g, LAS unsigned char* lds, int tid) {
;     ...
;               for (int q = 0; q < 4; ++q) { const f32x16& A = nb ? acc1 : acc0; const int t = 2 * w + (q >> 1), c0 = 8 * (q & 1) + 4 * hi; const size_t tok = tok0 + (size_t)(32 * nb + r32) * 16 + t;
;                   u32x2 o; o.x = pk2(gelu_tanh(A[4 * q]), gelu_tanh(A[4 * q + 1])); o.y = pk2(gelu_tanh(A[4 * q + 2]), gelu_tanh(A[4 * q + 3]));
;                   *(u32x2*)(Gb + tok * 512 + 16 * g + c0) = o; }
.LBB0_405:
	s_nop 7
	v_mul_f32_e32 v182, 0x3d372713, v18
	v_mul_f32_e32 v183, 0x3d372713, v19
	v_mul_f32_e32 v182, v18, v182
	v_mul_f32_e32 v183, v19, v183
	v_fma_f32 v182, v18, v182, v18
	v_fma_f32 v183, v19, v183, v19
	v_mul_f32_e32 v182, 0x3f4c422a, v182
	v_mul_f32_e32 v183, 0x3f4c422a, v183
	v_mul_f32_e32 v182, 0xc038aa3b, v182
	v_mul_f32_e32 v183, 0xc038aa3b, v183
	v_exp_f32_e32 v182, v182
	v_exp_f32_e32 v183, v183
	v_lshl_or_b32 v214, s5, 10, v242
	v_lshl_add_u64 v[178:179], s[10:11], 0, v[214:215]
	v_lshl_add_u64 v[180:181], v[178:179], 0, s[2:3]
	v_pk_add_f32 v[182:183], v[182:183], 1.0 op_sel_hi:[1,0]
	v_or_b32_e32 v214, 0x200, v214
	s_add_i32 s5, s5, 1
	s_cmp_eq_u32 s5, 4
	v_rcp_f32_e32 v185, v183
	s_nop 0
	v_mul_f32_e32 v19, v19, v185
	s_nop 0
	v_rcp_f32_e32 v184, v182
	s_nop 0
	v_mul_f32_e32 v18, v18, v184
	v_cvt_pk_bf16_f32 v18, v18, v19
	v_mul_f32_e32 v19, 0x3d372713, v20
	v_mul_f32_e32 v19, v20, v19
	v_fma_f32 v19, v20, v19, v20
	v_mul_f32_e32 v19, 0x3f4c422a, v19
	v_mul_f32_e32 v19, 0xc038aa3b, v19
	v_exp_f32_e32 v182, v19
	v_mul_f32_e32 v19, 0x3d372713, v21
	v_mul_f32_e32 v19, v21, v19
	v_fma_f32 v19, v21, v19, v21
	v_mul_f32_e32 v19, 0x3f4c422a, v19
	v_mul_f32_e32 v19, 0xc038aa3b, v19
	v_exp_f32_e32 v183, v19
	s_nop 0
	v_pk_add_f32 v[182:183], v[182:183], 1.0 op_sel_hi:[1,0]
	s_nop 0
	s_nop 0
	v_rcp_f32_e32 v184, v183
	s_nop 0
	v_mul_f32_e32 v19, v21, v184
	s_nop 0
	v_rcp_f32_e32 v183, v182
	s_nop 0
	v_mul_f32_e32 v20, v20, v183
	v_cvt_pk_bf16_f32 v19, v20, v19
	v_lshlrev_b64 v[20:21], 10, v[180:181]
	v_lshl_add_u64 v[20:21], v[234:235], 0, v[20:21]
	global_store_dwordx2 v[20:21], v[18:19], off
	v_mul_f32_e32 v18, 0x3d372713, v22
	v_mul_f32_e32 v19, 0x3d372713, v23
	v_mul_f32_e32 v18, v22, v18
	v_mul_f32_e32 v19, v23, v19
	v_fma_f32 v18, v22, v18, v22
	v_fma_f32 v19, v23, v19, v23
	v_mul_f32_e32 v18, 0x3f4c422a, v18
	v_mul_f32_e32 v19, 0x3f4c422a, v19
	v_mul_f32_e32 v18, 0xc038aa3b, v18
	v_mul_f32_e32 v19, 0xc038aa3b, v19
	v_exp_f32_e32 v18, v18
	v_exp_f32_e32 v19, v19
	s_nop 0
	v_pk_add_f32 v[18:19], v[18:19], 1.0 op_sel_hi:[1,0]
	s_nop 0
	s_nop 0
	v_rcp_f32_e32 v181, v19
	s_nop 0
	v_mul_f32_e32 v19, v23, v181
	s_nop 0
	v_rcp_f32_e32 v180, v18
	s_nop 0
	v_mul_f32_e32 v18, v22, v180
	v_cvt_pk_bf16_f32 v18, v18, v19
	v_mul_f32_e32 v19, 0x3d372713, v24
	v_mul_f32_e32 v19, v24, v19
	v_fma_f32 v19, v24, v19, v24
	v_mul_f32_e32 v19, 0x3f4c422a, v19
	v_mul_f32_e32 v19, 0xc038aa3b, v19
	v_exp_f32_e32 v22, v19
	v_mul_f32_e32 v19, 0x3d372713, v25
	v_mul_f32_e32 v19, v25, v19
	v_fma_f32 v19, v25, v19, v25
	v_mul_f32_e32 v19, 0x3f4c422a, v19
	v_mul_f32_e32 v19, 0xc038aa3b, v19
	v_exp_f32_e32 v23, v19
	s_nop 0
	v_pk_add_f32 v[22:23], v[22:23], 1.0 op_sel_hi:[1,0]
	s_nop 0
	s_nop 0
	v_rcp_f32_e32 v180, v23
	s_nop 0
	v_mul_f32_e32 v19, v25, v180
	s_nop 0
	v_rcp_f32_e32 v25, v22
	s_nop 0
	v_mul_f32_e32 v22, v24, v25
	v_cvt_pk_bf16_f32 v19, v22, v19
	global_store_dwordx2 v[20:21], v[18:19], off offset:16
	v_mul_f32_e32 v20, 0x3d372713, v26
	v_mul_f32_e32 v21, 0x3d372713, v27
	v_mul_f32_e32 v20, v26, v20
	v_mul_f32_e32 v21, v27, v21
	v_fma_f32 v20, v26, v20, v26
	v_fma_f32 v21, v27, v21, v27
	v_mul_f32_e32 v20, 0x3f4c422a, v20
	v_mul_f32_e32 v21, 0x3f4c422a, v21
	v_mul_f32_e32 v20, 0xc038aa3b, v20
	v_mul_f32_e32 v21, 0xc038aa3b, v21
	v_exp_f32_e32 v20, v20
	v_exp_f32_e32 v21, v21
	v_lshl_add_u64 v[18:19], v[178:179], 0, s[20:21]
	v_lshlrev_b64 v[18:19], 10, v[18:19]
	v_lshl_add_u64 v[18:19], v[234:235], 0, v[18:19]
	v_pk_add_f32 v[20:21], v[20:21], 1.0 op_sel_hi:[1,0]
	s_nop 0
	s_nop 0
	v_rcp_f32_e32 v23, v21
	s_nop 0
	v_mul_f32_e32 v21, v27, v23
	s_nop 0
	v_rcp_f32_e32 v23, v20
	s_nop 0
	v_mul_f32_e32 v20, v26, v23
	v_cvt_pk_bf16_f32 v20, v20, v21
	v_mul_f32_e32 v21, 0x3d372713, v28
	v_mul_f32_e32 v21, v28, v21
	v_fma_f32 v21, v28, v21, v28
	v_mul_f32_e32 v21, 0x3f4c422a, v21
	v_mul_f32_e32 v21, 0xc038aa3b, v21
	v_exp_f32_e32 v22, v21
	v_mul_f32_e32 v21, 0x3d372713, v29
	v_mul_f32_e32 v21, v29, v21
	v_fma_f32 v21, v29, v21, v29
	v_mul_f32_e32 v21, 0x3f4c422a, v21
	v_mul_f32_e32 v21, 0xc038aa3b, v21
	v_exp_f32_e32 v23, v21
	s_nop 0
	v_pk_add_f32 v[22:23], v[22:23], 1.0 op_sel_hi:[1,0]
	s_nop 0
	s_nop 0
	v_rcp_f32_e32 v24, v23
	s_nop 0
	v_mul_f32_e32 v21, v29, v24
	s_nop 0
	v_rcp_f32_e32 v24, v22
	s_nop 0
	v_mul_f32_e32 v22, v28, v24
	v_cvt_pk_bf16_f32 v21, v22, v21
	global_store_dwordx2 v[18:19], v[20:21], off
	v_mul_f32_e32 v20, 0x3d372713, v30
	v_mul_f32_e32 v21, 0x3d372713, v31
	v_mul_f32_e32 v20, v30, v20
	v_mul_f32_e32 v21, v31, v21
	v_fma_f32 v20, v30, v20, v30
	v_fma_f32 v21, v31, v21, v31
	v_mul_f32_e32 v20, 0x3f4c422a, v20
	v_mul_f32_e32 v21, 0x3f4c422a, v21
	v_mul_f32_e32 v20, 0xc038aa3b, v20
	v_mul_f32_e32 v21, 0xc038aa3b, v21
	v_exp_f32_e32 v20, v20
	v_exp_f32_e32 v21, v21
	s_nop 0
	v_pk_add_f32 v[20:21], v[20:21], 1.0 op_sel_hi:[1,0]
	s_nop 0
	s_nop 0
	v_rcp_f32_e32 v23, v21
	s_nop 0
	v_mul_f32_e32 v21, v31, v23
	s_nop 0
	v_rcp_f32_e32 v23, v20
	s_nop 0
	v_mul_f32_e32 v20, v30, v23
	v_cvt_pk_bf16_f32 v20, v20, v21
	v_mul_f32_e32 v21, 0x3d372713, v32
	v_mul_f32_e32 v21, v32, v21
	v_fma_f32 v21, v32, v21, v32
	v_mul_f32_e32 v21, 0x3f4c422a, v21
	v_mul_f32_e32 v21, 0xc038aa3b, v21
	v_exp_f32_e32 v22, v21
	v_mul_f32_e32 v21, 0x3d372713, v33
	v_mul_f32_e32 v21, v33, v21
	v_fma_f32 v21, v33, v21, v33
	v_mul_f32_e32 v21, 0x3f4c422a, v21
	v_mul_f32_e32 v21, 0xc038aa3b, v21
	v_exp_f32_e32 v23, v21
	s_nop 0
	v_pk_add_f32 v[22:23], v[22:23], 1.0 op_sel_hi:[1,0]
	s_nop 0
; __device__ __forceinline__ unsigned pk2(float lo, float hi) { const f32x2pk v = {lo, hi}; return __builtin_bit_cast(unsigned, __builtin_convertvector(v, bf16x2pk)); }
; __device__ __forceinline__ float gelu_tanh(float x) {
;     const float z = 0.7978845608028654f * (x + 0.044715f * x * x * x);
;     return x / (1.f + __builtin_amdgcn_exp2f(-2.f * LOG2E * z));
; }
; __device__ __forceinline__ void ssm_prompt_item(const bf16* UG, const bf16* TQ, const bf16* PM, const float* SF, bf16* Gb, float* out, int b, int g, LAS unsigned char* lds, int tid) {
;     ...
;               for (int q = 0; q < 4; ++q) { const f32x16& A = nb ? acc1 : acc0; const int t = 2 * w + (q >> 1), c0 = 8 * (q & 1) + 4 * hi; const size_t tok = tok0 + (size_t)(32 * nb + r32) * 16 + t;
;                   u32x2 o; o.x = pk2(gelu_tanh(A[4 * q]), gelu_tanh(A[4 * q + 1])); o.y = pk2(gelu_tanh(A[4 * q + 2]), gelu_tanh(A[4 * q + 3]));
;                   *(u32x2*)(Gb + tok * 512 + 16 * g + c0) = o; }
	s_nop 0
	v_rcp_f32_e32 v24, v23
	s_nop 0
	v_mul_f32_e32 v21, v33, v24
	s_nop 0
	v_rcp_f32_e32 v24, v22
	s_nop 0
	v_mul_f32_e32 v22, v32, v24
	v_cvt_pk_bf16_f32 v21, v22, v21
	v_mul_f32_e32 v22, 0x3d372713, v2
	v_mul_f32_e32 v23, 0x3d372713, v3
	v_mul_f32_e32 v22, v2, v22
	v_mul_f32_e32 v23, v3, v23
	v_fma_f32 v22, v2, v22, v2
	v_fma_f32 v23, v3, v23, v3
	v_mul_f32_e32 v22, 0x3f4c422a, v22
	v_mul_f32_e32 v23, 0x3f4c422a, v23
	v_mul_f32_e32 v22, 0xc038aa3b, v22
	v_mul_f32_e32 v23, 0xc038aa3b, v23
	v_exp_f32_e32 v22, v22
	v_exp_f32_e32 v23, v23
	global_store_dwordx2 v[18:19], v[20:21], off offset:16
	v_lshl_add_u64 v[18:19], s[10:11], 0, v[214:215]
	v_lshl_add_u64 v[20:21], v[18:19], 0, s[2:3]
	v_pk_add_f32 v[22:23], v[22:23], 1.0 op_sel_hi:[1,0]
	s_nop 0
	s_nop 0
	v_rcp_f32_e32 v25, v23
	s_nop 0
	v_mul_f32_e32 v3, v3, v25
	s_nop 0
	v_rcp_f32_e32 v24, v22
	s_nop 0
	v_mul_f32_e32 v2, v2, v24
	v_cvt_pk_bf16_f32 v2, v2, v3
	v_mul_f32_e32 v3, 0x3d372713, v4
	v_mul_f32_e32 v3, v4, v3
	v_fma_f32 v3, v4, v3, v4
	v_mul_f32_e32 v3, 0x3f4c422a, v3
	v_mul_f32_e32 v3, 0xc038aa3b, v3
	v_exp_f32_e32 v22, v3
	v_mul_f32_e32 v3, 0x3d372713, v5
	v_mul_f32_e32 v3, v5, v3
	v_fma_f32 v3, v5, v3, v5
	v_mul_f32_e32 v3, 0x3f4c422a, v3
	v_mul_f32_e32 v3, 0xc038aa3b, v3
	v_exp_f32_e32 v23, v3
	s_nop 0
	v_pk_add_f32 v[22:23], v[22:23], 1.0 op_sel_hi:[1,0]
	s_nop 0
	s_nop 0
	v_rcp_f32_e32 v24, v23
	s_nop 0
	v_mul_f32_e32 v3, v5, v24
	s_nop 0
	v_rcp_f32_e32 v23, v22
	s_nop 0
	v_mul_f32_e32 v4, v4, v23
	v_cvt_pk_bf16_f32 v3, v4, v3
	v_lshlrev_b64 v[4:5], 10, v[20:21]
	v_lshl_add_u64 v[4:5], v[234:235], 0, v[4:5]
	global_store_dwordx2 v[4:5], v[2:3], off
	v_mul_f32_e32 v2, 0x3d372713, v6
	v_mul_f32_e32 v3, 0x3d372713, v7
	v_mul_f32_e32 v2, v6, v2
	v_mul_f32_e32 v3, v7, v3
	v_fma_f32 v2, v6, v2, v6
	v_fma_f32 v3, v7, v3, v7
	v_mul_f32_e32 v2, 0x3f4c422a, v2
	v_mul_f32_e32 v3, 0x3f4c422a, v3
	v_mul_f32_e32 v2, 0xc038aa3b, v2
	v_mul_f32_e32 v3, 0xc038aa3b, v3
	v_exp_f32_e32 v2, v2
	v_exp_f32_e32 v3, v3
	s_nop 0
	v_pk_add_f32 v[2:3], v[2:3], 1.0 op_sel_hi:[1,0]
	s_nop 0
	s_nop 0
	v_rcp_f32_e32 v21, v3
	s_nop 0
	v_mul_f32_e32 v3, v7, v21
	s_nop 0
	v_rcp_f32_e32 v20, v2
	s_nop 0
	v_mul_f32_e32 v2, v6, v20
	v_cvt_pk_bf16_f32 v2, v2, v3
	v_mul_f32_e32 v3, 0x3d372713, v8
	v_mul_f32_e32 v3, v8, v3
	v_fma_f32 v3, v8, v3, v8
	v_mul_f32_e32 v3, 0x3f4c422a, v3
	v_mul_f32_e32 v3, 0xc038aa3b, v3
	v_exp_f32_e32 v6, v3
	v_mul_f32_e32 v3, 0x3d372713, v9
	v_mul_f32_e32 v3, v9, v3
	v_fma_f32 v3, v9, v3, v9
	v_mul_f32_e32 v3, 0x3f4c422a, v3
	v_mul_f32_e32 v3, 0xc038aa3b, v3
	v_exp_f32_e32 v7, v3
	s_nop 0
	v_pk_add_f32 v[6:7], v[6:7], 1.0 op_sel_hi:[1,0]
	s_nop 0
	s_nop 0
	v_rcp_f32_e32 v20, v7
	s_nop 0
	v_mul_f32_e32 v3, v9, v20
	s_nop 0
	v_rcp_f32_e32 v9, v6
	s_nop 0
	v_mul_f32_e32 v6, v8, v9
	v_cvt_pk_bf16_f32 v3, v6, v3
	global_store_dwordx2 v[4:5], v[2:3], off offset:16
	v_mul_f32_e32 v4, 0x3d372713, v10
	v_mul_f32_e32 v5, 0x3d372713, v11
	v_mul_f32_e32 v4, v10, v4
	v_mul_f32_e32 v5, v11, v5
	v_fma_f32 v4, v10, v4, v10
	v_fma_f32 v5, v11, v5, v11
	v_mul_f32_e32 v4, 0x3f4c422a, v4
	v_mul_f32_e32 v5, 0x3f4c422a, v5
	v_mul_f32_e32 v4, 0xc038aa3b, v4
	v_mul_f32_e32 v5, 0xc038aa3b, v5
	v_exp_f32_e32 v4, v4
	v_exp_f32_e32 v5, v5
	v_lshl_add_u64 v[2:3], v[18:19], 0, s[20:21]
	v_lshlrev_b64 v[2:3], 10, v[2:3]
	v_lshl_add_u64 v[2:3], v[234:235], 0, v[2:3]
	v_pk_add_f32 v[4:5], v[4:5], 1.0 op_sel_hi:[1,0]
	s_nop 0
	s_nop 0
	v_rcp_f32_e32 v7, v5
	s_nop 0
	v_mul_f32_e32 v5, v11, v7
	s_nop 0
	v_rcp_f32_e32 v7, v4
	s_nop 0
	v_mul_f32_e32 v4, v10, v7
	v_cvt_pk_bf16_f32 v4, v4, v5
	v_mul_f32_e32 v5, 0x3d372713, v12
	v_mul_f32_e32 v5, v12, v5
	v_fma_f32 v5, v12, v5, v12
	v_mul_f32_e32 v5, 0x3f4c422a, v5
	v_mul_f32_e32 v5, 0xc038aa3b, v5
	v_exp_f32_e32 v6, v5
	v_mul_f32_e32 v5, 0x3d372713, v13
	v_mul_f32_e32 v5, v13, v5
	v_fma_f32 v5, v13, v5, v13
	v_mul_f32_e32 v5, 0x3f4c422a, v5
	v_mul_f32_e32 v5, 0xc038aa3b, v5
	v_exp_f32_e32 v7, v5
	s_nop 0
	v_pk_add_f32 v[6:7], v[6:7], 1.0 op_sel_hi:[1,0]
	s_nop 0
	s_nop 0
	v_rcp_f32_e32 v8, v7
	s_nop 0
	v_mul_f32_e32 v5, v13, v8
	s_nop 0
	v_rcp_f32_e32 v8, v6
	s_nop 0
	v_mul_f32_e32 v6, v12, v8
	v_cvt_pk_bf16_f32 v5, v6, v5
	global_store_dwordx2 v[2:3], v[4:5], off
	v_mul_f32_e32 v4, 0x3d372713, v14
	v_mul_f32_e32 v5, 0x3d372713, v15
	v_mul_f32_e32 v4, v14, v4
	v_mul_f32_e32 v5, v15, v5
	v_fma_f32 v4, v14, v4, v14
	v_fma_f32 v5, v15, v5, v15
	v_mul_f32_e32 v4, 0x3f4c422a, v4
	v_mul_f32_e32 v5, 0x3f4c422a, v5
	v_mul_f32_e32 v4, 0xc038aa3b, v4
	v_mul_f32_e32 v5, 0xc038aa3b, v5
	v_exp_f32_e32 v4, v4
	v_exp_f32_e32 v5, v5
	s_nop 0
	v_pk_add_f32 v[4:5], v[4:5], 1.0 op_sel_hi:[1,0]
	s_nop 0
	s_nop 0
	v_rcp_f32_e32 v7, v5
	s_nop 0
	v_mul_f32_e32 v5, v15, v7
	s_nop 0
	v_rcp_f32_e32 v7, v4
	s_nop 0
	v_mul_f32_e32 v4, v14, v7
	v_cvt_pk_bf16_f32 v4, v4, v5
	v_mul_f32_e32 v5, 0x3d372713, v16
	v_mul_f32_e32 v5, v16, v5
	v_fma_f32 v5, v16, v5, v16
	v_mul_f32_e32 v5, 0x3f4c422a, v5
	v_mul_f32_e32 v5, 0xc038aa3b, v5
	v_exp_f32_e32 v6, v5
	v_mul_f32_e32 v5, 0x3d372713, v17
	v_mul_f32_e32 v5, v17, v5
	v_fma_f32 v5, v17, v5, v17
	v_mul_f32_e32 v5, 0x3f4c422a, v5
	v_mul_f32_e32 v5, 0xc038aa3b, v5
	v_exp_f32_e32 v7, v5
	s_nop 0
	v_pk_add_f32 v[6:7], v[6:7], 1.0 op_sel_hi:[1,0]
	s_nop 0
	s_nop 0
	v_rcp_f32_e32 v8, v7
	s_nop 0
	v_mul_f32_e32 v5, v17, v8
	s_nop 0
	v_rcp_f32_e32 v8, v6
	s_nop 0
	v_mul_f32_e32 v6, v16, v8
	v_cvt_pk_bf16_f32 v5, v6, v5
	global_store_dwordx2 v[2:3], v[4:5], off offset:16
	s_cbranch_scc1 .LBB0_411

; #define LAS __attribute__((address_space(3)))
; __device__ __forceinline__ void ssm_sample_item(const bf16* UG, const float* SF, const float* cre, const float* cim, const float* dd, const float* sre, const float* sim,
;                                                 bf16* Gb, float* out, int s, int g, LAS float* hs, const LAS float* Cl, int lane) {
;     float Sre = sre[(s * NG + g) * 64 + lane], Sim = sim[(s * NG + g) * 64 + lane];
;     const float lr = SF[SF_LB1 + g * 128 + lane], li = SF[SF_LB1 + g * 128 + 64 + lane];
;     f32x4 bb[8];
; #pragma unroll
;     for (int i = 0; i < 8; ++i) bb[i] = *(const f32x4*)(SF + SF_BB + g * 2048 + lane * 32 + 4 * i);
;     const bf16* up = UG + ((size_t)g * MTOT + MP + 4 * s) * 16;
;     u32x4 uw[8];
; #pragma unroll
;     for (int i = 0; i < 8; ++i) uw[i] = *(const u32x4*)(up + 8 * i);
;     const float uval = bf2f(up[lane]), dval = dd[g * 16 + (lane & 15)];
; #pragma unroll
;     for (int t = 0; t < 4; ++t) { float br = 0.f, bi = 0.f;
; #pragma unroll
;         for (int c = 0; c < 16; ++c) { const unsigned wd = uw[2 * t + (c >> 3)][(c & 7) >> 1]; const float u = (c & 1) ? bfhi(wd) : bflo(wd);
;             br += bb[c >> 1][2 * (c & 1)] * u; bi += bb[c >> 1][2 * (c & 1) + 1] * u; }
;         const float nr = lr * Sre - li * Sim + br, ni = lr * Sim + li * Sre + bi; Sre = nr; Sim = ni;
;         hs[t * 128 + lane] = Sre; hs[t * 128 + 64 + lane] = Sim; }
.LBB0_417:
	v_ashrrev_i32_e32 v71, 31, v70
	v_readlane_b32 s44, v254, 10
	v_lshlrev_b64 v[2:3], 2, v[70:71]
	v_readlane_b32 s56, v254, 22
	v_readlane_b32 s57, v254, 23
	v_readlane_b32 s58, v254, 24
	v_readlane_b32 s59, v254, 25
	v_lshl_add_u64 v[4:5], s[56:57], 0, v[2:3]
	s_lshl_b32 s6, s7, 12
	v_lshl_add_u64 v[2:3], s[58:59], 0, v[2:3]
	global_load_dword v94, v[2:3], off
	v_subrev_u32_e32 v2, s6, v82
	s_lshl_b32 s6, s7, 16
	s_sub_i32 s34, s20, s6
	s_mul_i32 s6, s7, 0xfff7c004
	s_add_i32 s8, s28, s6
	s_ashr_i32 s9, s8, 31
	v_subrev_u32_e32 v66, 64, v2
	v_mov_b32_e32 v3, v67
	s_ashr_i32 s35, s34, 31
	s_lshl_b64 s[8:9], s[8:9], 5
	global_load_dword v91, v[4:5], off
	v_lshl_add_u64 v[4:5], v[66:67], 2, s[0:1]
	v_lshl_add_u64 v[2:3], v[2:3], 2, s[0:1]
	s_add_u32 s8, s10, s8
	global_load_dword v89, v[4:5], off
	global_load_dword v90, v[2:3], off
	s_addc_u32 s9, s11, s9
	v_lshl_add_u64 v[2:3], s[34:35], 2, v[68:69]
	global_load_dwordx4 v[62:65], v67, s[8:9]
	global_load_dwordx4 v[58:61], v67, s[8:9] offset:16
	global_load_dwordx4 v[54:57], v67, s[8:9] offset:32
	global_load_dwordx4 v[34:37], v[2:3], off
	global_load_dwordx4 v[30:33], v[2:3], off offset:16
	global_load_dwordx4 v[26:29], v[2:3], off offset:32
	global_load_dwordx4 v[22:25], v[2:3], off offset:48
	global_load_dwordx4 v[18:21], v[2:3], off offset:64
	global_load_dwordx4 v[10:13], v[2:3], off offset:80
	global_load_dwordx4 v[6:9], v[2:3], off offset:96
	s_nop 0
	global_load_dwordx4 v[2:5], v[2:3], off offset:112
	s_nop 0
	global_load_dwordx4 v[50:53], v67, s[8:9] offset:48
	global_load_dwordx4 v[14:17], v67, s[8:9] offset:112
	global_load_dwordx4 v[38:41], v67, s[8:9] offset:96
	global_load_dwordx4 v[42:45], v67, s[8:9] offset:80
	global_load_dwordx4 v[46:49], v67, s[8:9] offset:64
	s_lshl_b32 s6, s7, 9
	s_sub_i32 s6, s22, s6
	v_add_u32_e32 v92, s6, v104
	v_ashrrev_i32_e32 v93, 31, v92
	v_lshl_add_u64 v[92:93], v[92:93], 2, s[18:19]
	global_load_dword v71, v[92:93], off
	global_load_ushort v66, v87, s[8:9]
	s_lshl_b64 s[8:9], s[4:5], 8
	s_add_u32 s8, s92, s8
	s_addc_u32 s9, s93, s9
	s_mov_b32 s5, 0x8410000
	s_add_i32 s20, s20, s21
	s_add_i32 s22, s22, s23
	s_add_i32 s29, s29, s30
	v_add_u32_e32 v70, s12, v70
	v_add_u32_e32 v82, s13, v82
	v_readlane_b32 s45, v254, 11
	v_readlane_b32 s46, v254, 12
	v_readlane_b32 s47, v254, 13
	v_readlane_b32 s48, v254, 14
	v_readlane_b32 s49, v254, 15
	v_readlane_b32 s50, v254, 16
	v_readlane_b32 s51, v254, 17
	v_readlane_b32 s52, v254, 18
	v_readlane_b32 s53, v254, 19
	v_readlane_b32 s54, v254, 20
	v_readlane_b32 s55, v254, 21
	s_waitcnt vmcnt(15)
	v_lshlrev_b32_e32 v101, 16, v54
	s_waitcnt vmcnt(14)
	v_fma_f32 v103, v34, v101, 0
	v_fma_f32 v101, v35, v101, 0
	v_and_b32_e32 v54, 0xffff0000, v54
	v_fmac_f32_e32 v103, v36, v54
	v_fmac_f32_e32 v101, v37, v54
	v_lshlrev_b32_e32 v54, 16, v55
	s_waitcnt vmcnt(13)
	v_fmac_f32_e32 v103, v30, v54
	v_fmac_f32_e32 v101, v31, v54
	v_and_b32_e32 v54, 0xffff0000, v55
	v_fmac_f32_e32 v103, v32, v54
	v_fmac_f32_e32 v101, v33, v54
	v_lshlrev_b32_e32 v54, 16, v56
	s_waitcnt vmcnt(12)
	v_fmac_f32_e32 v103, v26, v54
	v_fmac_f32_e32 v101, v27, v54
	v_and_b32_e32 v54, 0xffff0000, v56
	v_fmac_f32_e32 v103, v28, v54
	v_fmac_f32_e32 v101, v29, v54
	v_lshlrev_b32_e32 v54, 16, v57
	s_waitcnt vmcnt(11)
	v_fmac_f32_e32 v103, v22, v54
	v_fmac_f32_e32 v101, v23, v54
	v_and_b32_e32 v54, 0xffff0000, v57
	v_fmac_f32_e32 v103, v24, v54
	v_fmac_f32_e32 v101, v25, v54
	s_waitcnt vmcnt(6)
	v_lshlrev_b32_e32 v54, 16, v50
	v_fmac_f32_e32 v103, v18, v54
	v_fmac_f32_e32 v101, v19, v54
	v_and_b32_e32 v50, 0xffff0000, v50
	v_fmac_f32_e32 v103, v20, v50
	v_fmac_f32_e32 v101, v21, v50
	v_lshlrev_b32_e32 v50, 16, v51
	v_fmac_f32_e32 v103, v10, v50
	v_fmac_f32_e32 v101, v11, v50
	v_and_b32_e32 v50, 0xffff0000, v51
	v_fmac_f32_e32 v103, v12, v50
	v_fmac_f32_e32 v101, v13, v50
	v_lshlrev_b32_e32 v50, 16, v52
	v_fmac_f32_e32 v103, v6, v50
	v_fmac_f32_e32 v101, v7, v50
	v_and_b32_e32 v50, 0xffff0000, v52
	v_fmac_f32_e32 v103, v8, v50
	v_fmac_f32_e32 v101, v9, v50
	v_lshlrev_b32_e32 v50, 16, v53
	s_waitcnt vmcnt(2)
	v_lshlrev_b32_e32 v52, 16, v46
	v_fmac_f32_e32 v103, v2, v50
	v_fmac_f32_e32 v101, v3, v50
	v_and_b32_e32 v50, 0xffff0000, v53
	v_fma_f32 v53, v34, v52, 0
	v_fma_f32 v52, v35, v52, 0
	v_and_b32_e32 v46, 0xffff0000, v46
	v_fmac_f32_e32 v53, v36, v46
	v_fmac_f32_e32 v52, v37, v46
	v_lshlrev_b32_e32 v46, 16, v47
	v_fmac_f32_e32 v53, v30, v46
	v_fmac_f32_e32 v52, v31, v46
	v_and_b32_e32 v46, 0xffff0000, v47
	v_mul_f32_e32 v92, v94, v90
	v_fmac_f32_e32 v53, v32, v46
	v_fmac_f32_e32 v52, v33, v46
	v_lshlrev_b32_e32 v46, 16, v48
	v_mul_f32_e32 v93, v91, v90
	v_fma_f32 v91, v91, v89, -v92
	v_lshlrev_b32_e32 v92, 16, v62
	v_fmac_f32_e32 v53, v26, v46
	v_fmac_f32_e32 v52, v27, v46
	v_and_b32_e32 v46, 0xffff0000, v48
	v_and_b32_e32 v62, 0xffff0000, v62
	v_fma_f32 v102, v34, v92, 0
	v_fma_f32 v92, v35, v92, 0
	v_fmac_f32_e32 v53, v28, v46
	v_fmac_f32_e32 v52, v29, v46
	v_lshlrev_b32_e32 v46, 16, v49
	v_fmac_f32_e32 v93, v94, v89
	v_lshlrev_b32_e32 v94, 16, v63
	v_fmac_f32_e32 v92, v37, v62
	v_fmac_f32_e32 v53, v22, v46
	v_fmac_f32_e32 v52, v23, v46
	v_and_b32_e32 v46, 0xffff0000, v49
	v_and_b32_e32 v63, 0xffff0000, v63
	v_fmac_f32_e32 v102, v36, v62
	v_fmac_f32_e32 v92, v31, v94
	v_fmac_f32_e32 v53, v24, v46
	v_fmac_f32_e32 v52, v25, v46
	v_lshlrev_b32_e32 v46, 16, v42
	v_lshlrev_b32_e32 v95, 16, v64
	v_fmac_f32_e32 v102, v30, v94
	v_fmac_f32_e32 v92, v33, v63
	v_fmac_f32_e32 v53, v18, v46
	v_fmac_f32_e32 v52, v19, v46
	v_and_b32_e32 v42, 0xffff0000, v42
	v_and_b32_e32 v64, 0xffff0000, v64
	v_fmac_f32_e32 v102, v32, v63
	v_fmac_f32_e32 v92, v27, v95
; #define LAS __attribute__((address_space(3)))
; #define LDS_WAIT() asm volatile("s_waitcnt lgkmcnt(0)" ::: "memory")
; __device__ __forceinline__ void ssm_sample_item(const bf16* UG, const float* SF, const float* cre, const float* cim, const float* dd, const float* sre, const float* sim,
;                                                 bf16* Gb, float* out, int s, int g, LAS float* hs, const LAS float* Cl, int lane) {
;     ...
;     for (int t = 0; t < 4; ++t) { float br = 0.f, bi = 0.f;
; #pragma unroll
;         for (int c = 0; c < 16; ++c) { const unsigned wd = uw[2 * t + (c >> 3)][(c & 7) >> 1]; const float u = (c & 1) ? bfhi(wd) : bflo(wd);
;             br += bb[c >> 1][2 * (c & 1)] * u; bi += bb[c >> 1][2 * (c & 1) + 1] * u; }
;         const float nr = lr * Sre - li * Sim + br, ni = lr * Sim + li * Sre + bi; Sre = nr; Sim = ni;
;         hs[t * 128 + lane] = Sre; hs[t * 128 + 64 + lane] = Sim; }
;     out[O_HRS + (size_t)(s * NG + g) * 64 + lane] = Sre * DBG_SSM; out[O_HIS + (size_t)(s * NG + g) * 64 + lane] = Sim * DBG_SSM;
;     LDS_WAIT(); asm volatile("" ::: "memory");
;     const int t = lane >> 4, c = lane & 15; float y = 0.f;
; #pragma unroll
;     for (int p4 = 0; p4 < 16; ++p4) { const f32x4 a = *(const LAS f32x4*)(Cl + c * 68 + 4 * p4), bq = *(const LAS f32x4*)(Cl + 16 * 68 + c * 68 + 4 * p4);
;         const f32x4 hr = *(const LAS f32x4*)(hs + t * 128 + 4 * p4), hq = *(const LAS f32x4*)(hs + t * 128 + 64 + 4 * p4);
;         y += (a[0] * hr[0] - bq[0] * hq[0]) + (a[1] * hr[1] - bq[1] * hq[1]) + (a[2] * hr[2] - bq[2] * hq[2]) + (a[3] * hr[3] - bq[3] * hq[3]); }
	v_fmac_f32_e32 v53, v20, v42
	v_fmac_f32_e32 v52, v21, v42
	v_lshlrev_b32_e32 v42, 16, v43
	v_lshlrev_b32_e32 v96, 16, v65
	v_fmac_f32_e32 v102, v26, v95
	v_fmac_f32_e32 v92, v29, v64
	v_fmac_f32_e32 v53, v10, v42
	v_fmac_f32_e32 v52, v11, v42
	v_and_b32_e32 v42, 0xffff0000, v43
	v_and_b32_e32 v65, 0xffff0000, v65
	v_fmac_f32_e32 v102, v28, v64
	v_fmac_f32_e32 v92, v23, v96
	v_fmac_f32_e32 v53, v12, v42
	v_fmac_f32_e32 v52, v13, v42
	v_lshlrev_b32_e32 v42, 16, v44
	v_lshlrev_b32_e32 v97, 16, v58
	v_fmac_f32_e32 v102, v22, v96
	v_fmac_f32_e32 v92, v25, v65
	v_fmac_f32_e32 v53, v6, v42
	v_fmac_f32_e32 v52, v7, v42
	v_and_b32_e32 v42, 0xffff0000, v44
	v_lshlrev_b32_e32 v44, 16, v38
	v_and_b32_e32 v58, 0xffff0000, v58
	v_fmac_f32_e32 v102, v24, v65
	v_fmac_f32_e32 v92, v19, v97
	v_fma_f32 v34, v34, v44, 0
	v_fma_f32 v35, v35, v44, 0
	v_and_b32_e32 v38, 0xffff0000, v38
	v_lshlrev_b32_e32 v98, 16, v59
	v_fmac_f32_e32 v102, v18, v97
	v_fmac_f32_e32 v92, v21, v58
	v_fmac_f32_e32 v34, v36, v38
	v_fmac_f32_e32 v35, v37, v38
	v_lshlrev_b32_e32 v36, 16, v39
	v_and_b32_e32 v59, 0xffff0000, v59
	v_fmac_f32_e32 v102, v20, v58
	v_fmac_f32_e32 v92, v11, v98
	v_fmac_f32_e32 v34, v30, v36
	v_fmac_f32_e32 v35, v31, v36
	v_and_b32_e32 v30, 0xffff0000, v39
	v_lshlrev_b32_e32 v99, 16, v60
	v_fmac_f32_e32 v102, v10, v98
	v_fmac_f32_e32 v92, v13, v59
	v_fmac_f32_e32 v34, v32, v30
	v_fmac_f32_e32 v35, v33, v30
	v_lshlrev_b32_e32 v30, 16, v40
	v_and_b32_e32 v60, 0xffff0000, v60
	v_fmac_f32_e32 v102, v12, v59
	v_fmac_f32_e32 v92, v7, v99
	v_fmac_f32_e32 v34, v26, v30
	v_fmac_f32_e32 v35, v27, v30
	v_and_b32_e32 v26, 0xffff0000, v40
	v_lshlrev_b32_e32 v100, 16, v61
	v_fmac_f32_e32 v102, v6, v99
	v_fmac_f32_e32 v92, v9, v60
	v_fmac_f32_e32 v34, v28, v26
	v_fmac_f32_e32 v35, v29, v26
	v_lshlrev_b32_e32 v26, 16, v41
	v_and_b32_e32 v61, 0xffff0000, v61
	v_fmac_f32_e32 v102, v8, v60
	v_fmac_f32_e32 v92, v3, v100
	v_fmac_f32_e32 v34, v22, v26
	v_fmac_f32_e32 v35, v23, v26
	v_and_b32_e32 v22, 0xffff0000, v41
	v_fmac_f32_e32 v102, v2, v100
	v_fmac_f32_e32 v92, v5, v61
	v_fmac_f32_e32 v34, v24, v22
	v_fmac_f32_e32 v35, v25, v22
	v_lshlrev_b32_e32 v22, 16, v14
	v_fmac_f32_e32 v102, v4, v61
	v_add_f32_e32 v59, v93, v92
	v_fmac_f32_e32 v34, v18, v22
	v_fmac_f32_e32 v35, v19, v22
	v_and_b32_e32 v14, 0xffff0000, v14
	v_add_f32_e32 v58, v91, v102
	v_fmac_f32_e32 v103, v4, v50
	v_fmac_f32_e32 v101, v5, v50
	v_mul_f32_e32 v50, v90, v59
	v_fmac_f32_e32 v34, v20, v14
	v_fmac_f32_e32 v35, v21, v14
	v_lshlrev_b32_e32 v14, 16, v15
	v_fma_f32 v50, v89, v58, -v50
	v_mul_f32_e32 v51, v90, v58
	v_fmac_f32_e32 v34, v10, v14
	v_fmac_f32_e32 v35, v11, v14
	v_and_b32_e32 v10, 0xffff0000, v15
	v_add_f32_e32 v50, v103, v50
	v_fmac_f32_e32 v51, v89, v59
	v_fmac_f32_e32 v53, v8, v42
	v_fmac_f32_e32 v52, v9, v42
	v_lshlrev_b32_e32 v42, 16, v45
	v_fmac_f32_e32 v34, v12, v10
	v_fmac_f32_e32 v35, v13, v10
	v_lshlrev_b32_e32 v10, 16, v16
	v_add_f32_e32 v51, v101, v51
	v_fmac_f32_e32 v53, v2, v42
	v_fmac_f32_e32 v52, v3, v42
	v_and_b32_e32 v42, 0xffff0000, v45
	v_mul_f32_e32 v43, v90, v50
	v_fmac_f32_e32 v34, v6, v10
	v_fmac_f32_e32 v35, v7, v10
	v_and_b32_e32 v6, 0xffff0000, v16
	v_fmac_f32_e32 v53, v4, v42
	v_fmac_f32_e32 v52, v5, v42
	v_mul_f32_e32 v42, v90, v51
	v_fmac_f32_e32 v43, v89, v51
	v_fmac_f32_e32 v34, v8, v6
	v_fmac_f32_e32 v35, v9, v6
	v_lshlrev_b32_e32 v6, 16, v17
	v_fma_f32 v42, v89, v50, -v42
	v_add_f32_e32 v43, v52, v43
	v_fmac_f32_e32 v34, v2, v6
	v_fmac_f32_e32 v35, v3, v6
	v_and_b32_e32 v2, 0xffff0000, v17
	v_add_f32_e32 v42, v53, v42
	v_fmac_f32_e32 v34, v4, v2
	v_fmac_f32_e32 v35, v5, v2
	v_mul_f32_e32 v2, v90, v43
	v_fma_f32 v2, v89, v42, -v2
	v_add_f32_e32 v6, v34, v2
	v_mul_f32_e32 v2, v90, v42
	v_fmac_f32_e32 v2, v89, v43
	v_add_f32_e32 v7, v35, v2
	v_lshl_add_u64 v[2:3], s[8:9], 0, v[72:73]
	v_add_co_u32_e32 v4, vcc, s5, v2
	s_mov_b32 s5, 0x8510000
	s_nop 0
	v_addc_co_u32_e32 v5, vcc, 0, v3, vcc
	v_add_co_u32_e32 v2, vcc, s5, v2
	ds_write2st64_b32 v1, v58, v59 offset1:1
	s_nop 0
	v_addc_co_u32_e32 v3, vcc, 0, v3, vcc
	ds_write2st64_b32 v1, v50, v51 offset0:2 offset1:3
	ds_write2st64_b32 v1, v42, v43 offset0:4 offset1:5
	ds_write2st64_b32 v1, v6, v7 offset0:6 offset1:7
	global_store_dword v[4:5], v6, off
	global_store_dword v[2:3], v7, off
	s_waitcnt lgkmcnt(0)
	ds_read_b128 v[2:5], v76 offset:6400
	ds_read_b128 v[6:9], v88 offset:256
	ds_read_b128 v[10:13], v76 offset:2048
	ds_read_b128 v[14:17], v76 offset:2064
	ds_read_b128 v[18:21], v76 offset:2080
	ds_read_b128 v[22:25], v76 offset:2096
	ds_read_b128 v[26:29], v88
	ds_read_b128 v[30:33], v88 offset:16
	ds_read_b128 v[34:37], v88 offset:32
	ds_read_b128 v[38:41], v88 offset:48
	ds_read_b128 v[42:45], v76 offset:6416
	ds_read_b128 v[46:49], v88 offset:272
	s_waitcnt lgkmcnt(10)
	v_mul_f32_e32 v2, v2, v6
	v_mul_f32_e32 v3, v3, v7
	s_waitcnt lgkmcnt(5)
	v_fma_f32 v2, v10, v26, -v2
	v_fma_f32 v3, v11, v27, -v3
	v_add_f32_e32 v2, v2, v3
	v_mul_f32_e32 v3, v4, v8
	v_fma_f32 v3, v12, v28, -v3
	v_add_f32_e32 v2, v3, v2
	v_mul_f32_e32 v3, v5, v9
	v_fma_f32 v3, v13, v29, -v3
	v_add_f32_e32 v2, v3, v2
	v_add_f32_e32 v10, 0, v2
	s_waitcnt lgkmcnt(0)
	v_mul_f32_e32 v2, v42, v46
	v_mul_f32_e32 v3, v43, v47
	v_fma_f32 v2, v14, v30, -v2
	v_fma_f32 v3, v15, v31, -v3
	v_add_f32_e32 v2, v2, v3
	v_mul_f32_e32 v3, v44, v48
	v_fma_f32 v3, v16, v32, -v3
	v_add_f32_e32 v11, v3, v2
	v_mul_f32_e32 v2, v45, v49
	v_fma_f32 v12, v17, v33, -v2
	ds_read_b128 v[2:5], v76 offset:6432
	ds_read_b128 v[6:9], v88 offset:288
	v_add_f32_e32 v11, v12, v11
	v_add_f32_e32 v26, v10, v11
	ds_read_b128 v[10:13], v76 offset:6448
	ds_read_b128 v[14:17], v88 offset:304
	s_waitcnt lgkmcnt(2)
; #define LAS __attribute__((address_space(3)))
; __device__ __forceinline__ void ssm_sample_item(const bf16* UG, const float* SF, const float* cre, const float* cim, const float* dd, const float* sre, const float* sim,
;                                                 bf16* Gb, float* out, int s, int g, LAS float* hs, const LAS float* Cl, int lane) {
;     ...
;     const int t = lane >> 4, c = lane & 15; float y = 0.f;
; #pragma unroll
;     for (int p4 = 0; p4 < 16; ++p4) { const f32x4 a = *(const LAS f32x4*)(Cl + c * 68 + 4 * p4), bq = *(const LAS f32x4*)(Cl + 16 * 68 + c * 68 + 4 * p4);
;         const f32x4 hr = *(const LAS f32x4*)(hs + t * 128 + 4 * p4), hq = *(const LAS f32x4*)(hs + t * 128 + 64 + 4 * p4);
;         y += (a[0] * hr[0] - bq[0] * hq[0]) + (a[1] * hr[1] - bq[1] * hq[1]) + (a[2] * hr[2] - bq[2] * hq[2]) + (a[3] * hr[3] - bq[3] * hq[3]); }
	v_mul_f32_e32 v2, v2, v6
	v_mul_f32_e32 v3, v3, v7
	v_fma_f32 v2, v18, v34, -v2
	v_fma_f32 v3, v19, v35, -v3
	v_add_f32_e32 v2, v2, v3
	v_mul_f32_e32 v3, v4, v8
	v_fma_f32 v3, v20, v36, -v3
	v_add_f32_e32 v2, v3, v2
	v_mul_f32_e32 v3, v5, v9
	v_fma_f32 v3, v21, v37, -v3
	v_add_f32_e32 v2, v3, v2
	s_waitcnt lgkmcnt(0)
	v_mul_f32_e32 v3, v10, v14
	v_mul_f32_e32 v4, v11, v15
	v_fma_f32 v3, v22, v38, -v3
	v_fma_f32 v4, v23, v39, -v4
	v_add_f32_e32 v3, v3, v4
	v_mul_f32_e32 v4, v12, v16
	v_fma_f32 v4, v24, v40, -v4
	v_add_f32_e32 v3, v4, v3
	v_mul_f32_e32 v4, v13, v17
	v_fma_f32 v4, v25, v41, -v4
	v_add_f32_e32 v2, v26, v2
	v_add_f32_e32 v3, v4, v3
	v_add_f32_e32 v34, v2, v3
	ds_read_b128 v[2:5], v76 offset:6464
	ds_read_b128 v[6:9], v88 offset:320
	ds_read_b128 v[10:13], v76 offset:2112
	ds_read_b128 v[14:17], v88 offset:64
	ds_read_b128 v[18:21], v76 offset:6480
	ds_read_b128 v[22:25], v88 offset:336
	s_waitcnt lgkmcnt(4)
	v_mul_f32_e32 v2, v2, v6
	v_mul_f32_e32 v3, v3, v7
	s_waitcnt lgkmcnt(2)
	v_fma_f32 v2, v10, v14, -v2
	v_fma_f32 v3, v11, v15, -v3
	ds_read_b128 v[26:29], v76 offset:2128
	ds_read_b128 v[30:33], v88 offset:80
	v_add_f32_e32 v2, v2, v3
	v_mul_f32_e32 v3, v4, v8
	v_fma_f32 v3, v12, v16, -v3
	v_add_f32_e32 v2, v3, v2
	v_mul_f32_e32 v3, v5, v9
	v_fma_f32 v3, v13, v17, -v3
	v_add_f32_e32 v2, v3, v2
	s_waitcnt lgkmcnt(2)
	v_mul_f32_e32 v3, v18, v22
	v_mul_f32_e32 v4, v19, v23
	s_waitcnt lgkmcnt(0)
	v_fma_f32 v3, v26, v30, -v3
	v_fma_f32 v4, v27, v31, -v4
	v_add_f32_e32 v3, v3, v4
	v_mul_f32_e32 v4, v20, v24
	v_fma_f32 v4, v28, v32, -v4
	v_add_f32_e32 v3, v4, v3
	v_mul_f32_e32 v4, v21, v25
	v_fma_f32 v4, v29, v33, -v4
	v_add_f32_e32 v2, v34, v2
	v_add_f32_e32 v3, v4, v3
	v_add_f32_e32 v42, v2, v3
	ds_read_b128 v[2:5], v76 offset:2144
	ds_read_b128 v[6:9], v76 offset:2160
	ds_read_b128 v[10:13], v76 offset:6496
	ds_read_b128 v[14:17], v76 offset:6512
	ds_read_b128 v[18:21], v88 offset:96
	ds_read_b128 v[22:25], v88 offset:112
	ds_read_b128 v[26:29], v88 offset:352
	ds_read_b128 v[30:33], v88 offset:368
	s_waitcnt lgkmcnt(5)
	v_mov_b32_e32 v38, v10
	s_waitcnt lgkmcnt(4)
	v_mov_b32_e32 v39, v14
	v_mov_b32_e32 v14, v11
	s_waitcnt lgkmcnt(1)
	v_mov_b32_e32 v40, v26
	s_waitcnt lgkmcnt(0)
	v_mov_b32_e32 v41, v30
	v_mov_b32_e32 v30, v27
	v_mov_b32_e32 v34, v2
	v_mov_b32_e32 v35, v6
	v_mov_b32_e32 v36, v18
	v_mov_b32_e32 v37, v22
	v_pk_mul_f32 v[38:39], v[38:39], v[40:41]
	v_mov_b32_e32 v6, v3
	v_mov_b32_e32 v22, v19
	v_pk_mul_f32 v[2:3], v[14:15], v[30:31]
	v_mov_b32_e32 v14, v12
	v_mov_b32_e32 v15, v16
	v_mov_b32_e32 v18, v28
	v_mov_b32_e32 v19, v32
	v_pk_fma_f32 v[34:35], v[34:35], v[36:37], v[38:39] neg_lo:[0,0,1] neg_hi:[0,0,1]
	v_pk_fma_f32 v[2:3], v[6:7], v[22:23], v[2:3] neg_lo:[0,0,1] neg_hi:[0,0,1]
	v_mov_b32_e32 v6, v4
	v_mov_b32_e32 v7, v8
	v_mov_b32_e32 v10, v20
	v_mov_b32_e32 v11, v24
	v_pk_mul_f32 v[14:15], v[14:15], v[18:19]
	v_mov_b32_e32 v16, v13
	v_mov_b32_e32 v32, v29
	v_pk_add_f32 v[2:3], v[34:35], v[2:3]
	v_pk_fma_f32 v[6:7], v[6:7], v[10:11], v[14:15] neg_lo:[0,0,1] neg_hi:[0,0,1]
	v_mov_b32_e32 v8, v5
	v_mov_b32_e32 v24, v21
	v_pk_mul_f32 v[4:5], v[16:17], v[32:33]
	v_pk_add_f32 v[2:3], v[6:7], v[2:3]
	v_pk_fma_f32 v[4:5], v[8:9], v[24:25], v[4:5] neg_lo:[0,0,1] neg_hi:[0,0,1]
	s_nop 0
	v_pk_add_f32 v[2:3], v[4:5], v[2:3]
	s_nop 0
	v_add_f32_e32 v2, v42, v2
	v_add_f32_e32 v42, v2, v3
	ds_read_b128 v[2:5], v76 offset:2176
	ds_read_b128 v[6:9], v76 offset:2192
	ds_read_b128 v[10:13], v76 offset:6528
	ds_read_b128 v[14:17], v76 offset:6544
	ds_read_b128 v[18:21], v88 offset:128
	ds_read_b128 v[22:25], v88 offset:144
	ds_read_b128 v[26:29], v88 offset:384
	ds_read_b128 v[30:33], v88 offset:400
	s_waitcnt lgkmcnt(5)
	v_mov_b32_e32 v38, v10
	s_waitcnt lgkmcnt(4)
	v_mov_b32_e32 v39, v14
	v_mov_b32_e32 v14, v11
	s_waitcnt lgkmcnt(1)
	v_mov_b32_e32 v40, v26
	s_waitcnt lgkmcnt(0)
	v_mov_b32_e32 v41, v30
	v_mov_b32_e32 v30, v27
	v_mov_b32_e32 v34, v2
	v_mov_b32_e32 v35, v6
	v_mov_b32_e32 v36, v18
	v_mov_b32_e32 v37, v22
	v_pk_mul_f32 v[38:39], v[38:39], v[40:41]
	v_mov_b32_e32 v6, v3
	v_mov_b32_e32 v22, v19
	v_pk_mul_f32 v[2:3], v[14:15], v[30:31]
	v_mov_b32_e32 v14, v12
	v_mov_b32_e32 v15, v16
	v_mov_b32_e32 v18, v28
	v_mov_b32_e32 v19, v32
	v_pk_fma_f32 v[34:35], v[34:35], v[36:37], v[38:39] neg_lo:[0,0,1] neg_hi:[0,0,1]
	v_pk_fma_f32 v[2:3], v[6:7], v[22:23], v[2:3] neg_lo:[0,0,1] neg_hi:[0,0,1]
	v_mov_b32_e32 v6, v4
	v_mov_b32_e32 v7, v8
	v_mov_b32_e32 v10, v20
	v_mov_b32_e32 v11, v24
	v_pk_mul_f32 v[14:15], v[14:15], v[18:19]
	v_mov_b32_e32 v16, v13
	v_mov_b32_e32 v32, v29
	v_pk_add_f32 v[2:3], v[34:35], v[2:3]
	v_pk_fma_f32 v[6:7], v[6:7], v[10:11], v[14:15] neg_lo:[0,0,1] neg_hi:[0,0,1]
	v_mov_b32_e32 v8, v5
	v_mov_b32_e32 v24, v21
	v_pk_mul_f32 v[4:5], v[16:17], v[32:33]
	v_pk_add_f32 v[2:3], v[6:7], v[2:3]
	v_pk_fma_f32 v[4:5], v[8:9], v[24:25], v[4:5] neg_lo:[0,0,1] neg_hi:[0,0,1]
	s_nop 0
	v_pk_add_f32 v[2:3], v[4:5], v[2:3]
	s_nop 0
	v_add_f32_e32 v2, v42, v2
	v_add_f32_e32 v42, v2, v3
	ds_read_b128 v[2:5], v76 offset:2208
	ds_read_b128 v[6:9], v76 offset:2224
	ds_read_b128 v[10:13], v76 offset:6560
	ds_read_b128 v[14:17], v76 offset:6576
	ds_read_b128 v[18:21], v88 offset:160
	ds_read_b128 v[22:25], v88 offset:176
	ds_read_b128 v[26:29], v88 offset:416
	ds_read_b128 v[30:33], v88 offset:432
	s_waitcnt lgkmcnt(5)
	v_mov_b32_e32 v38, v10
	s_waitcnt lgkmcnt(4)
	v_mov_b32_e32 v39, v14
	v_mov_b32_e32 v14, v11
	s_waitcnt lgkmcnt(1)
	v_mov_b32_e32 v40, v26
	s_waitcnt lgkmcnt(0)
; #define LAS __attribute__((address_space(3)))
; __device__ __forceinline__ unsigned f2bf(float f) { return pk2(f, 0.f) & 0xffffu; }
; #define LDS_WAIT() asm volatile("s_waitcnt lgkmcnt(0)" ::: "memory")
; __device__ __forceinline__ void ssm_sample_item(const bf16* UG, const float* SF, const float* cre, const float* cim, const float* dd, const float* sre, const float* sim,
;                                                 bf16* Gb, float* out, int s, int g, LAS float* hs, const LAS float* Cl, int lane) {
;     ...
;         y += (a[0] * hr[0] - bq[0] * hq[0]) + (a[1] * hr[1] - bq[1] * hq[1]) + (a[2] * hr[2] - bq[2] * hq[2]) + (a[3] * hr[3] - bq[3] * hq[3]); }
;     y += dval * uval;
;     Gb[(size_t)(MP + 4 * s + t) * 512 + 16 * g + c] = (bf16)f2bf(gelu_tanh(y));
;     LDS_WAIT(); asm volatile("" ::: "memory");
; }
; __global__ void __launch_bounds__(512, 2) mk_fwd(Args a) {
;     ...
;           for (int it = gw; it < NDEC * NG; it += NGW) { const int s_ = it / NG, g_ = it % NG;
;               if (g_ != gcur) { gcur = g_;
; #pragma unroll
;                   for (int q = 0; q < 4; ++q) { const int i4 = lane + 64 * q; *(LAS f32x4*)(Cl + (i4 >> 4) * 68 + 4 * (i4 & 15)) = *(const f32x4*)(INF(I_CRE) + g_ * 1024 + 4 * i4);
;                       *(LAS f32x4*)(Cl + 16 * 68 + (i4 >> 4) * 68 + 4 * (i4 & 15)) = *(const f32x4*)(INF(I_CIM) + g_ * 1024 + 4 * i4); }
;                   LDS_WAIT(); asm volatile("" ::: "memory"); }
	v_mov_b32_e32 v41, v30
	v_mov_b32_e32 v30, v27
	v_mov_b32_e32 v34, v2
	v_mov_b32_e32 v35, v6
	v_mov_b32_e32 v36, v18
	v_mov_b32_e32 v37, v22
	v_pk_mul_f32 v[38:39], v[38:39], v[40:41]
	v_mov_b32_e32 v6, v3
	v_mov_b32_e32 v22, v19
	v_pk_mul_f32 v[2:3], v[14:15], v[30:31]
	v_mov_b32_e32 v14, v12
	v_mov_b32_e32 v15, v16
	v_mov_b32_e32 v18, v28
	v_mov_b32_e32 v19, v32
	v_pk_fma_f32 v[34:35], v[34:35], v[36:37], v[38:39] neg_lo:[0,0,1] neg_hi:[0,0,1]
	v_pk_fma_f32 v[2:3], v[6:7], v[22:23], v[2:3] neg_lo:[0,0,1] neg_hi:[0,0,1]
	v_mov_b32_e32 v6, v4
	v_mov_b32_e32 v7, v8
	v_mov_b32_e32 v10, v20
	v_mov_b32_e32 v11, v24
	v_pk_mul_f32 v[14:15], v[14:15], v[18:19]
	v_mov_b32_e32 v16, v13
	v_mov_b32_e32 v32, v29
	v_pk_add_f32 v[2:3], v[34:35], v[2:3]
	v_pk_fma_f32 v[6:7], v[6:7], v[10:11], v[14:15] neg_lo:[0,0,1] neg_hi:[0,0,1]
	v_mov_b32_e32 v8, v5
	v_mov_b32_e32 v24, v21
	v_pk_mul_f32 v[4:5], v[16:17], v[32:33]
	v_pk_add_f32 v[2:3], v[6:7], v[2:3]
	v_pk_fma_f32 v[4:5], v[8:9], v[24:25], v[4:5] neg_lo:[0,0,1] neg_hi:[0,0,1]
	s_nop 0
	v_pk_add_f32 v[2:3], v[4:5], v[2:3]
	s_nop 0
	v_add_f32_e32 v2, v42, v2
	v_add_f32_e32 v42, v2, v3
	ds_read_b128 v[2:5], v76 offset:2240
	ds_read_b128 v[6:9], v76 offset:2256
	ds_read_b128 v[10:13], v76 offset:6592
	ds_read_b128 v[14:17], v76 offset:6608
	ds_read_b128 v[18:21], v88 offset:192
	ds_read_b128 v[22:25], v88 offset:208
	ds_read_b128 v[26:29], v88 offset:448
	ds_read_b128 v[30:33], v88 offset:464
	s_waitcnt lgkmcnt(5)
	v_mov_b32_e32 v38, v10
	s_waitcnt lgkmcnt(4)
	v_mov_b32_e32 v39, v14
	v_mov_b32_e32 v14, v11
	s_waitcnt lgkmcnt(1)
	v_mov_b32_e32 v40, v26
	s_waitcnt lgkmcnt(0)
	v_mov_b32_e32 v41, v30
	v_mov_b32_e32 v30, v27
	v_mov_b32_e32 v34, v2
	v_mov_b32_e32 v35, v6
	v_mov_b32_e32 v36, v18
	v_mov_b32_e32 v37, v22
	v_pk_mul_f32 v[38:39], v[38:39], v[40:41]
	v_mov_b32_e32 v6, v3
	v_mov_b32_e32 v22, v19
	v_pk_mul_f32 v[2:3], v[14:15], v[30:31]
	v_mov_b32_e32 v14, v12
	v_mov_b32_e32 v15, v16
	v_mov_b32_e32 v18, v28
	v_mov_b32_e32 v19, v32
	v_pk_fma_f32 v[34:35], v[34:35], v[36:37], v[38:39] neg_lo:[0,0,1] neg_hi:[0,0,1]
	v_pk_fma_f32 v[2:3], v[6:7], v[22:23], v[2:3] neg_lo:[0,0,1] neg_hi:[0,0,1]
	v_mov_b32_e32 v6, v4
	v_mov_b32_e32 v7, v8
	v_mov_b32_e32 v10, v20
	v_mov_b32_e32 v11, v24
	v_pk_mul_f32 v[14:15], v[14:15], v[18:19]
	v_mov_b32_e32 v16, v13
	v_mov_b32_e32 v32, v29
	v_pk_add_f32 v[2:3], v[34:35], v[2:3]
	v_pk_fma_f32 v[6:7], v[6:7], v[10:11], v[14:15] neg_lo:[0,0,1] neg_hi:[0,0,1]
	v_mov_b32_e32 v8, v5
	v_mov_b32_e32 v24, v21
	v_pk_mul_f32 v[4:5], v[16:17], v[32:33]
	v_pk_add_f32 v[2:3], v[6:7], v[2:3]
	v_pk_fma_f32 v[4:5], v[8:9], v[24:25], v[4:5] neg_lo:[0,0,1] neg_hi:[0,0,1]
	s_nop 0
	v_pk_add_f32 v[2:3], v[4:5], v[2:3]
	s_nop 0
	v_add_f32_e32 v2, v42, v2
	v_add_f32_e32 v42, v2, v3
	ds_read_b128 v[2:5], v76 offset:2272
	ds_read_b128 v[6:9], v76 offset:2288
	ds_read_b128 v[10:13], v76 offset:6624
	ds_read_b128 v[14:17], v76 offset:6640
	ds_read_b128 v[18:21], v88 offset:224
	ds_read_b128 v[22:25], v88 offset:240
	ds_read_b128 v[26:29], v88 offset:480
	ds_read_b128 v[30:33], v88 offset:496
	s_waitcnt lgkmcnt(5)
	v_mov_b32_e32 v38, v10
	s_waitcnt lgkmcnt(4)
	v_mov_b32_e32 v39, v14
	v_mov_b32_e32 v14, v11
	s_waitcnt lgkmcnt(1)
	v_mov_b32_e32 v40, v26
	s_waitcnt lgkmcnt(0)
	v_mov_b32_e32 v41, v30
	v_mov_b32_e32 v30, v27
	v_mov_b32_e32 v34, v2
	v_mov_b32_e32 v35, v6
	v_mov_b32_e32 v36, v18
	v_mov_b32_e32 v37, v22
	v_pk_mul_f32 v[38:39], v[38:39], v[40:41]
	v_mov_b32_e32 v6, v3
	v_mov_b32_e32 v22, v19
	v_pk_mul_f32 v[2:3], v[14:15], v[30:31]
	v_mov_b32_e32 v14, v12
	v_mov_b32_e32 v15, v16
	v_mov_b32_e32 v18, v28
	v_mov_b32_e32 v19, v32
	v_pk_fma_f32 v[34:35], v[34:35], v[36:37], v[38:39] neg_lo:[0,0,1] neg_hi:[0,0,1]
	v_pk_fma_f32 v[2:3], v[6:7], v[22:23], v[2:3] neg_lo:[0,0,1] neg_hi:[0,0,1]
	v_mov_b32_e32 v6, v4
	v_mov_b32_e32 v7, v8
	v_mov_b32_e32 v10, v20
	v_mov_b32_e32 v11, v24
	v_pk_mul_f32 v[14:15], v[14:15], v[18:19]
	v_mov_b32_e32 v16, v13
	v_mov_b32_e32 v32, v29
	v_pk_add_f32 v[2:3], v[34:35], v[2:3]
	v_pk_fma_f32 v[6:7], v[6:7], v[10:11], v[14:15] neg_lo:[0,0,1] neg_hi:[0,0,1]
	v_mov_b32_e32 v8, v5
	v_mov_b32_e32 v24, v21
	v_pk_mul_f32 v[4:5], v[16:17], v[32:33]
	v_pk_add_f32 v[2:3], v[6:7], v[2:3]
	v_pk_fma_f32 v[4:5], v[8:9], v[24:25], v[4:5] neg_lo:[0,0,1] neg_hi:[0,0,1]
	s_nop 0
	v_pk_add_f32 v[2:3], v[4:5], v[2:3]
	s_nop 0
	v_add_f32_e32 v2, v42, v2
	v_add_f32_e32 v2, v2, v3
	s_waitcnt vmcnt(2)
	v_lshlrev_b32_e32 v3, 16, v66
	v_fmac_f32_e32 v2, v71, v3
	v_mul_f32_e32 v3, 0x3d372713, v2
	v_mul_f32_e32 v3, v2, v3
	v_fma_f32 v3, v2, v3, v2
	v_mul_f32_e32 v3, 0x3f4c422a, v3
	v_mul_f32_e32 v3, 0xc038aa3b, v3
	v_exp_f32_e32 v3, v3
	s_nop 0
	v_add_f32_e32 v3, 1.0, v3
	s_nop 0
	v_rcp_f32_e32 v5, v3
	s_nop 0
	v_mul_f32_e32 v2, v2, v5
	v_cvt_pk_bf16_f32 v4, v2, s0
	v_lshl_add_u32 v2, s7, 2, v77
	v_ashrrev_i32_e32 v3, 31, v2
	v_lshlrev_b64 v[2:3], 10, v[2:3]
	s_ashr_i32 s7, s6, 31
	v_lshl_add_u64 v[2:3], s[2:3], 0, v[2:3]
	v_lshl_add_u64 v[2:3], s[6:7], 1, v[2:3]
	v_lshl_add_u64 v[2:3], v[2:3], 0, v[74:75]
	global_store_short v[2:3], v4, off
	s_waitcnt lgkmcnt(0)
	v_readlane_b32 s6, v255, 3
	s_mul_i32 s5, s6, 0x4200
	s_add_i32 s4, s4, s6
	s_add_i32 s28, s28, s5
	s_cmpk_gt_i32 s4, 0xfff
	v_readlane_b32 s7, v255, 4
	s_cbranch_scc1 .LBB0_420
.LBB0_418:
	s_ashr_i32 s5, s4, 31
	s_lshr_b32 s6, s5, 27
	s_add_i32 s6, s4, s6
	s_ashr_i32 s7, s6, 5
	s_andn2_b32 s6, s6, 31
	s_sub_i32 s6, s4, s6
	s_cmp_eq_u32 s6, s31
	s_cbranch_scc1 .LBB0_417
	s_lshl_b32 s8, s7, 15
	s_sub_i32 s8, s29, s8
	s_ashr_i32 s9, s8, 31
	s_lshl_b64 s[8:9], s[8:9], 2
	s_add_u32 s34, s14, s8
	s_addc_u32 s35, s15, s9
	s_add_u32 s8, s16, s8
	s_addc_u32 s9, s17, s9
	s_mov_b32 s31, s6
	global_load_dwordx4 v[2:5], v83, s[34:35]
	global_load_dwordx4 v[6:9], v83, s[8:9]
	global_load_dwordx4 v[10:13], v84, s[34:35]
	global_load_dwordx4 v[14:17], v84, s[8:9]
	global_load_dwordx4 v[18:21], v85, s[34:35]
	global_load_dwordx4 v[22:25], v85, s[8:9]
	global_load_dwordx4 v[26:29], v86, s[34:35]
	global_load_dwordx4 v[30:33], v86, s[8:9]
	s_waitcnt vmcnt(7)
	ds_write_b128 v78, v[2:5] offset:2048
	s_waitcnt vmcnt(6)
	ds_write_b128 v78, v[6:9] offset:6400
	s_waitcnt vmcnt(5)
	ds_write_b128 v79, v[10:13] offset:2048
	s_waitcnt vmcnt(4)
	ds_write_b128 v79, v[14:17] offset:6400
	s_waitcnt vmcnt(3)
	ds_write_b128 v80, v[18:21] offset:2048
	s_waitcnt vmcnt(2)
	ds_write_b128 v80, v[22:25] offset:6400
	s_waitcnt vmcnt(1)
	ds_write_b128 v81, v[26:29] offset:2048
	s_waitcnt vmcnt(0)
	ds_write_b128 v81, v[30:33] offset:6400
	s_waitcnt lgkmcnt(0)
	s_branch .LBB0_417

; __global__ void __launch_bounds__(512, 2) mk_fwd(Args a) {
;     ...
;         const float smax2 = __builtin_bit_cast(float, __builtin_amdgcn_readfirstlane(__builtin_bit_cast(int, 8.f * wave_max(fabsf(INF(I_QG)[lane])) * wave_max(fabsf(INF(I_KG)[lane])) * LOG2E)));
;         __syncthreads();
; #pragma unroll 1
;         for (int c0_ = bid; c0_ < 256; c0_ += G) {
;             const int c = (G == 256) ? (c0_ & 7) * 32 + (c0_ >> 3) : c0_;
;             const int grp = c >> 4, j = c & 15, b = grp >> 2, map = (grp >> 1) & 1, vh = grp & 1;
;             bf16x8 qrx[4];
; #pragma unroll
.LBB0_422:
.LBB0_423:
	v_readlane_b32 s0, v255, 50
	s_cmp_lg_u32 s0, 0
	s_cbranch_scc1 .Lp2_attn
	s_cmpk_lt_i32 s96, 0x80
	s_cbranch_scc1 .Lp2_attn
	v_readfirstlane_b32 s0, v2
	s_mov_b32 s1, 1
	s_nop 0
	v_writelane_b32 v255, s0, 51
	v_writelane_b32 v255, s1, 52
	s_branch .LBB0_479
.Lp2_attn:
	s_mov_b32 s0, 1
	v_writelane_b32 v255, s0, 50
	s_cmpk_eq_i32 s75, 0x100
	s_cselect_b64 s[70:71], -1, 0
	s_add_u32 s34, s94, 0x6900000
	s_addc_u32 s35, s95, 0
	s_add_u32 s42, s94, 0x7a00000
	s_addc_u32 s43, s95, 0
	s_add_u32 s44, s94, 0x8b00000
	v_mov_b32_e32 v1, 0x3e800000
	s_mov_b32 s12, 0xffff0000
	s_addc_u32 s45, s95, 0
	v_fmac_f32_e32 v1, 0x3f8147ae, v2
	s_mov_b32 s46, 0xc2fc0000
	s_mov_b32 s5, 0
	v_mov_b32_e32 v183, 0x42800000
	v_mov_b32_e32 v184, 0x3fb8aa3b
	v_mov_b32_e32 v177, 0
	s_mov_b64 s[6:7], 0x10000
	s_mov_b64 s[8:9], 0x20000
	s_mov_b64 s[10:11], 0x30000
	s_mov_b32 s13, -1
	v_mov_b32_e32 v185, 0xff800000
	s_mov_b32 s47, s96
	s_branch .LBB0_425

; __global__ void __launch_bounds__(512, 2) mk_fwd(Args a) {
;     ...
;           for (;;) {
;               __syncthreads();
;               if (tid == 0) qslot[0] = (int)atomicAdd(qctr, 1u);
;               __syncthreads();
;               const int u_ = __builtin_amdgcn_readfirstlane(qslot[0]);
;               if (u_ >= NDEC * NH * ((MK_DBL == 22) ? 2 : 1)) break;
.LBB0_481:
	s_mov_b64 s[0:1], 0
	s_barrier
	v_readlane_b32 s2, v255, 50
	s_cmp_lg_u32 s2, 0
	s_cbranch_scc1 .LBB0_482
	v_readlane_b32 s2, v255, 52
	s_add_i32 s2, s2, -1
	s_nop 0
	v_writelane_b32 v255, s2, 52
	s_cmp_lg_u32 s2, 0
	s_cbranch_scc1 .LBB0_482
	s_mov_b64 s[0:1], -1

; __device__ __forceinline__ void sattn_unit(const bf16* Qb, const bf16* Kb, const bf16* Vb, const float* ck, const float* cv, const int* pt, bf16* MIX, const float* sg, float lam,
;                                            int s, int h, int c0, LAS unsigned char* lds, int tid_in) {
;     ...
;     const int r32 = lane & 31, hi = lane >> 5;
;     bf16x8 qf[2][4];
; #pragma unroll
;     for (int mp = 0; mp < 2; ++mp)
; #pragma unroll
;         for (int ks = 0; ks < 4; ++ks) qf[mp][ks] = *(const bf16x8*)(Qb + (size_t)(MP + 4 * s + (r32 & 3)) * 512 + h * 128 + mp * 64 + 16 * ks + 8 * hi);
;     float mrun[8], lrun[8], acc[8][4];
; #pragma unroll
;     for (int c = 0; c < 8; ++c) { mrun[c] = -INFINITY; lrun[c] = 0.f; acc[c][0] = 0.f; acc[c][1] = 0.f; acc[c][2] = 0.f; acc[c][3] = 0.f; }
;     for (int chunk = c0 + w; chunk < 32; chunk += 8) {
;         const int page = pt[s * NPAGES + (chunk >> 1)];
; __global__ void __launch_bounds__(512, 2) mk_fwd(Args a) {
;     ...
;               const int u_ = __builtin_amdgcn_readfirstlane(qslot[0]);
;               if (u_ >= NDEC * NH * ((MK_DBL == 22) ? 2 : 1)) break;
;               const int u = u_ & (NDEC * NH - 1);
;               const int h = 3 - (u >> 7), s = u & 127;
;               const float a2 = exp2f(-2.f * (float)(h + 1)) * LOG2E; const int W = (int)fminf((2.f * smax2 + 36.f) / a2 + 1.f, 1.0e6f);
;               int c0 = (PAST - W) >> 6; c0 = __builtin_amdgcn_readfirstlane(c0 < 0 ? 0 : c0);
;     ...
;               sattn_unit((const bf16*)(ws + WS_QB), (const bf16*)(ws + WS_KB), (const bf16*)(ws + WS_VB), INF(I_CK), INF(I_CV), (const int*)a.in[I_PT], (bf16*)(ws + WS_MIX), INF(I_SUBLN), lam, s, h, c0, lds, tid);
.LBB0_487:
	s_or_b64 exec, exec, s[0:1]
	s_waitcnt lgkmcnt(0)
	s_barrier
	ds_read_b32 v2, v148
	s_mov_b64 s[0:1], -1
	s_waitcnt lgkmcnt(0)
	v_readfirstlane_b32 s2, v2
	s_cmpk_gt_i32 s2, 0x1ff
	s_cbranch_scc1 .LBB0_482
	s_lshr_b32 s0, s2, 6
	s_and_b32 s0, s0, 6
	s_or_b32 s0, s0, -8
	v_ldexp_f32 v2, 1.0, s0
	v_mul_f32_e32 v151, 0x3fb8aa3b, v2
	v_div_scale_f32 v2, s[0:1], v151, v151, v1
	v_rcp_f32_e32 v3, v2
	v_div_scale_f32 v4, vcc, v1, v151, v1
	s_and_b32 s18, s2, 0x7f
	v_fma_f32 v5, -v2, v3, 1.0
	v_fmac_f32_e32 v3, v5, v3
	v_mul_f32_e32 v5, v4, v3
	v_fma_f32 v6, -v2, v5, v4
	v_fmac_f32_e32 v5, v6, v3
	v_fma_f32 v2, -v2, v5, v4
	v_div_fmas_f32 v2, v2, v3, v5
	v_div_fixup_f32 v2, v2, v151, v1
	v_add_f32_e32 v2, 1.0, v2
	v_min_f32_e32 v2, 0x49742400, v2
	v_cvt_i32_f32_e32 v3, v2
	v_mov_b32_e32 v2, v0
	s_lshl_b32 s16, s18, 11
	v_sub_u32_e32 v3, 0x800, v3
	v_ashrrev_i32_e32 v3, 6, v3
	v_max_i32_e32 v3, 0, v3
	v_readfirstlane_b32 s19, v2
	v_readfirstlane_b32 s0, v3
	s_ashr_i32 s8, s19, 6
	s_lshl_b32 s9, s8, 9
	s_andn2_b32 s17, 0x180, s2
	v_and_b32_e32 v138, 31, v2
	s_add_i32 s20, s8, s0
	v_and_b32_e32 v150, 63, v2
	v_bfe_u32 v134, v2, 5, 1
	s_cmp_gt_i32 s20, 31
	v_lshlrev_b32_e32 v136, 4, v138
	s_cbranch_scc1 .LBB0_502
	v_lshlrev_b32_e32 v2, 9, v2
	v_and_b32_e32 v2, 0x600, v2
	v_or_b32_e32 v2, s16, v2
	v_lshlrev_b32_e32 v130, 1, v2
	v_lshl_add_u64 v[2:3], s[4:5], 0, v[130:131]
	s_lshl_b32 s6, s17, 1
	v_lshl_add_u64 v[2:3], v[2:3], 0, s[6:7]
	v_lshlrev_b32_e32 v130, 4, v134
	v_lshl_add_u64 v[2:3], v[2:3], 0, v[130:131]
	s_mov_b64 s[0:1], 0x1000000
	v_lshl_add_u64 v[4:5], v[2:3], 0, s[0:1]
	s_mov_b32 s0, 0x1000000
	v_add_co_u32_e32 v2, vcc, s0, v2
	v_readlane_b32 s52, v254, 10
	s_nop 0
	v_addc_co_u32_e32 v3, vcc, 0, v3, vcc
	global_load_dwordx4 v[18:21], v[4:5], off offset:32
	global_load_dwordx4 v[22:25], v[4:5], off offset:64
	global_load_dwordx4 v[26:29], v[4:5], off offset:96
	global_load_dwordx4 v[30:33], v[4:5], off offset:128
	global_load_dwordx4 v[34:37], v[4:5], off offset:160
	global_load_dwordx4 v[38:41], v[4:5], off offset:192
	global_load_dwordx4 v[42:45], v[2:3], off
	global_load_dwordx4 v[46:49], v[4:5], off offset:224
	s_lshl_b32 s0, s9, 2
	v_readlane_b32 s58, v254, 16
	v_readlane_b32 s59, v254, 17
	s_add_i32 s21, s0, 0
	s_lshl_b32 s22, s18, 4
	s_lshl_b32 s6, s17, 2
	s_mov_b64 s[50:51], s[58:59]
	v_readlane_b32 s53, v254, 11
	v_readlane_b32 s54, v254, 12
	v_readlane_b32 s55, v254, 13
	v_readlane_b32 s60, v254, 18
	v_readlane_b32 s61, v254, 19
	s_add_u32 s0, s50, s6
	v_readlane_b32 s62, v254, 20
	v_readlane_b32 s63, v254, 21
	s_mov_b64 s[52:53], s[60:61]
	s_addc_u32 s1, s51, 0
	v_lshlrev_b32_e32 v2, 5, v134
	v_mov_b32_e32 v3, v131
	v_lshl_add_u64 v[140:141], s[0:1], 0, v[2:3]
	s_add_u32 s0, s52, s6
	v_lshl_add_u32 v2, v138, 8, s21
	v_lshlrev_b32_e32 v3, 5, v150
	s_addc_u32 s1, s53, 0
	v_mov_b32_e32 v137, v131
	v_cmp_gt_u32_e64 s[2:3], 4, v138
	v_lshl_add_u32 v152, v150, 2, s21
	v_lshl_add_u64 v[142:143], s[0:1], 0, v[136:137]
	v_or_b32_e32 v144, 32, v138
	s_mov_b32 s25, 0xff800000
	v_mov_b32_e32 v85, 0
	v_mov_b32_e32 v84, 0
	v_mov_b32_e32 v83, 0
	v_mov_b32_e32 v82, 0
	v_mov_b32_e32 v89, 0
	v_mov_b32_e32 v88, 0
	v_mov_b32_e32 v87, 0
	v_mov_b32_e32 v86, 0
	v_mov_b32_e32 v50, 0
	v_mov_b32_e32 v51, 0
	v_mov_b32_e32 v54, 0
	v_mov_b32_e32 v55, 0
	v_mov_b32_e32 v52, 0
	v_mov_b32_e32 v53, 0
	v_mov_b32_e32 v56, 0
	v_mov_b32_e32 v57, 0
	v_mov_b32_e32 v58, 0
	v_mov_b32_e32 v59, 0
	v_mov_b32_e32 v62, 0
	v_mov_b32_e32 v63, 0
	v_mov_b32_e32 v60, 0
	v_mov_b32_e32 v61, 0
	v_mov_b32_e32 v64, 0
	v_mov_b32_e32 v65, 0
	v_mov_b32_e32 v66, 0
	v_mov_b32_e32 v67, 0
	v_mov_b32_e32 v74, 0
	v_mov_b32_e32 v75, 0
	v_mov_b32_e32 v68, 0
	v_mov_b32_e32 v69, 0
	v_mov_b32_e32 v76, 0
	v_mov_b32_e32 v77, 0
	v_mov_b32_e32 v78, 0
	v_mov_b32_e32 v79, 0
	v_mov_b32_e32 v70, 0
	v_mov_b32_e32 v71, 0
	v_mov_b32_e32 v80, 0
	v_mov_b32_e32 v81, 0
	v_mov_b32_e32 v72, 0
	v_mov_b32_e32 v73, 0
	v_add_u32_e32 v137, s21, v3
	v_add_u32_e32 v130, v2, v130
	s_mov_b32 s26, 0xff800000
	s_mov_b32 s29, 0xff800000
	s_mov_b32 s30, 0xff800000
	s_mov_b32 s35, 0xff800000
	s_mov_b32 s42, 0xff800000
	s_mov_b32 s44, 0xff800000
	s_mov_b32 s6, 0xff800000
	v_readlane_b32 s56, v254, 14
	v_readlane_b32 s57, v254, 15
	v_readlane_b32 s64, v254, 22
	v_readlane_b32 s65, v254, 23
	v_readlane_b32 s66, v254, 24
	v_readlane_b32 s67, v254, 25
	s_mov_b64 s[54:55], s[62:63]
	v_and_b32_e32 v246, 15, v252
	v_add_lshl_u32 v246, v246, s22, 2
	global_load_dword v246, v246, s[62:63]
; __device__ __forceinline__ u32x4 pack8(const f32x4 a, const f32x4 b) { u32x4 w; w.x = cvt_pk_bf16(a[0], a[1]); w.y = cvt_pk_bf16(a[2], a[3]); w.z = cvt_pk_bf16(b[0], b[1]); w.w = cvt_pk_bf16(b[2], b[3]); return w; }
; __device__ __forceinline__ void sattn_unit(const bf16* Qb, const bf16* Kb, const bf16* Vb, const float* ck, const float* cv, const int* pt, bf16* MIX, const float* sg, float lam,
;                                            int s, int h, int c0, LAS unsigned char* lds, int tid_in) {
;     ...
;     for (int chunk = c0 + w; chunk < 32; chunk += 8) {
;         const int page = pt[s * NPAGES + (chunk >> 1)];
;         const size_t tok0 = (size_t)page * PAGE + (chunk & 1) * 64;
;         const int kp0 = 64 * chunk;
; #pragma unroll
;         for (int mp = 0; mp < 2; ++mp) {
;             f32x4 kk[2][4][2];
; #pragma unroll
;             for (int kb = 0; kb < 2; ++kb)
; #pragma unroll
;                 for (int ks = 0; ks < 4; ++ks) { const float* kp = ck + ((tok0 + kb * 32 + r32) * NH + h) * 128 + mp * 64 + 16 * ks + 8 * hi;
;                     kk[kb][ks][0] = *(const f32x4*)kp; kk[kb][ks][1] = *(const f32x4*)(kp + 4); }
;             asm volatile("s_waitcnt vmcnt(0)" ::: "memory");
; #pragma unroll
;             for (int kb = 0; kb < 2; ++kb) { f32x16 sa = {};
; #pragma unroll
;                 for (int ks = 0; ks < 4; ++ks) { const u32x4 kw = ep::pack8(kk[kb][ks][0], kk[kb][ks][1]);
;                     sa = __builtin_amdgcn_mfma_f32_32x32x16_bf16(__builtin_bit_cast(bf16x8, kw), qf[mp][ks], sa, 0, 0, 0); }
;                 if (r32 < 4) {
; #pragma unroll
;                     for (int r = 0; r < 16; ++r) sc[(mp * 4 + r32) * 64 + kb * 32 + (r & 3) + 8 * (r >> 2) + 4 * hi] = sa[r]; } }
.LBB0_490:
	s_ashr_i32 s0, s20, 1
	s_waitcnt vmcnt(0)
	v_readlane_b32 s1, v246, s0
	v_readlane_b32 s52, v254, 10
	v_readlane_b32 s62, v254, 20
	v_readlane_b32 s63, v254, 21
	s_lshl_b32 s23, s20, 6
	s_and_b32 s0, s23, 64
	v_readlane_b32 s53, v254, 11
	v_readlane_b32 s54, v254, 12
	v_readlane_b32 s55, v254, 13
	v_readlane_b32 s56, v254, 14
	v_readlane_b32 s57, v254, 15
	v_readlane_b32 s58, v254, 16
	v_readlane_b32 s59, v254, 17
	v_readlane_b32 s60, v254, 18
	v_readlane_b32 s61, v254, 19
	v_readlane_b32 s64, v254, 22
	v_readlane_b32 s65, v254, 23
	v_readlane_b32 s66, v254, 24
	v_readlane_b32 s67, v254, 25
	v_mov_b32_e32 v2, s1
	v_ashrrev_i32_e32 v3, 31, v2
	v_lshlrev_b64 v[122:123], 7, v[2:3]
	v_or_b32_e32 v128, s0, v122
	v_or_b32_e32 v122, v128, v138
	v_lshlrev_b64 v[2:3], 11, v[122:123]
	v_lshl_add_u64 v[124:125], v[140:141], 0, v[2:3]
	global_load_dwordx4 v[2:5], v[124:125], off offset:16
	global_load_dwordx4 v[6:9], v[124:125], off
	global_load_dwordx4 v[154:157], v[124:125], off offset:80
	global_load_dwordx4 v[158:161], v[124:125], off offset:64
	global_load_dwordx4 v[162:165], v[124:125], off offset:144
	global_load_dwordx4 v[166:169], v[124:125], off offset:128
	global_load_dwordx4 v[170:173], v[124:125], off offset:208
	global_load_dwordx4 v[174:177], v[124:125], off offset:192
	v_or_b32_e32 v122, v128, v144
	v_lshlrev_b64 v[10:11], 11, v[122:123]
	v_lshl_add_u64 v[126:127], v[140:141], 0, v[10:11]
	global_load_dwordx4 v[114:117], v[126:127], off offset:16
	global_load_dwordx4 v[118:121], v[126:127], off
	global_load_dwordx4 v[106:109], v[126:127], off offset:80
	global_load_dwordx4 v[110:113], v[126:127], off offset:64
	global_load_dwordx4 v[98:101], v[126:127], off offset:144
	global_load_dwordx4 v[102:105], v[126:127], off offset:128
	global_load_dwordx4 v[90:93], v[126:127], off offset:208
	global_load_dwordx4 v[94:97], v[126:127], off offset:192
	global_load_dwordx4 v[178:181], v[124:125], off offset:272
	global_load_dwordx4 v[182:185], v[124:125], off offset:256
	global_load_dwordx4 v[186:189], v[124:125], off offset:336
	global_load_dwordx4 v[190:193], v[124:125], off offset:320
	global_load_dwordx4 v[194:197], v[124:125], off offset:400
	global_load_dwordx4 v[198:201], v[124:125], off offset:384
	global_load_dwordx4 v[202:205], v[124:125], off offset:464
	global_load_dwordx4 v[206:209], v[124:125], off offset:448
	global_load_dwordx4 v[210:213], v[126:127], off offset:272
	global_load_dwordx4 v[214:217], v[126:127], off offset:256
	global_load_dwordx4 v[218:221], v[126:127], off offset:336
	global_load_dwordx4 v[222:225], v[126:127], off offset:320
	global_load_dwordx4 v[226:229], v[126:127], off offset:400
	global_load_dwordx4 v[230:233], v[126:127], off offset:384
	global_load_dwordx4 v[234:237], v[126:127], off offset:464
	global_load_dwordx4 v[242:245], v[126:127], off offset:448
	s_waitcnt vmcnt(16)
	s_waitcnt vmcnt(30)
	v_cvt_pk_bf16_f32 v6, v6, v7
	v_cvt_pk_bf16_f32 v7, v8, v9
	v_cvt_pk_bf16_f32 v8, v2, v3
	v_cvt_pk_bf16_f32 v9, v4, v5
	s_waitcnt vmcnt(28)
	v_cvt_pk_bf16_f32 v158, v158, v159
	v_cvt_pk_bf16_f32 v159, v160, v161
	v_mfma_f32_32x32x16_bf16 v[2:17], v[6:9], v[42:45], 0
	v_cvt_pk_bf16_f32 v160, v154, v155
	v_cvt_pk_bf16_f32 v161, v156, v157
	s_waitcnt vmcnt(26)
	v_cvt_pk_bf16_f32 v154, v166, v167
	v_cvt_pk_bf16_f32 v155, v168, v169
	v_cvt_pk_bf16_f32 v156, v162, v163
	v_cvt_pk_bf16_f32 v157, v164, v165
	v_mfma_f32_32x32x16_bf16 v[2:17], v[158:161], v[18:21], v[2:17]
	s_nop 0
	v_mfma_f32_32x32x16_bf16 v[2:17], v[154:157], v[22:25], v[2:17]
	s_waitcnt vmcnt(24)
	v_cvt_pk_bf16_f32 v154, v174, v175
	v_cvt_pk_bf16_f32 v155, v176, v177
	v_cvt_pk_bf16_f32 v156, v170, v171
	v_cvt_pk_bf16_f32 v157, v172, v173
	s_nop 1
	v_mfma_f32_32x32x16_bf16 v[2:17], v[154:157], v[26:29], v[2:17]
	s_and_saveexec_b64 s[0:1], s[2:3]
	s_cbranch_execz .LBB0_492
	s_nop 9
	ds_write_b128 v130, v[2:5]
	ds_write_b128 v130, v[6:9] offset:32
	ds_write_b128 v130, v[10:13] offset:64
	ds_write_b128 v130, v[14:17] offset:96
; __device__ __forceinline__ u32x4 pack8(const f32x4 a, const f32x4 b) { u32x4 w; w.x = cvt_pk_bf16(a[0], a[1]); w.y = cvt_pk_bf16(a[2], a[3]); w.z = cvt_pk_bf16(b[0], b[1]); w.w = cvt_pk_bf16(b[2], b[3]); return w; }
; __device__ __forceinline__ void sattn_unit(const bf16* Qb, const bf16* Kb, const bf16* Vb, const float* ck, const float* cv, const int* pt, bf16* MIX, const float* sg, float lam,
;                                            int s, int h, int c0, LAS unsigned char* lds, int tid_in) {
;     ...
;         for (int mp = 0; mp < 2; ++mp) {
;             f32x4 kk[2][4][2];
; #pragma unroll
;             for (int kb = 0; kb < 2; ++kb)
; #pragma unroll
;                 for (int ks = 0; ks < 4; ++ks) { const float* kp = ck + ((tok0 + kb * 32 + r32) * NH + h) * 128 + mp * 64 + 16 * ks + 8 * hi;
;                     kk[kb][ks][0] = *(const f32x4*)kp; kk[kb][ks][1] = *(const f32x4*)(kp + 4); }
;             asm volatile("s_waitcnt vmcnt(0)" ::: "memory");
; #pragma unroll
;             for (int kb = 0; kb < 2; ++kb) { f32x16 sa = {};
; #pragma unroll
;                 for (int ks = 0; ks < 4; ++ks) { const u32x4 kw = ep::pack8(kk[kb][ks][0], kk[kb][ks][1]);
;                     sa = __builtin_amdgcn_mfma_f32_32x32x16_bf16(__builtin_bit_cast(bf16x8, kw), qf[mp][ks], sa, 0, 0, 0); }
;                 if (r32 < 4) {
; #pragma unroll
;                     for (int r = 0; r < 16; ++r) sc[(mp * 4 + r32) * 64 + kb * 32 + (r & 3) + 8 * (r >> 2) + 4 * hi] = sa[r]; } }
.LBB0_492:
	s_or_b64 exec, exec, s[0:1]
	s_waitcnt vmcnt(22)
	s_nop 7
	v_cvt_pk_bf16_f32 v2, v118, v119
	v_cvt_pk_bf16_f32 v3, v120, v121
	v_cvt_pk_bf16_f32 v4, v114, v115
	v_cvt_pk_bf16_f32 v5, v116, v117
	s_waitcnt vmcnt(20)
	v_cvt_pk_bf16_f32 v110, v110, v111
	v_cvt_pk_bf16_f32 v111, v112, v113
	v_mfma_f32_32x32x16_bf16 v[2:17], v[2:5], v[42:45], 0
	v_cvt_pk_bf16_f32 v112, v106, v107
	v_cvt_pk_bf16_f32 v113, v108, v109
	s_waitcnt vmcnt(18)
	v_cvt_pk_bf16_f32 v102, v102, v103
	v_cvt_pk_bf16_f32 v103, v104, v105
	v_cvt_pk_bf16_f32 v104, v98, v99
	v_cvt_pk_bf16_f32 v105, v100, v101
	s_waitcnt vmcnt(16)
	v_cvt_pk_bf16_f32 v94, v94, v95
	v_mfma_f32_32x32x16_bf16 v[2:17], v[110:113], v[18:21], v[2:17]
	v_cvt_pk_bf16_f32 v95, v96, v97
	v_cvt_pk_bf16_f32 v96, v90, v91
	v_cvt_pk_bf16_f32 v97, v92, v93
	v_mfma_f32_32x32x16_bf16 v[2:17], v[102:105], v[22:25], v[2:17]
	s_nop 0
	v_mfma_f32_32x32x16_bf16 v[2:17], v[94:97], v[26:29], v[2:17]
	s_and_saveexec_b64 s[0:1], s[2:3]
	s_cbranch_execz .LBB0_494
	s_nop 9
	ds_write_b128 v130, v[2:5] offset:128
	ds_write_b128 v130, v[6:9] offset:160
	ds_write_b128 v130, v[10:13] offset:192
	ds_write_b128 v130, v[14:17] offset:224
.LBB0_494:
	s_or_b64 exec, exec, s[0:1]
	s_nop 8
	s_waitcnt vmcnt(0)
	s_waitcnt vmcnt(14)
	v_cvt_pk_bf16_f32 v6, v182, v183
	v_cvt_pk_bf16_f32 v7, v184, v185
	v_cvt_pk_bf16_f32 v8, v178, v179
	v_cvt_pk_bf16_f32 v9, v180, v181
	s_waitcnt vmcnt(12)
	v_cvt_pk_bf16_f32 v124, v190, v191
	v_cvt_pk_bf16_f32 v125, v192, v193
	v_mfma_f32_32x32x16_bf16 v[2:17], v[6:9], v[30:33], 0
	v_cvt_pk_bf16_f32 v126, v186, v187
	v_cvt_pk_bf16_f32 v127, v188, v189
	s_nop 1
	v_mfma_f32_32x32x16_bf16 v[2:17], v[124:127], v[34:37], v[2:17]
	s_waitcnt vmcnt(10)
	v_cvt_pk_bf16_f32 v124, v198, v199
	v_cvt_pk_bf16_f32 v125, v200, v201
	v_cvt_pk_bf16_f32 v126, v194, v195
	v_cvt_pk_bf16_f32 v127, v196, v197
	s_nop 1
	v_mfma_f32_32x32x16_bf16 v[2:17], v[124:127], v[38:41], v[2:17]
	s_waitcnt vmcnt(8)
	v_cvt_pk_bf16_f32 v124, v206, v207
	v_cvt_pk_bf16_f32 v125, v208, v209
	v_cvt_pk_bf16_f32 v126, v202, v203
	v_cvt_pk_bf16_f32 v127, v204, v205
	s_nop 1
	v_mfma_f32_32x32x16_bf16 v[2:17], v[124:127], v[46:49], v[2:17]
	s_and_saveexec_b64 s[0:1], s[2:3]
	s_cbranch_execz .LBB0_496
	s_nop 9
	ds_write_b128 v130, v[2:5] offset:1024
	ds_write_b128 v130, v[6:9] offset:1056
	ds_write_b128 v130, v[10:13] offset:1088
	ds_write_b128 v130, v[14:17] offset:1120
.LBB0_496:
	s_or_b64 exec, exec, s[0:1]
	s_waitcnt vmcnt(6)
	s_nop 7
	v_cvt_pk_bf16_f32 v2, v214, v215
	v_cvt_pk_bf16_f32 v3, v216, v217
	v_cvt_pk_bf16_f32 v4, v210, v211
	v_cvt_pk_bf16_f32 v5, v212, v213
	s_waitcnt vmcnt(4)
	v_cvt_pk_bf16_f32 v110, v222, v223
	v_cvt_pk_bf16_f32 v111, v224, v225
	v_mfma_f32_32x32x16_bf16 v[2:17], v[2:5], v[30:33], 0
	v_cvt_pk_bf16_f32 v112, v218, v219
	v_cvt_pk_bf16_f32 v113, v220, v221
	s_waitcnt vmcnt(2)
	v_cvt_pk_bf16_f32 v102, v230, v231
	v_cvt_pk_bf16_f32 v103, v232, v233
	v_cvt_pk_bf16_f32 v104, v226, v227
	v_cvt_pk_bf16_f32 v105, v228, v229
	s_waitcnt vmcnt(0)
	v_cvt_pk_bf16_f32 v94, v242, v243
	v_mfma_f32_32x32x16_bf16 v[2:17], v[110:113], v[34:37], v[2:17]
	v_cvt_pk_bf16_f32 v95, v244, v245
	v_cvt_pk_bf16_f32 v96, v234, v235
	v_cvt_pk_bf16_f32 v97, v236, v237
	v_mfma_f32_32x32x16_bf16 v[2:17], v[102:105], v[38:41], v[2:17]
	s_nop 0
	v_mfma_f32_32x32x16_bf16 v[2:17], v[94:97], v[46:49], v[2:17]
	s_and_saveexec_b64 s[0:1], s[2:3]
	s_cbranch_execz .LBB0_498
	s_nop 9
	ds_write_b128 v130, v[2:5] offset:1152
	ds_write_b128 v130, v[6:9] offset:1184
	ds_write_b128 v130, v[10:13] offset:1216
	ds_write_b128 v130, v[14:17] offset:1248

; #define LAS __attribute__((address_space(3)))
; __device__ __forceinline__ void sattn_unit(const bf16* Qb, const bf16* Kb, const bf16* Vb, const float* ck, const float* cv, const int* pt, bf16* MIX, const float* sg, float lam,
;                                            int s, int h, int c0, LAS unsigned char* lds, int tid_in) {
;     ...
;     __syncthreads();
;     { const int map = w >> 2, t = w & 3;
;       const float q = bf2f(Qb[(size_t)(MP + 4 * s + t) * 512 + h * 128 + map * 64 + lane]);
;       float sn[4];
; #pragma unroll
;       for (int t2 = 0; t2 < 4; ++t2) { const float kk = bf2f(Kb[(size_t)(MP + 4 * s + t2) * 512 + h * 128 + map * 64 + lane]); sn[t2] = wave_sum(q * kk) - slope2 * (float)(t - t2); if (t2 > t) sn[t2] = -INFINITY; }
;       float M = fmaxf(fmaxf(sn[0], sn[1]), fmaxf(sn[2], sn[3]));
; #pragma unroll
;       for (int w2 = 0; w2 < 8; ++w2) M = fmaxf(M, ml[w2 * 8 + w]);
;       float L = 0.f, o0 = 0.f, o1 = 0.f;
; #pragma unroll
;       for (int w2 = 0; w2 < 8; ++w2) { const float f = __builtin_amdgcn_exp2f(ml[w2 * 8 + w] - M); L += ml[64 + w2 * 8 + w] * f;
;           const f32x2 a = *(const LAS f32x2*)(accm + ((2 * w2) * 8 + w) * 128 + 2 * lane), b2 = *(const LAS f32x2*)(accm + ((2 * w2 + 1) * 8 + w) * 128 + 2 * lane); o0 += (a[0] + b2[0]) * f; o1 += (a[1] + b2[1]) * f; }
; #pragma unroll
;       for (int t2 = 0; t2 < 4; ++t2) { const float p = __builtin_amdgcn_exp2f(sn[t2] - M); L += p; const unsigned vv = *(const unsigned*)(Vb + (size_t)(MP + 4 * s + t2) * 512 + h * 128 + 2 * lane); o0 += p * bflo(vv); o1 += p * bfhi(vv); }
.LBB0_505:
	s_or_b64 exec, exec, s[0:1]
	s_lshl_b32 s20, s18, 2
	s_bfe_u32 s1, s19, 0x20006
	s_bitset1_b32 s20, 14
	s_or_b32 s0, s1, s20
	s_ashr_i32 s2, s19, 2
	s_andn2_b32 s2, s2, 63
	s_lshl_b32 s0, s0, 10
	s_lshl_b32 s18, s17, 1
	s_ashr_i32 s3, s2, 31
	s_or_b32 s0, s0, s18
	s_add_u32 s0, s4, s0
	s_addc_u32 s6, s5, 0
	s_lshl_b64 s[2:3], s[2:3], 1
	s_add_u32 s22, s0, s2
	s_addc_u32 s23, s6, s3
	s_add_u32 s2, s11, s2
	s_addc_u32 s3, s12, s3
	v_lshlrev_b32_e32 v130, 1, v150
	s_lshl_b32 s0, s20, 10
	v_lshl_add_u64 v[2:3], s[2:3], 0, v[130:131]
	s_or_b32 s6, s0, s18
	v_lshl_add_u64 v[4:5], v[2:3], 0, s[6:7]
	s_waitcnt lgkmcnt(0)
	s_barrier
	global_load_ushort v4, v[4:5], off
	s_nop 0
	global_load_ushort v5, v130, s[22:23]
	s_or_b32 s19, s16, 0x800200
	s_or_b32 s21, s16, 0x800400
	s_or_b32 s16, s16, 0x800600
	s_add_i32 s3, s1, -3
	v_lshlrev_b32_e32 v38, 2, v150
	v_mov_b32_e32 v39, v131
	s_waitcnt vmcnt(1)
	v_lshlrev_b32_e32 v4, 16, v4
	s_waitcnt vmcnt(0)
	v_lshlrev_b32_e32 v6, 16, v5
	v_mul_f32_e32 v5, v4, v6
	s_nop 1
	v_mov_b32_dpp v5, v5 row_shr:1 row_mask:0xf bank_mask:0xf bound_ctrl:1
	v_fmac_f32_e32 v5, v4, v6
	s_nop 1
	v_add_f32_dpp v4, v5, v5 row_shr:2 row_mask:0xf bank_mask:0xf bound_ctrl:1
	v_mov_b32_e32 v5, v131
	s_nop 0
	v_add_f32_dpp v4, v4, v4 row_shr:4 row_mask:0xf bank_mask:0xf bound_ctrl:1
	s_nop 1
	v_add_f32_dpp v4, v4, v4 row_shr:8 row_mask:0xf bank_mask:0xf bound_ctrl:1
	s_nop 1
	v_mov_b32_dpp v5, v4 row_bcast:15 row_mask:0xa bank_mask:0xf
	v_add_f32_e32 v4, v4, v5
	v_mov_b32_e32 v5, v131
	s_nop 1
	v_mov_b32_dpp v5, v4 row_bcast:31 row_mask:0xc bank_mask:0xf
	v_add_f32_e32 v4, v4, v5
	s_nop 0
	v_readlane_b32 s2, v4, 63
	v_cvt_f32_ubyte0_e32 v4, s1
	s_nop 0
	v_fma_f32 v30, -v151, v4, s2
	s_or_b32 s2, s19, s17
	s_lshl_b32 s6, s2, 1
	v_lshl_add_u64 v[4:5], v[2:3], 0, s[6:7]
	global_load_ushort v4, v[4:5], off
	s_waitcnt vmcnt(0)
	v_lshlrev_b32_e32 v4, 16, v4
	v_mul_f32_e32 v5, v6, v4
	s_nop 1
	v_mov_b32_dpp v5, v5 row_shr:1 row_mask:0xf bank_mask:0xf bound_ctrl:1
	v_fmac_f32_e32 v5, v6, v4
	s_nop 1
	v_add_f32_dpp v4, v5, v5 row_shr:2 row_mask:0xf bank_mask:0xf bound_ctrl:1
	v_mov_b32_e32 v5, v131
	s_nop 0
	v_add_f32_dpp v4, v4, v4 row_shr:4 row_mask:0xf bank_mask:0xf bound_ctrl:1
	s_nop 1
	v_add_f32_dpp v4, v4, v4 row_shr:8 row_mask:0xf bank_mask:0xf bound_ctrl:1
	s_nop 1
	v_mov_b32_dpp v5, v4 row_bcast:15 row_mask:0xa bank_mask:0xf
	v_add_f32_e32 v4, v4, v5
	v_mov_b32_e32 v5, v131
	s_nop 1
	v_mov_b32_dpp v5, v4 row_bcast:31 row_mask:0xc bank_mask:0xf
	v_add_f32_e32 v4, v4, v5
	s_nop 0
	v_readlane_b32 s2, v4, 63
	v_sub_co_u32_e64 v4, vcc, s1, 1
	v_cvt_f32_i32_e32 v4, v4
	v_fma_f32 v4, -v151, v4, s2
	s_or_b32 s2, s21, s17
	s_lshl_b32 s6, s2, 1
	v_cndmask_b32_e32 v32, v4, v145, vcc
	v_lshl_add_u64 v[4:5], v[2:3], 0, s[6:7]
	global_load_ushort v4, v[4:5], off
	s_waitcnt vmcnt(0)
	v_lshlrev_b32_e32 v4, 16, v4
	v_mul_f32_e32 v5, v6, v4
	s_nop 1
	v_mov_b32_dpp v5, v5 row_shr:1 row_mask:0xf bank_mask:0xf bound_ctrl:1
	v_fmac_f32_e32 v5, v6, v4
	s_nop 1
	v_add_f32_dpp v4, v5, v5 row_shr:2 row_mask:0xf bank_mask:0xf bound_ctrl:1
	v_mov_b32_e32 v5, v131
	s_nop 0
	v_add_f32_dpp v4, v4, v4 row_shr:4 row_mask:0xf bank_mask:0xf bound_ctrl:1
	s_nop 1
	v_add_f32_dpp v4, v4, v4 row_shr:8 row_mask:0xf bank_mask:0xf bound_ctrl:1
	s_nop 1
	v_mov_b32_dpp v5, v4 row_bcast:15 row_mask:0xa bank_mask:0xf
	v_add_f32_e32 v4, v4, v5
	v_mov_b32_e32 v5, v131
	s_nop 1
	v_mov_b32_dpp v5, v4 row_bcast:31 row_mask:0xc bank_mask:0xf
	v_add_f32_e32 v4, v4, v5
	s_nop 0
	v_readlane_b32 s2, v4, 63
	v_sub_co_u32_e64 v4, vcc, s1, 2
	v_cvt_f32_i32_e32 v4, v4
	v_fma_f32 v4, -v151, v4, s2
	s_or_b32 s2, s16, s17
	s_lshl_b32 s6, s2, 1
	v_lshl_add_u64 v[2:3], v[2:3], 0, s[6:7]
	global_load_ushort v2, v[2:3], off
	s_cmp_eq_u32 s1, 3
	v_cndmask_b32_e32 v36, v4, v145, vcc
	s_cselect_b64 vcc, -1, 0
	s_lshl_b32 s1, s8, 2
	s_add_i32 s1, s1, 0
	s_waitcnt vmcnt(0)
	v_lshlrev_b32_e32 v2, 16, v2
	v_mul_f32_e32 v3, v6, v2
	s_nop 1
	v_mov_b32_dpp v3, v3 row_shr:1 row_mask:0xf bank_mask:0xf bound_ctrl:1
	v_fmac_f32_e32 v3, v6, v2
	s_nop 1
	v_add_f32_dpp v2, v3, v3 row_shr:2 row_mask:0xf bank_mask:0xf bound_ctrl:1
	v_mov_b32_e32 v3, v131
	s_nop 0
	v_add_f32_dpp v2, v2, v2 row_shr:4 row_mask:0xf bank_mask:0xf bound_ctrl:1
	s_nop 1
	v_add_f32_dpp v2, v2, v2 row_shr:8 row_mask:0xf bank_mask:0xf bound_ctrl:1
	s_nop 1
	v_mov_b32_dpp v3, v2 row_bcast:15 row_mask:0xa bank_mask:0xf
	v_add_f32_e32 v2, v2, v3
	v_mov_b32_e32 v3, v131
	s_nop 1
	v_mov_b32_dpp v3, v2 row_bcast:31 row_mask:0xc bank_mask:0xf
	v_add_f32_e32 v2, v2, v3
	s_nop 0
	v_readlane_b32 s2, v2, 63
	v_cvt_f32_i32_e32 v2, s3
	s_nop 0
	v_fma_f32 v2, -v151, v2, s2
	s_add_i32 s2, s1, 0x18000
	v_mov_b32_e32 v3, s2
	ds_read2_b32 v[6:7], v3 offset1:8
	ds_read2_b32 v[10:11], v3 offset0:16 offset1:24
	v_cndmask_b32_e32 v33, v145, v2, vcc
	ds_read2_b32 v[12:13], v3 offset0:32 offset1:40
	v_max_f32_e32 v2, v36, v33
	ds_read2_b32 v[14:15], v3 offset0:48 offset1:56
	v_max3_f32 v2, v30, v32, v2
	s_waitcnt lgkmcnt(3)
	v_max3_f32 v2, v2, v6, v7
	s_waitcnt lgkmcnt(2)
	v_max3_f32 v2, v2, v10, v11
	s_waitcnt lgkmcnt(1)
	v_max3_f32 v2, v2, v12, v13
	s_waitcnt lgkmcnt(0)
	v_max3_f32 v37, v2, v14, v15
	s_add_i32 s2, s9, 0
	v_lshl_add_u32 v31, v150, 3, s2
	v_sub_f32_e32 v2, v6, v37
	s_add_i32 s2, s1, 0x18100
	v_exp_f32_e32 v16, v2
	v_mov_b32_e32 v2, s2
	v_sub_f32_e32 v6, v7, v37
	s_add_i32 s2, s1, 0x18120
	ds_read_b32 v2, v2
	v_exp_f32_e32 v18, v6
	v_mov_b32_e32 v6, s2
	ds_read_b32 v6, v6
	v_add_u32_e32 v17, 0x8000, v31
	s_waitcnt lgkmcnt(1)
	v_fma_f32 v15, v2, v16, 0
	ds_read2st64_b64 v[2:5], v31 offset0:64 offset1:72
	s_add_i32 s2, s1, 0x18140
	s_waitcnt lgkmcnt(1)
; #define LAS __attribute__((address_space(3)))
; __device__ __forceinline__ void sattn_unit(const bf16* Qb, const bf16* Kb, const bf16* Vb, const float* ck, const float* cv, const int* pt, bf16* MIX, const float* sg, float lam,
;                                            int s, int h, int c0, LAS unsigned char* lds, int tid_in) {
;     ...
;       for (int w2 = 0; w2 < 8; ++w2) M = fmaxf(M, ml[w2 * 8 + w]);
;       float L = 0.f, o0 = 0.f, o1 = 0.f;
; #pragma unroll
;       for (int w2 = 0; w2 < 8; ++w2) { const float f = __builtin_amdgcn_exp2f(ml[w2 * 8 + w] - M); L += ml[64 + w2 * 8 + w] * f;
;           const f32x2 a = *(const LAS f32x2*)(accm + ((2 * w2) * 8 + w) * 128 + 2 * lane), b2 = *(const LAS f32x2*)(accm + ((2 * w2 + 1) * 8 + w) * 128 + 2 * lane); o0 += (a[0] + b2[0]) * f; o1 += (a[1] + b2[1]) * f; }
; #pragma unroll
;       for (int t2 = 0; t2 < 4; ++t2) { const float p = __builtin_amdgcn_exp2f(sn[t2] - M); L += p; const unsigned vv = *(const unsigned*)(Vb + (size_t)(MP + 4 * s + t2) * 512 + h * 128 + 2 * lane); o0 += p * bflo(vv); o1 += p * bfhi(vv); }
;       const float rl = 1.f / L;
;       *(LAS f32x2*)(fin + w * 128 + 2 * lane) = (f32x2){o0 * rl, o1 * rl}; }
;     __syncthreads();
	v_fmac_f32_e32 v15, v6, v18
	ds_read2st64_b64 v[6:9], v31 offset0:80 offset1:88
	v_sub_f32_e32 v30, v30, v37
	s_waitcnt lgkmcnt(1)
	v_pk_add_f32 v[2:3], v[2:3], v[4:5]
	v_exp_f32_e32 v30, v30
	v_pk_fma_f32 v[2:3], v[2:3], v[16:17], 0 op_sel_hi:[1,0,0]
	s_waitcnt lgkmcnt(0)
	v_pk_add_f32 v[4:5], v[6:7], v[8:9]
	v_sub_f32_e32 v32, v32, v37
	v_pk_fma_f32 v[18:19], v[18:19], v[4:5], v[2:3] op_sel_hi:[0,1,1]
	v_sub_f32_e32 v2, v10, v37
	v_exp_f32_e32 v20, v2
	v_mov_b32_e32 v2, s2
	ds_read_b32 v6, v2
	ds_read2st64_b64 v[2:5], v31 offset0:96 offset1:104
	s_add_i32 s2, s1, 0x18160
	v_sub_f32_e32 v10, v14, v37
	v_exp_f32_e32 v28, v10
	v_exp_f32_e32 v32, v32
	s_waitcnt lgkmcnt(0)
	v_pk_add_f32 v[22:23], v[2:3], v[4:5]
	v_sub_f32_e32 v2, v11, v37
	v_exp_f32_e32 v21, v2
	v_mov_b32_e32 v2, s2
	ds_read_b32 v7, v2
	s_add_i32 s2, s1, 0x18180
	v_sub_f32_e32 v36, v36, v37
	v_exp_f32_e32 v36, v36
	v_sub_f32_e32 v33, v33, v37
	s_waitcnt lgkmcnt(0)
	v_pk_mul_f32 v[2:3], v[20:21], v[6:7]
	v_sub_f32_e32 v7, v13, v37
	v_add_f32_e32 v2, v2, v15
	v_add_f32_e32 v8, v2, v3
	ds_read2st64_b64 v[2:5], v31 offset0:112 offset1:120
	v_exp_f32_e32 v25, v7
	v_pk_fma_f32 v[18:19], v[20:21], v[22:23], v[18:19] op_sel_hi:[0,1,1]
	v_mov_b32_e32 v20, v21
	s_waitcnt lgkmcnt(0)
	v_pk_add_f32 v[26:27], v[2:3], v[4:5]
	v_sub_f32_e32 v2, v12, v37
	v_exp_f32_e32 v24, v2
	v_mov_b32_e32 v2, s2
	s_add_i32 s2, s1, 0x181a0
	v_mov_b32_e32 v7, s2
	ds_read_b32 v6, v2
	ds_read2st64_b64 v[2:5], v17 offset0:64 offset1:72
	ds_read_b32 v7, v7
	s_add_i32 s2, s1, 0x181c0
	v_mov_b32_e32 v10, s2
	s_add_i32 s2, s1, 0x180e0
	v_mov_b32_e32 v15, s2
	s_waitcnt lgkmcnt(0)
	v_pk_mul_f32 v[6:7], v[6:7], v[24:25]
	s_add_i32 s1, s1, 0x181e0
	v_add_f32_e32 v6, v8, v6
	v_add_f32_e32 v16, v6, v7
	ds_read2st64_b64 v[6:9], v17 offset0:80 offset1:88
	ds_read_b32 v14, v10
	ds_read2st64_b64 v[10:13], v17 offset0:96 offset1:104
	ds_read_b32 v15, v15
	s_add_u32 s2, s13, s18
	s_addc_u32 s3, s14, 0
	v_lshl_add_u64 v[44:45], s[2:3], 0, v[38:39]
	s_lshl_b32 s6, s19, 1
	s_waitcnt lgkmcnt(0)
	v_sub_f32_e32 v15, v15, v37
	v_exp_f32_e32 v29, v15
	v_mov_b32_e32 v15, s1
	ds_read_b32 v15, v15
	s_mov_b32 s1, s7
	v_pk_fma_f32 v[18:19], v[20:21], v[26:27], v[18:19] op_sel_hi:[0,1,1]
	v_pk_add_f32 v[2:3], v[2:3], v[4:5]
	v_pk_add_f32 v[4:5], v[6:7], v[8:9]
	s_waitcnt lgkmcnt(0)
	v_pk_mul_f32 v[14:15], v[14:15], v[28:29]
	v_pk_fma_f32 v[2:3], v[24:25], v[2:3], v[18:19] op_sel_hi:[0,1,1]
	v_add_f32_e32 v14, v16, v14
	v_add_f32_e32 v34, v14, v15
	v_add_f32_e32 v38, v30, v34
	v_add_f32_e32 v40, v32, v38
	v_lshl_add_u64 v[38:39], v[44:45], 0, s[6:7]
	s_lshl_b32 s6, s21, 1
	v_lshl_add_u64 v[34:35], v[44:45], 0, s[0:1]
	v_add_f32_e32 v46, v36, v40
	v_lshl_add_u64 v[40:41], v[44:45], 0, s[6:7]
	global_load_dword v35, v[34:35], off
	s_lshl_b32 s6, s16, 1
	global_load_dword v39, v[38:39], off
	v_lshl_add_u64 v[44:45], v[44:45], 0, s[6:7]
	global_load_dword v40, v[40:41], off
	ds_read2st64_b64 v[14:17], v17 offset0:112 offset1:120
	global_load_dword v37, v[44:45], off
	v_mov_b32_e32 v6, v25
	v_pk_fma_f32 v[2:3], v[6:7], v[4:5], v[2:3] op_sel_hi:[0,1,1]
	v_pk_add_f32 v[4:5], v[10:11], v[12:13]
	v_mov_b32_e32 v6, v29
	v_pk_fma_f32 v[2:3], v[28:29], v[4:5], v[2:3] op_sel_hi:[0,1,1]
	s_waitcnt lgkmcnt(0)
	v_pk_add_f32 v[4:5], v[14:15], v[16:17]
	s_cmp_gt_i32 s8, 3
	v_pk_fma_f32 v[2:3], v[6:7], v[4:5], v[2:3] op_sel_hi:[0,1,1]
	s_waitcnt vmcnt(3)
	v_lshlrev_b32_e32 v34, 16, v35
	v_and_b32_e32 v35, 0xffff0000, v35
	s_waitcnt vmcnt(2)
	v_lshlrev_b32_e32 v38, 16, v39
	v_and_b32_e32 v39, 0xffff0000, v39
	s_waitcnt vmcnt(1)
	v_lshlrev_b32_e32 v42, 16, v40
	v_and_b32_e32 v43, 0xffff0000, v40
	v_exp_f32_e32 v40, v33
	s_waitcnt vmcnt(0)
	v_lshlrev_b32_e32 v44, 16, v37
	v_and_b32_e32 v45, 0xffff0000, v37
	v_pk_fma_f32 v[2:3], v[30:31], v[34:35], v[2:3] op_sel_hi:[0,1,1]
	v_add_f32_e32 v33, v40, v46
	v_div_scale_f32 v37, s[0:1], v33, v33, 1.0
	v_rcp_f32_e32 v41, v37
	v_pk_fma_f32 v[2:3], v[32:33], v[38:39], v[2:3] op_sel_hi:[0,1,1]
	v_fma_f32 v46, -v37, v41, 1.0
	v_fmac_f32_e32 v41, v46, v41
	v_div_scale_f32 v46, vcc, 1.0, v33, 1.0
	v_mul_f32_e32 v47, v46, v41
	v_fma_f32 v48, -v37, v47, v46
	v_fmac_f32_e32 v47, v48, v41
	v_fma_f32 v37, -v37, v47, v46
	v_div_fmas_f32 v37, v37, v41, v47
	v_pk_fma_f32 v[2:3], v[36:37], v[42:43], v[2:3] op_sel_hi:[0,1,1]
	v_div_fixup_f32 v46, v37, v33, 1.0
	v_pk_fma_f32 v[2:3], v[40:41], v[44:45], v[2:3] op_sel_hi:[0,1,1]
	s_nop 0
	v_pk_mul_f32 v[4:5], v[46:47], v[2:3] op_sel_hi:[0,1]
	v_add_u32_e32 v2, 0x18400, v31
	ds_write_b64 v2, v[4:5]
	s_waitcnt lgkmcnt(0)
	s_barrier
; #define LAS __attribute__((address_space(3)))
; __device__ __forceinline__ void sattn_unit(const bf16* Qb, const bf16* Kb, const bf16* Vb, const float* ck, const float* cv, const int* pt, bf16* MIX, const float* sg, float lam,
;                                            int s, int h, int c0, LAS unsigned char* lds, int tid_in) {
;     ...
;     if (w < 4) { const f32x2 a = *(const LAS f32x2*)(fin + w * 128 + 2 * lane), b = *(const LAS f32x2*)(fin + (4 + w) * 128 + 2 * lane);
;         const float v0 = a[0] - lam * b[0], v1 = a[1] - lam * b[1]; const float ss = wave_sum(v0 * v0 + v1 * v1);
;         const float rinv = (1.f - LAM0) / sqrtf(ss * (1.f / VD) + EPS);
;         *(unsigned*)(MIX + (size_t)(MP + 4 * s + w) * 1024 + 512 + h * 128 + 2 * lane) = pk2(v0 * rinv * sg[2 * lane], v1 * rinv * sg[2 * lane + 1]); }
; __global__ void __launch_bounds__(512, 2) mk_fwd(Args a) {
;     ...
;         const float smax2 = __builtin_bit_cast(float, __builtin_amdgcn_readfirstlane(__builtin_bit_cast(int, 8.f * wave_max(fabsf(INF(I_QG)[lane])) * wave_max(fabsf(INF(I_KG)[lane])) * LOG2E)));
;         __syncthreads();
; #pragma unroll 1
;         for (int c0_ = bid; c0_ < 256; c0_ += G) {
;             const int c = (G == 256) ? (c0_ & 7) * 32 + (c0_ >> 3) : c0_;
;             const int grp = c >> 4, j = c & 15, b = grp >> 2, map = (grp >> 1) & 1, vh = grp & 1;
;             bf16x8 qrx[4];
; #pragma unroll
;             for (int d = 0; d < 4; ++d) qrx[d] = bf16x8{};
; #pragma unroll 1
;             for (int i = 0; i < 4; ++i) { const int h = 3 - i, qb = (i & 1) ? 15 - j : j;
;                 const float a2 = __builtin_bit_cast(float, __builtin_amdgcn_readfirstlane(__builtin_bit_cast(int, exp2f(-2.f * (float)(h + 1)) * LOG2E)));
;                 const int W = (int)fminf((2.f * smax2 + 36.f) / a2 + 1.f, 1.0e6f); int t0 = (qb * 256 - W) >> 6; t0 = (t0 < 0 ? 0 : t0) & ~1;
;                 t0 = __builtin_amdgcn_readfirstlane(t0);
;                 const size_t qoff = (size_t)(h * 128 + map * 64) * 2, voff = (size_t)(h * 128 + vh * 64) * 2;
;                 const int hn = i < 3 ? 2 - i : 0, qbn = (i & 1) ? j : 15 - j;
;                 const float a2n = exp2f(-2.f * (float)(hn + 1)) * LOG2E; const int Wn = (int)fminf((2.f * smax2 + 36.f) / a2n + 1.f, 1.0e6f); int t0n = (qbn * 256 - Wn) >> 6; t0n = (t0n < 0 ? 0 : t0n) & ~1;
;                 t0n = __builtin_amdgcn_readfirstlane(t0n);
	s_cbranch_scc1 .LBB0_481
	v_readlane_b32 s52, v254, 26
	v_lshlrev_b32_e32 v3, 2, v130
	v_readlane_b32 s60, v254, 34
	v_readlane_b32 s61, v254, 35
	v_mov_b32_e32 v8, v131
	v_mov_b32_e32 v9, v131
	s_mov_b32 s2, 0xf800000
	s_add_i32 s0, s8, s20
	s_ashr_i32 s1, s0, 31
	global_load_dwordx2 v[6:7], v3, s[60:61]
	ds_read2st64_b64 v[2:5], v2 offset1:4
	s_lshl_b64 s[0:1], s[0:1], 11
	s_add_u32 s0, s94, s0
	s_addc_u32 s1, s95, s1
	v_lshlrev_b32_e32 v130, 1, v130
	s_waitcnt lgkmcnt(0)
	v_pk_fma_f32 v[2:3], v[132:133], v[4:5], v[2:3] neg_lo:[1,0,0] neg_hi:[1,0,0]
	v_readlane_b32 s53, v254, 27
	v_pk_mul_f32 v[4:5], v[2:3], v[2:3]
	v_readlane_b32 s54, v254, 28
	v_add_f32_e32 v4, v4, v5
	v_readlane_b32 s55, v254, 29
	v_readlane_b32 s56, v254, 30
	v_add_f32_dpp v4, v4, v4 row_shr:1 row_mask:0xf bank_mask:0xf bound_ctrl:1
	v_readlane_b32 s57, v254, 31
	v_readlane_b32 s58, v254, 32
	v_add_f32_dpp v4, v4, v4 row_shr:2 row_mask:0xf bank_mask:0xf bound_ctrl:1
	v_readlane_b32 s59, v254, 33
	v_readlane_b32 s62, v254, 36
	v_add_f32_dpp v4, v4, v4 row_shr:4 row_mask:0xf bank_mask:0xf bound_ctrl:1
	v_readlane_b32 s63, v254, 37
	v_readlane_b32 s64, v254, 38
	v_add_f32_dpp v4, v4, v4 row_shr:8 row_mask:0xf bank_mask:0xf bound_ctrl:1
	v_readlane_b32 s65, v254, 39
	v_readlane_b32 s66, v254, 40
	v_mov_b32_dpp v8, v4 row_bcast:15 row_mask:0xa bank_mask:0xf
	v_add_f32_e32 v4, v4, v8
	v_readlane_b32 s67, v254, 41
	s_nop 0
	v_mov_b32_dpp v9, v4 row_bcast:31 row_mask:0xc bank_mask:0xf
	v_add_f32_e32 v4, v4, v9
	s_nop 0
	v_readlane_b32 s3, v4, 63
	s_nop 1
	v_fma_f32 v4, s3, v149, v135
	v_mul_f32_e32 v5, 0x4f800000, v4
	v_cmp_gt_f32_e32 vcc, s2, v4
	s_add_u32 s2, s0, s18
	s_addc_u32 s3, s1, 0
	v_cndmask_b32_e32 v4, v4, v5, vcc
	v_sqrt_f32_e32 v5, v4
	s_nop 0
	v_add_u32_e32 v8, -1, v5
	v_add_u32_e32 v9, 1, v5
	v_fma_f32 v10, -v8, v5, v4
	v_fma_f32 v11, -v9, v5, v4
	v_cmp_ge_f32_e64 s[0:1], 0, v10
	s_nop 1
	v_cndmask_b32_e64 v5, v5, v8, s[0:1]
	v_cmp_lt_f32_e64 s[0:1], 0, v11
	s_nop 1
	v_cndmask_b32_e64 v5, v5, v9, s[0:1]
	v_mul_f32_e32 v8, 0x37800000, v5
	v_cndmask_b32_e32 v5, v5, v8, vcc
	v_cmp_class_f32_e32 vcc, v4, v139
	s_nop 1
	v_cndmask_b32_e32 v8, v5, v4, vcc
	v_div_scale_f32 v9, s[0:1], v8, v8, s10
	v_rcp_f32_e32 v10, v9
	v_div_scale_f32 v11, vcc, s10, v8, s10
	v_lshl_add_u64 v[4:5], s[2:3], 0, v[130:131]
	v_fma_f32 v12, -v9, v10, 1.0
	v_fmac_f32_e32 v10, v12, v10
	v_mul_f32_e32 v12, v11, v10
	v_fma_f32 v13, -v9, v12, v11
	v_fmac_f32_e32 v12, v13, v10
	v_fma_f32 v9, -v9, v12, v11
	v_div_fmas_f32 v9, v9, v10, v12
	v_div_fixup_f32 v8, v9, v8, s10
	v_pk_mul_f32 v[2:3], v[2:3], v[8:9] op_sel_hi:[1,0]
	v_add_co_u32_e32 v4, vcc, 0xcf00000, v4
	s_waitcnt vmcnt(0)
	v_pk_mul_f32 v[2:3], v[6:7], v[2:3]
	v_addc_co_u32_e32 v5, vcc, 0, v5, vcc
	v_cvt_pk_bf16_f32 v2, v2, v3
	global_store_dword v[4:5], v2, off offset:1024
	s_branch .LBB0_481
.LBB0_507:
	v_readlane_b32 s0, v255, 50
	s_cmp_lg_u32 s0, 0
	s_cbranch_scc1 .Lp2_tail
	v_readlane_b32 s0, v255, 51
	v_lshlrev_b32_e32 v174, 2, v252
	v_mov_b32_e32 v175, 0
	v_mov_b32_e32 v2, s0
	s_nop 0
	v_fmaak_f32 v182, 2.0, v2, 0x42100000
	s_branch .Lp2_attn

; __device__ __forceinline__ u32x4 pack8(const f32x4 a, const f32x4 b) { u32x4 w; w.x = cvt_pk_bf16(a[0], a[1]); w.y = cvt_pk_bf16(a[2], a[3]); w.z = cvt_pk_bf16(b[0], b[1]); w.w = cvt_pk_bf16(b[2], b[3]); return w; }
; __device__ __forceinline__ f32x4 ld4bf(const bf16* p) { const u32x2 w = *(const u32x2*)p; return (f32x4){bflo(w.x), bfhi(w.x), bflo(w.y), bfhi(w.y)}; }
; #define EP_ROWS(...) _Pragma("unroll") for (int ai = 0; ai < 2; ++ai) _Pragma("unroll") for (int m = 0; m < 4; ++m) { const int r = row0 + 128 * ai + 16 * m; __VA_ARGS__ }
; __device__ __forceinline__ float sigm(float x) { return 1.f / (1.f + __builtin_amdgcn_exp2f(-LOG2E * x)); }
;     __device__ __forceinline__ void operator()(const f32x4 (&acc)[2][2][4][2], const Unit& u, int wr, int wc, int fr, int fq) const {
;         const int row0 = u.pm * 256 + wr * 64 + fr, c0 = u.pn * 256 + 64 * wc + 8 * fq;
;         EP_ROWS(
; _Pragma("unroll")
;             for (int bj = 0; bj < 2; ++bj) { const int c = c0 + 32 * bj; const f32x4 g0 = ld4bf(Gb + (size_t)r * 512 + c), g1 = ld4bf(Gb + (size_t)r * 512 + c + 4);
;                 f32x4 v0, v1;
; _Pragma("unroll")
;                 for (int j = 0; j < 4; ++j) { v0[j] = g0[j] * sigm(acc[ai][bj][m][0][j]); v1[j] = g1[j] * sigm(acc[ai][bj][m][1][j]); }
;                 *(u32x4*)(MIX + (size_t)r * 1024 + c) = pack8(v0, v1); } )
;     }
.LBB0_602:
	v_lshl_add_u32 v152, s0, 8, v155
	v_lshl_or_b32 v130, s1, 8, v157
	v_ashrrev_i32_e32 v153, 31, v152
	v_lshlrev_b64 v[132:133], 10, v[152:153]
	v_ashrrev_i32_e32 v131, 31, v130
	v_lshl_add_u64 v[132:133], s[14:15], 0, v[132:133]
	v_lshlrev_b64 v[150:151], 1, v[130:131]
	v_lshl_add_u64 v[162:163], v[132:133], 0, v[150:151]
	global_load_dwordx4 v[130:133], v[162:163], off
	v_mul_f32_e32 v126, 0xbfb8aa3b, v126
	v_mul_f32_e32 v161, 0xbfb8aa3b, v122
	v_mul_f32_e32 v127, 0xbfb8aa3b, v127
	v_mul_f32_e32 v164, 0xbfb8aa3b, v123
	v_exp_f32_e32 v122, v126
	v_exp_f32_e32 v126, v161
	v_exp_f32_e32 v123, v127
	v_exp_f32_e32 v127, v164
	v_mul_f32_e32 v128, 0xbfb8aa3b, v128
	v_mul_f32_e32 v129, 0xbfb8aa3b, v129
	v_exp_f32_e32 v164, v128
	v_exp_f32_e32 v165, v129
	v_pk_add_f32 v[168:169], v[126:127], 1.0 op_sel_hi:[1,0]
	global_load_dwordx4 v[126:129], v[162:163], off offset:64
	v_pk_add_f32 v[122:123], v[122:123], 1.0 op_sel_hi:[1,0]
	v_lshlrev_b64 v[166:167], 11, v[152:153]
	v_div_scale_f32 v162, s[0:1], v122, v122, 1.0
	v_div_scale_f32 v170, s[4:5], v169, v169, 1.0
	v_rcp_f32_e32 v175, v162
	v_div_scale_f32 v172, s[6:7], v168, v168, 1.0
	v_rcp_f32_e32 v176, v170
	v_rcp_f32_e32 v177, v172
	v_fma_f32 v179, -v162, v175, 1.0
	v_div_scale_f32 v163, s[0:1], 1.0, v122, 1.0
	v_fma_f32 v180, -v170, v176, 1.0
	v_fmac_f32_e32 v175, v179, v175
	v_div_scale_f32 v171, s[4:5], 1.0, v169, 1.0
	v_fma_f32 v181, -v172, v177, 1.0
	v_fmac_f32_e32 v176, v180, v176
	v_mul_f32_e32 v179, v163, v175
	v_div_scale_f32 v173, s[6:7], 1.0, v168, 1.0
	v_fmac_f32_e32 v177, v181, v177
	v_mul_f32_e32 v180, v171, v176
	v_fma_f32 v183, -v162, v179, v163
	v_mul_f32_e32 v181, v173, v177
	v_fma_f32 v184, -v170, v180, v171
	v_fmac_f32_e32 v179, v183, v175
	v_fma_f32 v185, -v172, v181, v173
	v_fmac_f32_e32 v180, v184, v176
	v_fma_f32 v161, -v162, v179, v163
	s_mov_b64 vcc, s[0:1]
	v_fmac_f32_e32 v181, v185, v177
	v_fma_f32 v162, -v170, v180, v171
	v_rcp_f32_e32 v123, v123
	v_div_fmas_f32 v153, v161, v175, v179
	s_mov_b64 vcc, s[4:5]
	v_fma_f32 v170, -v172, v181, v173
	v_div_fixup_f32 v122, v153, v122, 1.0
	v_div_fmas_f32 v153, v162, v176, v180
	s_mov_b64 vcc, s[6:7]
	v_pk_add_f32 v[164:165], v[164:165], 1.0 op_sel_hi:[1,0]
	v_div_fixup_f32 v163, v153, v169, 1.0
	v_div_fmas_f32 v153, v170, v177, v181
	v_div_fixup_f32 v162, v153, v168, 1.0
	v_mul_f32_e32 v124, 0xbfb8aa3b, v124
	v_mul_f32_e32 v125, 0xbfb8aa3b, v125
	v_exp_f32_e32 v124, v124
	v_exp_f32_e32 v125, v125
	v_mul_f32_e32 v118, 0xbfb8aa3b, v118
	v_mul_f32_e32 v119, 0xbfb8aa3b, v119
	v_exp_f32_e32 v118, v118
	s_waitcnt vmcnt(0)
	v_lshlrev_b32_e32 v170, 16, v132
	v_and_b32_e32 v171, 0xffff0000, v132
	v_lshlrev_b32_e32 v168, 16, v130
	v_and_b32_e32 v169, 0xffff0000, v130
	v_pk_mul_f32 v[122:123], v[122:123], v[168:169]
	v_rcp_f32_e32 v165, v165
	v_pk_add_f32 v[124:125], v[124:125], 1.0 op_sel_hi:[1,0]
	v_rcp_f32_e32 v164, v164
	v_lshlrev_b32_e32 v130, 16, v131
	v_and_b32_e32 v131, 0xffff0000, v131
	v_pk_mul_f32 v[164:165], v[164:165], v[130:131]
	v_lshlrev_b32_e32 v130, 16, v133
	v_and_b32_e32 v131, 0xffff0000, v133
	v_rcp_f32_e32 v125, v125
	v_exp_f32_e32 v119, v119
	v_rcp_f32_e32 v124, v124
	v_pk_mul_f32 v[162:163], v[162:163], v[170:171]
	v_pk_mul_f32 v[124:125], v[124:125], v[130:131]
	v_cvt_pk_bf16_f32 v130, v122, v123
	v_lshl_add_u64 v[122:123], s[16:17], 0, v[166:167]
	v_cvt_pk_bf16_f32 v131, v164, v165
	v_cvt_pk_bf16_f32 v132, v162, v163
	v_cvt_pk_bf16_f32 v133, v124, v125
	v_lshl_add_u64 v[122:123], v[122:123], 0, v[150:151]
	v_pk_add_f32 v[118:119], v[118:119], 1.0 op_sel_hi:[1,0]
	global_store_dwordx4 v[122:123], v[130:133], off
	v_lshlrev_b32_e32 v124, 16, v126
	v_and_b32_e32 v125, 0xffff0000, v126
	v_mul_f32_e32 v114, 0xbfb8aa3b, v114
	v_mul_f32_e32 v115, 0xbfb8aa3b, v115
	v_exp_f32_e32 v114, v114
	v_rcp_f32_e32 v119, v119
	v_exp_f32_e32 v115, v115
	s_nop 0
	v_pk_add_f32 v[114:115], v[114:115], 1.0 op_sel_hi:[1,0]
	v_rcp_f32_e32 v118, v118
	s_nop 0
	v_pk_mul_f32 v[124:125], v[118:119], v[124:125]
	v_lshlrev_b32_e32 v118, 16, v128
	v_and_b32_e32 v119, 0xffff0000, v128
	v_rcp_f32_e32 v115, v115
	v_mul_f32_e32 v120, 0xbfb8aa3b, v120
	v_mul_f32_e32 v121, 0xbfb8aa3b, v121
	v_or_b32_e32 v162, 16, v152
	v_rcp_f32_e32 v114, v114
	v_exp_f32_e32 v120, v120
	v_exp_f32_e32 v121, v121
	v_ashrrev_i32_e32 v163, 31, v162
	v_pk_mul_f32 v[130:131], v[114:115], v[118:119]
	v_lshlrev_b64 v[118:119], 10, v[162:163]
	v_lshl_add_u64 v[118:119], s[14:15], 0, v[118:119]
	v_lshl_add_u64 v[164:165], v[118:119], 0, v[150:151]
	v_pk_add_f32 v[132:133], v[120:121], 1.0 op_sel_hi:[1,0]
	global_load_dwordx4 v[118:121], v[164:165], off
	v_mul_f32_e32 v114, 0xbfb8aa3b, v116
	v_exp_f32_e32 v114, v114
	v_lshlrev_b32_e32 v126, 16, v127
	v_and_b32_e32 v127, 0xffff0000, v127
	v_rcp_f32_e32 v133, v133
	v_mul_f32_e32 v110, 0xbfb8aa3b, v110
	v_mul_f32_e32 v115, 0xbfb8aa3b, v117
	v_exp_f32_e32 v115, v115
	v_rcp_f32_e32 v132, v132
	s_nop 0
	v_pk_mul_f32 v[116:117], v[132:133], v[126:127]
	v_pk_add_f32 v[114:115], v[114:115], 1.0 op_sel_hi:[1,0]
	v_lshlrev_b32_e32 v126, 16, v129
	v_and_b32_e32 v127, 0xffff0000, v129
	v_mul_f32_e32 v106, 0xbfb8aa3b, v106
	v_mul_f32_e32 v107, 0xbfb8aa3b, v107
	v_rcp_f32_e32 v115, v115
	v_exp_f32_e32 v106, v106
	v_rcp_f32_e32 v114, v114
	s_nop 0
	v_pk_mul_f32 v[126:127], v[114:115], v[126:127]
	v_cvt_pk_bf16_f32 v114, v124, v125
	v_cvt_pk_bf16_f32 v115, v116, v117
	v_cvt_pk_bf16_f32 v116, v130, v131
	v_cvt_pk_bf16_f32 v117, v126, v127
	global_store_dwordx4 v[122:123], v[114:117], off offset:64
	v_exp_f32_e32 v107, v107
	v_mul_f32_e32 v112, 0xbfb8aa3b, v112
	v_exp_f32_e32 v114, v110
	v_mul_f32_e32 v110, 0xbfb8aa3b, v111
	v_exp_f32_e32 v115, v110
	v_pk_add_f32 v[106:107], v[106:107], 1.0 op_sel_hi:[1,0]
	v_mul_f32_e32 v113, 0xbfb8aa3b, v113
	v_exp_f32_e32 v112, v112
	v_pk_add_f32 v[122:123], v[114:115], 1.0 op_sel_hi:[1,0]
	global_load_dwordx4 v[114:117], v[164:165], off offset:64
	s_waitcnt vmcnt(2)
; __device__ __forceinline__ u32x4 pack8(const f32x4 a, const f32x4 b) { u32x4 w; w.x = cvt_pk_bf16(a[0], a[1]); w.y = cvt_pk_bf16(a[2], a[3]); w.z = cvt_pk_bf16(b[0], b[1]); w.w = cvt_pk_bf16(b[2], b[3]); return w; }
; __device__ __forceinline__ f32x4 ld4bf(const bf16* p) { const u32x2 w = *(const u32x2*)p; return (f32x4){bflo(w.x), bfhi(w.x), bflo(w.y), bfhi(w.y)}; }
; #define EP_ROWS(...) _Pragma("unroll") for (int ai = 0; ai < 2; ++ai) _Pragma("unroll") for (int m = 0; m < 4; ++m) { const int r = row0 + 128 * ai + 16 * m; __VA_ARGS__ }
; __device__ __forceinline__ float sigm(float x) { return 1.f / (1.f + __builtin_amdgcn_exp2f(-LOG2E * x)); }
;     __device__ __forceinline__ void operator()(const f32x4 (&acc)[2][2][4][2], const Unit& u, int wr, int wc, int fr, int fq) const {
;         const int row0 = u.pm * 256 + wr * 64 + fr, c0 = u.pn * 256 + 64 * wc + 8 * fq;
;         EP_ROWS(
; _Pragma("unroll")
;             for (int bj = 0; bj < 2; ++bj) { const int c = c0 + 32 * bj; const f32x4 g0 = ld4bf(Gb + (size_t)r * 512 + c), g1 = ld4bf(Gb + (size_t)r * 512 + c + 4);
;                 f32x4 v0, v1;
; _Pragma("unroll")
;                 for (int j = 0; j < 4; ++j) { v0[j] = g0[j] * sigm(acc[ai][bj][m][0][j]); v1[j] = g1[j] * sigm(acc[ai][bj][m][1][j]); }
;                 *(u32x4*)(MIX + (size_t)r * 1024 + c) = pack8(v0, v1); } )
;     }
	v_lshlrev_b32_e32 v124, 16, v118
	v_and_b32_e32 v125, 0xffff0000, v118
	v_exp_f32_e32 v113, v113
	v_rcp_f32_e32 v123, v123
	v_pk_add_f32 v[112:113], v[112:113], 1.0 op_sel_hi:[1,0]
	v_rcp_f32_e32 v122, v122
	s_nop 0
	v_pk_mul_f32 v[122:123], v[122:123], v[124:125]
	v_lshlrev_b32_e32 v124, 16, v120
	v_and_b32_e32 v125, 0xffff0000, v120
	v_rcp_f32_e32 v107, v107
	v_mul_f32_e32 v108, 0xbfb8aa3b, v108
	v_rcp_f32_e32 v106, v106
	s_nop 0
	v_pk_mul_f32 v[106:107], v[106:107], v[124:125]
	v_mul_f32_e32 v109, 0xbfb8aa3b, v109
	v_exp_f32_e32 v108, v108
	v_exp_f32_e32 v109, v109
	v_rcp_f32_e32 v113, v113
	v_pk_add_f32 v[108:109], v[108:109], 1.0 op_sel_hi:[1,0]
	v_rcp_f32_e32 v112, v112
	v_lshlrev_b32_e32 v118, 16, v119
	v_and_b32_e32 v119, 0xffff0000, v119
	v_pk_mul_f32 v[112:113], v[112:113], v[118:119]
	v_lshlrev_b32_e32 v118, 16, v121
	v_and_b32_e32 v119, 0xffff0000, v121
	v_rcp_f32_e32 v109, v109
	v_mul_f32_e32 v102, 0xbfb8aa3b, v102
	v_mul_f32_e32 v103, 0xbfb8aa3b, v103
	v_exp_f32_e32 v102, v102
	v_exp_f32_e32 v103, v103
	v_lshlrev_b64 v[110:111], 11, v[162:163]
	v_pk_add_f32 v[102:103], v[102:103], 1.0 op_sel_hi:[1,0]
	v_rcp_f32_e32 v108, v108
	v_cvt_pk_bf16_f32 v120, v106, v107
	v_lshl_add_u64 v[106:107], s[16:17], 0, v[110:111]
	v_pk_mul_f32 v[108:109], v[108:109], v[118:119]
	v_cvt_pk_bf16_f32 v119, v112, v113
	v_cvt_pk_bf16_f32 v121, v108, v109
	s_waitcnt vmcnt(0)
	v_lshlrev_b32_e32 v108, 16, v114
	v_and_b32_e32 v109, 0xffff0000, v114
	v_rcp_f32_e32 v103, v103
	v_mul_f32_e32 v98, 0xbfb8aa3b, v98
	v_mul_f32_e32 v99, 0xbfb8aa3b, v99
	v_exp_f32_e32 v98, v98
	v_exp_f32_e32 v99, v99
	s_nop 0
	v_pk_add_f32 v[98:99], v[98:99], 1.0 op_sel_hi:[1,0]
	v_rcp_f32_e32 v102, v102
	v_cvt_pk_bf16_f32 v118, v122, v123
	v_lshl_add_u64 v[106:107], v[106:107], 0, v[150:151]
	global_store_dwordx4 v[106:107], v[118:121], off
	v_rcp_f32_e32 v99, v99
	v_mul_f32_e32 v104, 0xbfb8aa3b, v104
	v_mul_f32_e32 v105, 0xbfb8aa3b, v105
	v_or_b32_e32 v118, 32, v152
	v_pk_mul_f32 v[108:109], v[102:103], v[108:109]
	v_lshlrev_b32_e32 v102, 16, v116
	v_and_b32_e32 v103, 0xffff0000, v116
	v_rcp_f32_e32 v98, v98
	v_exp_f32_e32 v104, v104
	v_exp_f32_e32 v105, v105
	v_ashrrev_i32_e32 v119, 31, v118
	v_pk_mul_f32 v[110:111], v[98:99], v[102:103]
	v_lshlrev_b64 v[102:103], 10, v[118:119]
	v_lshl_add_u64 v[102:103], s[14:15], 0, v[102:103]
	v_lshl_add_u64 v[120:121], v[102:103], 0, v[150:151]
	v_pk_add_f32 v[112:113], v[104:105], 1.0 op_sel_hi:[1,0]
	global_load_dwordx4 v[102:105], v[120:121], off
	v_mul_f32_e32 v98, 0xbfb8aa3b, v100
	v_exp_f32_e32 v98, v98
	v_lshlrev_b32_e32 v114, 16, v115
	v_and_b32_e32 v115, 0xffff0000, v115
	v_rcp_f32_e32 v113, v113
	v_mul_f32_e32 v94, 0xbfb8aa3b, v94
	v_mul_f32_e32 v99, 0xbfb8aa3b, v101
	v_exp_f32_e32 v99, v99
	v_rcp_f32_e32 v112, v112
	s_nop 0
	v_pk_mul_f32 v[100:101], v[112:113], v[114:115]
	v_pk_add_f32 v[98:99], v[98:99], 1.0 op_sel_hi:[1,0]
	v_lshlrev_b32_e32 v112, 16, v117
	v_and_b32_e32 v113, 0xffff0000, v117
	v_mul_f32_e32 v90, 0xbfb8aa3b, v90
	v_mul_f32_e32 v91, 0xbfb8aa3b, v91
	v_rcp_f32_e32 v99, v99
	v_exp_f32_e32 v90, v90
	v_rcp_f32_e32 v98, v98
	s_nop 0
	v_pk_mul_f32 v[112:113], v[98:99], v[112:113]
	v_cvt_pk_bf16_f32 v98, v108, v109
	v_cvt_pk_bf16_f32 v99, v100, v101
	v_cvt_pk_bf16_f32 v100, v110, v111
	v_cvt_pk_bf16_f32 v101, v112, v113
	global_store_dwordx4 v[106:107], v[98:101], off offset:64
	v_exp_f32_e32 v91, v91
	v_mul_f32_e32 v96, 0xbfb8aa3b, v96
	v_exp_f32_e32 v98, v94
	v_mul_f32_e32 v94, 0xbfb8aa3b, v95
	v_exp_f32_e32 v99, v94
	v_pk_add_f32 v[90:91], v[90:91], 1.0 op_sel_hi:[1,0]
	v_mul_f32_e32 v97, 0xbfb8aa3b, v97
	v_exp_f32_e32 v96, v96
	v_pk_add_f32 v[106:107], v[98:99], 1.0 op_sel_hi:[1,0]
	global_load_dwordx4 v[98:101], v[120:121], off offset:64
	s_waitcnt vmcnt(2)
	v_lshlrev_b32_e32 v108, 16, v102
	v_and_b32_e32 v109, 0xffff0000, v102
	v_exp_f32_e32 v97, v97
	v_rcp_f32_e32 v107, v107
	v_pk_add_f32 v[96:97], v[96:97], 1.0 op_sel_hi:[1,0]
	v_rcp_f32_e32 v106, v106
	s_nop 0
	v_pk_mul_f32 v[106:107], v[106:107], v[108:109]
	v_lshlrev_b32_e32 v108, 16, v104
	v_and_b32_e32 v109, 0xffff0000, v104
	v_rcp_f32_e32 v91, v91
	v_mul_f32_e32 v92, 0xbfb8aa3b, v92
	v_rcp_f32_e32 v90, v90
	s_nop 0
	v_pk_mul_f32 v[90:91], v[90:91], v[108:109]
	v_mul_f32_e32 v93, 0xbfb8aa3b, v93
	v_exp_f32_e32 v92, v92
	v_exp_f32_e32 v93, v93
	v_rcp_f32_e32 v97, v97
	v_pk_add_f32 v[92:93], v[92:93], 1.0 op_sel_hi:[1,0]
	v_rcp_f32_e32 v96, v96
	v_lshlrev_b32_e32 v102, 16, v103
	v_and_b32_e32 v103, 0xffff0000, v103
	v_pk_mul_f32 v[96:97], v[96:97], v[102:103]
	v_lshlrev_b32_e32 v102, 16, v105
	v_and_b32_e32 v103, 0xffff0000, v105
	v_rcp_f32_e32 v93, v93
	v_mul_f32_e32 v86, 0xbfb8aa3b, v86
	v_mul_f32_e32 v87, 0xbfb8aa3b, v87
	v_exp_f32_e32 v86, v86
	v_exp_f32_e32 v87, v87
	v_lshlrev_b64 v[94:95], 11, v[118:119]
	v_pk_add_f32 v[86:87], v[86:87], 1.0 op_sel_hi:[1,0]
	v_rcp_f32_e32 v92, v92
	v_cvt_pk_bf16_f32 v104, v90, v91
	v_lshl_add_u64 v[90:91], s[16:17], 0, v[94:95]
	v_pk_mul_f32 v[92:93], v[92:93], v[102:103]
	v_cvt_pk_bf16_f32 v103, v96, v97
	v_cvt_pk_bf16_f32 v105, v92, v93
	s_waitcnt vmcnt(0)
; __device__ __forceinline__ u32x4 pack8(const f32x4 a, const f32x4 b) { u32x4 w; w.x = cvt_pk_bf16(a[0], a[1]); w.y = cvt_pk_bf16(a[2], a[3]); w.z = cvt_pk_bf16(b[0], b[1]); w.w = cvt_pk_bf16(b[2], b[3]); return w; }
; #define EP_ROWS(...) _Pragma("unroll") for (int ai = 0; ai < 2; ++ai) _Pragma("unroll") for (int m = 0; m < 4; ++m) { const int r = row0 + 128 * ai + 16 * m; __VA_ARGS__ }
; __device__ __forceinline__ float sigm(float x) { return 1.f / (1.f + __builtin_amdgcn_exp2f(-LOG2E * x)); }
; __device__ __forceinline__ f32x4 ld4bf(const bf16* p) { const u32x2 w = *(const u32x2*)p; return (f32x4){bflo(w.x), bfhi(w.x), bflo(w.y), bfhi(w.y)}; }
;     __device__ __forceinline__ void operator()(const f32x4 (&acc)[2][2][4][2], const Unit& u, int wr, int wc, int fr, int fq) const {
;         const int row0 = u.pm * 256 + wr * 64 + fr, c0 = u.pn * 256 + 64 * wc + 8 * fq;
;         EP_ROWS(
; _Pragma("unroll")
;             for (int bj = 0; bj < 2; ++bj) { const int c = c0 + 32 * bj; const f32x4 g0 = ld4bf(Gb + (size_t)r * 512 + c), g1 = ld4bf(Gb + (size_t)r * 512 + c + 4);
;                 f32x4 v0, v1;
; _Pragma("unroll")
;                 for (int j = 0; j < 4; ++j) { v0[j] = g0[j] * sigm(acc[ai][bj][m][0][j]); v1[j] = g1[j] * sigm(acc[ai][bj][m][1][j]); }
;                 *(u32x4*)(MIX + (size_t)r * 1024 + c) = pack8(v0, v1); } )
;     }
	v_lshlrev_b32_e32 v92, 16, v98
	v_and_b32_e32 v93, 0xffff0000, v98
	v_rcp_f32_e32 v87, v87
	v_mul_f32_e32 v82, 0xbfb8aa3b, v82
	v_mul_f32_e32 v83, 0xbfb8aa3b, v83
	v_exp_f32_e32 v82, v82
	v_exp_f32_e32 v83, v83
	s_nop 0
	v_pk_add_f32 v[82:83], v[82:83], 1.0 op_sel_hi:[1,0]
	v_rcp_f32_e32 v86, v86
	v_cvt_pk_bf16_f32 v102, v106, v107
	v_lshl_add_u64 v[90:91], v[90:91], 0, v[150:151]
	global_store_dwordx4 v[90:91], v[102:105], off
	v_rcp_f32_e32 v83, v83
	v_mul_f32_e32 v88, 0xbfb8aa3b, v88
	v_mul_f32_e32 v89, 0xbfb8aa3b, v89
	v_or_b32_e32 v102, 48, v152
	v_pk_mul_f32 v[92:93], v[86:87], v[92:93]
	v_lshlrev_b32_e32 v86, 16, v100
	v_and_b32_e32 v87, 0xffff0000, v100
	v_rcp_f32_e32 v82, v82
	v_exp_f32_e32 v88, v88
	v_exp_f32_e32 v89, v89
	v_ashrrev_i32_e32 v103, 31, v102
	v_pk_mul_f32 v[94:95], v[82:83], v[86:87]
	v_lshlrev_b64 v[86:87], 10, v[102:103]
	v_lshl_add_u64 v[86:87], s[14:15], 0, v[86:87]
	v_lshl_add_u64 v[104:105], v[86:87], 0, v[150:151]
	v_pk_add_f32 v[96:97], v[88:89], 1.0 op_sel_hi:[1,0]
	global_load_dwordx4 v[86:89], v[104:105], off
	v_mul_f32_e32 v82, 0xbfb8aa3b, v84
	v_exp_f32_e32 v82, v82
	v_lshlrev_b32_e32 v98, 16, v99
	v_and_b32_e32 v99, 0xffff0000, v99
	v_rcp_f32_e32 v97, v97
	v_mul_f32_e32 v78, 0xbfb8aa3b, v78
	v_mul_f32_e32 v83, 0xbfb8aa3b, v85
	v_exp_f32_e32 v83, v83
	v_rcp_f32_e32 v96, v96
	s_nop 0
	v_pk_mul_f32 v[84:85], v[96:97], v[98:99]
	v_pk_add_f32 v[82:83], v[82:83], 1.0 op_sel_hi:[1,0]
	v_lshlrev_b32_e32 v96, 16, v101
	v_and_b32_e32 v97, 0xffff0000, v101
	v_mul_f32_e32 v74, 0xbfb8aa3b, v74
	v_mul_f32_e32 v75, 0xbfb8aa3b, v75
	v_rcp_f32_e32 v83, v83
	v_exp_f32_e32 v74, v74
	v_rcp_f32_e32 v82, v82
	s_nop 0
	v_pk_mul_f32 v[96:97], v[82:83], v[96:97]
	v_cvt_pk_bf16_f32 v82, v92, v93
	v_cvt_pk_bf16_f32 v83, v84, v85
	v_cvt_pk_bf16_f32 v84, v94, v95
	v_cvt_pk_bf16_f32 v85, v96, v97
	global_store_dwordx4 v[90:91], v[82:85], off offset:64
	v_exp_f32_e32 v75, v75
	v_mul_f32_e32 v80, 0xbfb8aa3b, v80
	v_exp_f32_e32 v82, v78
	v_mul_f32_e32 v78, 0xbfb8aa3b, v79
	v_exp_f32_e32 v83, v78
	v_pk_add_f32 v[74:75], v[74:75], 1.0 op_sel_hi:[1,0]
	v_mul_f32_e32 v81, 0xbfb8aa3b, v81
	v_exp_f32_e32 v80, v80
	v_pk_add_f32 v[90:91], v[82:83], 1.0 op_sel_hi:[1,0]
	global_load_dwordx4 v[82:85], v[104:105], off offset:64
	s_waitcnt vmcnt(2)
	v_lshlrev_b32_e32 v92, 16, v86
	v_and_b32_e32 v93, 0xffff0000, v86
	v_exp_f32_e32 v81, v81
	v_rcp_f32_e32 v91, v91
	v_pk_add_f32 v[80:81], v[80:81], 1.0 op_sel_hi:[1,0]
	v_rcp_f32_e32 v90, v90
	s_nop 0
	v_pk_mul_f32 v[90:91], v[90:91], v[92:93]
	v_lshlrev_b32_e32 v92, 16, v88
	v_and_b32_e32 v93, 0xffff0000, v88
	v_rcp_f32_e32 v75, v75
	v_mul_f32_e32 v76, 0xbfb8aa3b, v76
	v_rcp_f32_e32 v74, v74
	s_nop 0
	v_pk_mul_f32 v[74:75], v[74:75], v[92:93]
	v_mul_f32_e32 v77, 0xbfb8aa3b, v77
	v_exp_f32_e32 v76, v76
	v_exp_f32_e32 v77, v77
	v_rcp_f32_e32 v81, v81
	v_pk_add_f32 v[76:77], v[76:77], 1.0 op_sel_hi:[1,0]
	v_rcp_f32_e32 v80, v80
	v_lshlrev_b32_e32 v86, 16, v87
	v_and_b32_e32 v87, 0xffff0000, v87
	v_pk_mul_f32 v[80:81], v[80:81], v[86:87]
	v_lshlrev_b32_e32 v86, 16, v89
	v_and_b32_e32 v87, 0xffff0000, v89
	v_rcp_f32_e32 v77, v77
	v_mul_f32_e32 v70, 0xbfb8aa3b, v70
	v_mul_f32_e32 v71, 0xbfb8aa3b, v71
	v_exp_f32_e32 v70, v70
	v_exp_f32_e32 v71, v71
	v_lshlrev_b64 v[78:79], 11, v[102:103]
	v_pk_add_f32 v[70:71], v[70:71], 1.0 op_sel_hi:[1,0]
	v_rcp_f32_e32 v76, v76
	v_cvt_pk_bf16_f32 v88, v74, v75
	v_lshl_add_u64 v[74:75], s[16:17], 0, v[78:79]
	v_pk_mul_f32 v[76:77], v[76:77], v[86:87]
	v_cvt_pk_bf16_f32 v87, v80, v81
	v_cvt_pk_bf16_f32 v89, v76, v77
	s_waitcnt vmcnt(0)
	v_lshlrev_b32_e32 v76, 16, v82
	v_and_b32_e32 v77, 0xffff0000, v82
	v_rcp_f32_e32 v71, v71
	v_mul_f32_e32 v66, 0xbfb8aa3b, v66
	v_mul_f32_e32 v67, 0xbfb8aa3b, v67
	v_exp_f32_e32 v66, v66
	v_exp_f32_e32 v67, v67
	s_nop 0
	v_pk_add_f32 v[66:67], v[66:67], 1.0 op_sel_hi:[1,0]
	v_rcp_f32_e32 v70, v70
	v_cvt_pk_bf16_f32 v86, v90, v91
	v_lshl_add_u64 v[74:75], v[74:75], 0, v[150:151]
	global_store_dwordx4 v[74:75], v[86:89], off
	v_rcp_f32_e32 v67, v67
	v_mul_f32_e32 v72, 0xbfb8aa3b, v72
	v_mul_f32_e32 v73, 0xbfb8aa3b, v73
	v_add_u32_e32 v86, 0x80, v152
	v_pk_mul_f32 v[76:77], v[70:71], v[76:77]
	v_lshlrev_b32_e32 v70, 16, v84
	v_and_b32_e32 v71, 0xffff0000, v84
	v_rcp_f32_e32 v66, v66
	v_exp_f32_e32 v72, v72
	v_exp_f32_e32 v73, v73
	v_ashrrev_i32_e32 v87, 31, v86
	v_pk_mul_f32 v[78:79], v[66:67], v[70:71]
	v_lshlrev_b64 v[70:71], 10, v[86:87]
	v_lshl_add_u64 v[70:71], s[14:15], 0, v[70:71]
	v_lshl_add_u64 v[88:89], v[70:71], 0, v[150:151]
	v_pk_add_f32 v[80:81], v[72:73], 1.0 op_sel_hi:[1,0]
	global_load_dwordx4 v[70:73], v[88:89], off
	v_mul_f32_e32 v66, 0xbfb8aa3b, v68
	v_exp_f32_e32 v66, v66
	v_lshlrev_b32_e32 v82, 16, v83
	v_and_b32_e32 v83, 0xffff0000, v83
	v_rcp_f32_e32 v81, v81
	v_mul_f32_e32 v62, 0xbfb8aa3b, v62
	v_mul_f32_e32 v67, 0xbfb8aa3b, v69
	v_exp_f32_e32 v67, v67
	v_rcp_f32_e32 v80, v80
	s_nop 0
	v_pk_mul_f32 v[68:69], v[80:81], v[82:83]
	v_pk_add_f32 v[66:67], v[66:67], 1.0 op_sel_hi:[1,0]
	v_lshlrev_b32_e32 v80, 16, v85
	v_and_b32_e32 v81, 0xffff0000, v85
	v_mul_f32_e32 v58, 0xbfb8aa3b, v58
	v_mul_f32_e32 v59, 0xbfb8aa3b, v59
	v_rcp_f32_e32 v67, v67
	v_exp_f32_e32 v58, v58
	v_rcp_f32_e32 v66, v66
	s_nop 0
	v_pk_mul_f32 v[80:81], v[66:67], v[80:81]
	v_cvt_pk_bf16_f32 v66, v76, v77
	v_cvt_pk_bf16_f32 v67, v68, v69
	v_cvt_pk_bf16_f32 v68, v78, v79
	v_cvt_pk_bf16_f32 v69, v80, v81
	global_store_dwordx4 v[74:75], v[66:69], off offset:64
	v_exp_f32_e32 v59, v59
	v_mul_f32_e32 v64, 0xbfb8aa3b, v64
	v_exp_f32_e32 v66, v62
	v_mul_f32_e32 v62, 0xbfb8aa3b, v63
	v_exp_f32_e32 v67, v62
	v_pk_add_f32 v[58:59], v[58:59], 1.0 op_sel_hi:[1,0]
	v_mul_f32_e32 v65, 0xbfb8aa3b, v65
	v_exp_f32_e32 v64, v64
	v_pk_add_f32 v[74:75], v[66:67], 1.0 op_sel_hi:[1,0]
	global_load_dwordx4 v[66:69], v[88:89], off offset:64
	s_waitcnt vmcnt(2)
; __device__ __forceinline__ u32x4 pack8(const f32x4 a, const f32x4 b) { u32x4 w; w.x = cvt_pk_bf16(a[0], a[1]); w.y = cvt_pk_bf16(a[2], a[3]); w.z = cvt_pk_bf16(b[0], b[1]); w.w = cvt_pk_bf16(b[2], b[3]); return w; }
; #define EP_ROWS(...) _Pragma("unroll") for (int ai = 0; ai < 2; ++ai) _Pragma("unroll") for (int m = 0; m < 4; ++m) { const int r = row0 + 128 * ai + 16 * m; __VA_ARGS__ }
; __device__ __forceinline__ float sigm(float x) { return 1.f / (1.f + __builtin_amdgcn_exp2f(-LOG2E * x)); }
; __device__ __forceinline__ f32x4 ld4bf(const bf16* p) { const u32x2 w = *(const u32x2*)p; return (f32x4){bflo(w.x), bfhi(w.x), bflo(w.y), bfhi(w.y)}; }
;     __device__ __forceinline__ void operator()(const f32x4 (&acc)[2][2][4][2], const Unit& u, int wr, int wc, int fr, int fq) const {
;         const int row0 = u.pm * 256 + wr * 64 + fr, c0 = u.pn * 256 + 64 * wc + 8 * fq;
;         EP_ROWS(
; _Pragma("unroll")
;             for (int bj = 0; bj < 2; ++bj) { const int c = c0 + 32 * bj; const f32x4 g0 = ld4bf(Gb + (size_t)r * 512 + c), g1 = ld4bf(Gb + (size_t)r * 512 + c + 4);
;                 f32x4 v0, v1;
; _Pragma("unroll")
;                 for (int j = 0; j < 4; ++j) { v0[j] = g0[j] * sigm(acc[ai][bj][m][0][j]); v1[j] = g1[j] * sigm(acc[ai][bj][m][1][j]); }
;                 *(u32x4*)(MIX + (size_t)r * 1024 + c) = pack8(v0, v1); } )
;     }
	v_lshlrev_b32_e32 v76, 16, v70
	v_and_b32_e32 v77, 0xffff0000, v70
	v_exp_f32_e32 v65, v65
	v_rcp_f32_e32 v75, v75
	v_pk_add_f32 v[64:65], v[64:65], 1.0 op_sel_hi:[1,0]
	v_rcp_f32_e32 v74, v74
	s_nop 0
	v_pk_mul_f32 v[74:75], v[74:75], v[76:77]
	v_lshlrev_b32_e32 v76, 16, v72
	v_and_b32_e32 v77, 0xffff0000, v72
	v_rcp_f32_e32 v59, v59
	v_mul_f32_e32 v60, 0xbfb8aa3b, v60
	v_rcp_f32_e32 v58, v58
	s_nop 0
	v_pk_mul_f32 v[58:59], v[58:59], v[76:77]
	v_mul_f32_e32 v61, 0xbfb8aa3b, v61
	v_exp_f32_e32 v60, v60
	v_exp_f32_e32 v61, v61
	v_rcp_f32_e32 v65, v65
	v_pk_add_f32 v[60:61], v[60:61], 1.0 op_sel_hi:[1,0]
	v_rcp_f32_e32 v64, v64
	v_lshlrev_b32_e32 v70, 16, v71
	v_and_b32_e32 v71, 0xffff0000, v71
	v_pk_mul_f32 v[64:65], v[64:65], v[70:71]
	v_lshlrev_b32_e32 v70, 16, v73
	v_and_b32_e32 v71, 0xffff0000, v73
	v_rcp_f32_e32 v61, v61
	v_mul_f32_e32 v54, 0xbfb8aa3b, v54
	v_mul_f32_e32 v55, 0xbfb8aa3b, v55
	v_exp_f32_e32 v54, v54
	v_exp_f32_e32 v55, v55
	v_lshlrev_b64 v[62:63], 11, v[86:87]
	v_pk_add_f32 v[54:55], v[54:55], 1.0 op_sel_hi:[1,0]
	v_rcp_f32_e32 v60, v60
	v_cvt_pk_bf16_f32 v72, v58, v59
	v_lshl_add_u64 v[58:59], s[16:17], 0, v[62:63]
	v_pk_mul_f32 v[60:61], v[60:61], v[70:71]
	v_cvt_pk_bf16_f32 v71, v64, v65
	v_cvt_pk_bf16_f32 v73, v60, v61
	s_waitcnt vmcnt(0)
	v_lshlrev_b32_e32 v60, 16, v66
	v_and_b32_e32 v61, 0xffff0000, v66
	v_rcp_f32_e32 v55, v55
	v_mul_f32_e32 v50, 0xbfb8aa3b, v50
	v_mul_f32_e32 v51, 0xbfb8aa3b, v51
	v_exp_f32_e32 v50, v50
	v_exp_f32_e32 v51, v51
	s_nop 0
	v_pk_add_f32 v[50:51], v[50:51], 1.0 op_sel_hi:[1,0]
	v_rcp_f32_e32 v54, v54
	v_cvt_pk_bf16_f32 v70, v74, v75
	v_lshl_add_u64 v[58:59], v[58:59], 0, v[150:151]
	global_store_dwordx4 v[58:59], v[70:73], off
	v_rcp_f32_e32 v51, v51
	v_mul_f32_e32 v56, 0xbfb8aa3b, v56
	v_mul_f32_e32 v57, 0xbfb8aa3b, v57
	v_add_u32_e32 v70, 0x90, v152
	v_pk_mul_f32 v[60:61], v[54:55], v[60:61]
	v_lshlrev_b32_e32 v54, 16, v68
	v_and_b32_e32 v55, 0xffff0000, v68
	v_rcp_f32_e32 v50, v50
	v_exp_f32_e32 v56, v56
	v_exp_f32_e32 v57, v57
	v_ashrrev_i32_e32 v71, 31, v70
	v_pk_mul_f32 v[62:63], v[50:51], v[54:55]
	v_lshlrev_b64 v[54:55], 10, v[70:71]
	v_lshl_add_u64 v[54:55], s[14:15], 0, v[54:55]
	v_lshl_add_u64 v[72:73], v[54:55], 0, v[150:151]
	v_pk_add_f32 v[64:65], v[56:57], 1.0 op_sel_hi:[1,0]
	global_load_dwordx4 v[54:57], v[72:73], off
	v_mul_f32_e32 v50, 0xbfb8aa3b, v52
	v_exp_f32_e32 v50, v50
	v_lshlrev_b32_e32 v66, 16, v67
	v_and_b32_e32 v67, 0xffff0000, v67
	v_rcp_f32_e32 v65, v65
	v_mul_f32_e32 v46, 0xbfb8aa3b, v46
	v_mul_f32_e32 v51, 0xbfb8aa3b, v53
	v_exp_f32_e32 v51, v51
	v_rcp_f32_e32 v64, v64
	s_nop 0
	v_pk_mul_f32 v[52:53], v[64:65], v[66:67]
	v_pk_add_f32 v[50:51], v[50:51], 1.0 op_sel_hi:[1,0]
	v_lshlrev_b32_e32 v64, 16, v69
	v_and_b32_e32 v65, 0xffff0000, v69
	v_mul_f32_e32 v42, 0xbfb8aa3b, v42
	v_mul_f32_e32 v43, 0xbfb8aa3b, v43
	v_rcp_f32_e32 v51, v51
	v_exp_f32_e32 v42, v42
	v_rcp_f32_e32 v50, v50
	s_nop 0
	v_pk_mul_f32 v[64:65], v[50:51], v[64:65]
	v_cvt_pk_bf16_f32 v50, v60, v61
	v_cvt_pk_bf16_f32 v51, v52, v53
	v_cvt_pk_bf16_f32 v52, v62, v63
	v_cvt_pk_bf16_f32 v53, v64, v65
	global_store_dwordx4 v[58:59], v[50:53], off offset:64
	v_exp_f32_e32 v43, v43
	v_mul_f32_e32 v48, 0xbfb8aa3b, v48
	v_exp_f32_e32 v50, v46
	v_mul_f32_e32 v46, 0xbfb8aa3b, v47
	v_exp_f32_e32 v51, v46
	v_pk_add_f32 v[42:43], v[42:43], 1.0 op_sel_hi:[1,0]
	v_mul_f32_e32 v49, 0xbfb8aa3b, v49
	v_exp_f32_e32 v48, v48
	v_pk_add_f32 v[58:59], v[50:51], 1.0 op_sel_hi:[1,0]
	global_load_dwordx4 v[50:53], v[72:73], off offset:64
	s_waitcnt vmcnt(2)
	v_lshlrev_b32_e32 v60, 16, v54
	v_and_b32_e32 v61, 0xffff0000, v54
	v_exp_f32_e32 v49, v49
	v_rcp_f32_e32 v59, v59
	v_pk_add_f32 v[48:49], v[48:49], 1.0 op_sel_hi:[1,0]
	v_rcp_f32_e32 v58, v58
	s_nop 0
	v_pk_mul_f32 v[58:59], v[58:59], v[60:61]
	v_lshlrev_b32_e32 v60, 16, v56
	v_and_b32_e32 v61, 0xffff0000, v56
	v_rcp_f32_e32 v43, v43
	v_mul_f32_e32 v44, 0xbfb8aa3b, v44
	v_rcp_f32_e32 v42, v42
	s_nop 0
	v_pk_mul_f32 v[42:43], v[42:43], v[60:61]
	v_mul_f32_e32 v45, 0xbfb8aa3b, v45
	v_exp_f32_e32 v44, v44
	v_exp_f32_e32 v45, v45
	v_rcp_f32_e32 v49, v49
	v_pk_add_f32 v[44:45], v[44:45], 1.0 op_sel_hi:[1,0]
	v_rcp_f32_e32 v48, v48
	v_lshlrev_b32_e32 v54, 16, v55
	v_and_b32_e32 v55, 0xffff0000, v55
	v_pk_mul_f32 v[48:49], v[48:49], v[54:55]
	v_lshlrev_b32_e32 v54, 16, v57
	v_and_b32_e32 v55, 0xffff0000, v57
	v_rcp_f32_e32 v45, v45
	v_mul_f32_e32 v38, 0xbfb8aa3b, v38
	v_mul_f32_e32 v39, 0xbfb8aa3b, v39
	v_exp_f32_e32 v38, v38
	v_exp_f32_e32 v39, v39
	v_lshlrev_b64 v[46:47], 11, v[70:71]
	v_pk_add_f32 v[38:39], v[38:39], 1.0 op_sel_hi:[1,0]
	v_rcp_f32_e32 v44, v44
	v_cvt_pk_bf16_f32 v56, v42, v43
	v_lshl_add_u64 v[42:43], s[16:17], 0, v[46:47]
	v_pk_mul_f32 v[44:45], v[44:45], v[54:55]
	v_cvt_pk_bf16_f32 v55, v48, v49
	v_cvt_pk_bf16_f32 v57, v44, v45
	s_waitcnt vmcnt(0)
; __device__ __forceinline__ u32x4 pack8(const f32x4 a, const f32x4 b) { u32x4 w; w.x = cvt_pk_bf16(a[0], a[1]); w.y = cvt_pk_bf16(a[2], a[3]); w.z = cvt_pk_bf16(b[0], b[1]); w.w = cvt_pk_bf16(b[2], b[3]); return w; }
; #define EP_ROWS(...) _Pragma("unroll") for (int ai = 0; ai < 2; ++ai) _Pragma("unroll") for (int m = 0; m < 4; ++m) { const int r = row0 + 128 * ai + 16 * m; __VA_ARGS__ }
; __device__ __forceinline__ float sigm(float x) { return 1.f / (1.f + __builtin_amdgcn_exp2f(-LOG2E * x)); }
; __device__ __forceinline__ f32x4 ld4bf(const bf16* p) { const u32x2 w = *(const u32x2*)p; return (f32x4){bflo(w.x), bfhi(w.x), bflo(w.y), bfhi(w.y)}; }
;     __device__ __forceinline__ void operator()(const f32x4 (&acc)[2][2][4][2], const Unit& u, int wr, int wc, int fr, int fq) const {
;         const int row0 = u.pm * 256 + wr * 64 + fr, c0 = u.pn * 256 + 64 * wc + 8 * fq;
;         EP_ROWS(
; _Pragma("unroll")
;             for (int bj = 0; bj < 2; ++bj) { const int c = c0 + 32 * bj; const f32x4 g0 = ld4bf(Gb + (size_t)r * 512 + c), g1 = ld4bf(Gb + (size_t)r * 512 + c + 4);
;                 f32x4 v0, v1;
; _Pragma("unroll")
;                 for (int j = 0; j < 4; ++j) { v0[j] = g0[j] * sigm(acc[ai][bj][m][0][j]); v1[j] = g1[j] * sigm(acc[ai][bj][m][1][j]); }
;                 *(u32x4*)(MIX + (size_t)r * 1024 + c) = pack8(v0, v1); } )
;     }
	v_lshlrev_b32_e32 v44, 16, v50
	v_and_b32_e32 v45, 0xffff0000, v50
	v_rcp_f32_e32 v39, v39
	v_mul_f32_e32 v34, 0xbfb8aa3b, v34
	v_mul_f32_e32 v35, 0xbfb8aa3b, v35
	v_exp_f32_e32 v34, v34
	v_exp_f32_e32 v35, v35
	s_nop 0
	v_pk_add_f32 v[34:35], v[34:35], 1.0 op_sel_hi:[1,0]
	v_rcp_f32_e32 v38, v38
	v_cvt_pk_bf16_f32 v54, v58, v59
	v_lshl_add_u64 v[42:43], v[42:43], 0, v[150:151]
	global_store_dwordx4 v[42:43], v[54:57], off
	v_rcp_f32_e32 v35, v35
	v_mul_f32_e32 v40, 0xbfb8aa3b, v40
	v_mul_f32_e32 v41, 0xbfb8aa3b, v41
	v_add_u32_e32 v54, 0xa0, v152
	v_pk_mul_f32 v[44:45], v[38:39], v[44:45]
	v_lshlrev_b32_e32 v38, 16, v52
	v_and_b32_e32 v39, 0xffff0000, v52
	v_rcp_f32_e32 v34, v34
	v_exp_f32_e32 v40, v40
	v_exp_f32_e32 v41, v41
	v_ashrrev_i32_e32 v55, 31, v54
	v_pk_mul_f32 v[46:47], v[34:35], v[38:39]
	v_lshlrev_b64 v[38:39], 10, v[54:55]
	v_lshl_add_u64 v[38:39], s[14:15], 0, v[38:39]
	v_lshl_add_u64 v[56:57], v[38:39], 0, v[150:151]
	v_pk_add_f32 v[48:49], v[40:41], 1.0 op_sel_hi:[1,0]
	global_load_dwordx4 v[38:41], v[56:57], off
	v_mul_f32_e32 v34, 0xbfb8aa3b, v36
	v_exp_f32_e32 v34, v34
	v_lshlrev_b32_e32 v50, 16, v51
	v_and_b32_e32 v51, 0xffff0000, v51
	v_rcp_f32_e32 v49, v49
	v_mul_f32_e32 v30, 0xbfb8aa3b, v30
	v_mul_f32_e32 v35, 0xbfb8aa3b, v37
	v_exp_f32_e32 v35, v35
	v_rcp_f32_e32 v48, v48
	s_nop 0
	v_pk_mul_f32 v[36:37], v[48:49], v[50:51]
	v_pk_add_f32 v[34:35], v[34:35], 1.0 op_sel_hi:[1,0]
	v_lshlrev_b32_e32 v48, 16, v53
	v_and_b32_e32 v49, 0xffff0000, v53
	v_mul_f32_e32 v26, 0xbfb8aa3b, v26
	v_mul_f32_e32 v27, 0xbfb8aa3b, v27
	v_rcp_f32_e32 v35, v35
	v_exp_f32_e32 v26, v26
	v_rcp_f32_e32 v34, v34
	s_nop 0
	v_pk_mul_f32 v[48:49], v[34:35], v[48:49]
	v_cvt_pk_bf16_f32 v34, v44, v45
	v_cvt_pk_bf16_f32 v35, v36, v37
	v_cvt_pk_bf16_f32 v36, v46, v47
	v_cvt_pk_bf16_f32 v37, v48, v49
	global_store_dwordx4 v[42:43], v[34:37], off offset:64
	v_exp_f32_e32 v27, v27
	v_mul_f32_e32 v32, 0xbfb8aa3b, v32
	v_exp_f32_e32 v34, v30
	v_mul_f32_e32 v30, 0xbfb8aa3b, v31
	v_exp_f32_e32 v35, v30
	v_pk_add_f32 v[26:27], v[26:27], 1.0 op_sel_hi:[1,0]
	v_mul_f32_e32 v33, 0xbfb8aa3b, v33
	v_exp_f32_e32 v32, v32
	v_pk_add_f32 v[42:43], v[34:35], 1.0 op_sel_hi:[1,0]
	global_load_dwordx4 v[34:37], v[56:57], off offset:64
	s_waitcnt vmcnt(2)
	v_lshlrev_b32_e32 v44, 16, v38
	v_and_b32_e32 v45, 0xffff0000, v38
	v_exp_f32_e32 v33, v33
	v_rcp_f32_e32 v43, v43
	v_pk_add_f32 v[32:33], v[32:33], 1.0 op_sel_hi:[1,0]
	v_rcp_f32_e32 v42, v42
	s_nop 0
	v_pk_mul_f32 v[42:43], v[42:43], v[44:45]
	v_lshlrev_b32_e32 v44, 16, v40
	v_and_b32_e32 v45, 0xffff0000, v40
	v_rcp_f32_e32 v27, v27
	v_mul_f32_e32 v28, 0xbfb8aa3b, v28
	v_rcp_f32_e32 v26, v26
	s_nop 0
	v_pk_mul_f32 v[26:27], v[26:27], v[44:45]
	v_mul_f32_e32 v29, 0xbfb8aa3b, v29
	v_exp_f32_e32 v28, v28
	v_exp_f32_e32 v29, v29
	v_rcp_f32_e32 v33, v33
	v_pk_add_f32 v[28:29], v[28:29], 1.0 op_sel_hi:[1,0]
	v_rcp_f32_e32 v32, v32
	v_lshlrev_b32_e32 v38, 16, v39
	v_and_b32_e32 v39, 0xffff0000, v39
	v_pk_mul_f32 v[32:33], v[32:33], v[38:39]
	v_lshlrev_b32_e32 v38, 16, v41
	v_and_b32_e32 v39, 0xffff0000, v41
	v_rcp_f32_e32 v29, v29
	v_mul_f32_e32 v22, 0xbfb8aa3b, v22
	v_mul_f32_e32 v23, 0xbfb8aa3b, v23
	v_exp_f32_e32 v22, v22
	v_exp_f32_e32 v23, v23
	v_lshlrev_b64 v[30:31], 11, v[54:55]
	v_pk_add_f32 v[22:23], v[22:23], 1.0 op_sel_hi:[1,0]
	v_rcp_f32_e32 v28, v28
	v_cvt_pk_bf16_f32 v40, v26, v27
	v_lshl_add_u64 v[26:27], s[16:17], 0, v[30:31]
	v_pk_mul_f32 v[28:29], v[28:29], v[38:39]
	v_cvt_pk_bf16_f32 v39, v32, v33
	v_cvt_pk_bf16_f32 v41, v28, v29
	s_waitcnt vmcnt(0)
; #define PG8_BAR __builtin_amdgcn_s_barrier()
; __device__ __forceinline__ u32x4 pack8(const f32x4 a, const f32x4 b) { u32x4 w; w.x = cvt_pk_bf16(a[0], a[1]); w.y = cvt_pk_bf16(a[2], a[3]); w.z = cvt_pk_bf16(b[0], b[1]); w.w = cvt_pk_bf16(b[2], b[3]); return w; }
; #define EP_ROWS(...) _Pragma("unroll") for (int ai = 0; ai < 2; ++ai) _Pragma("unroll") for (int m = 0; m < 4; ++m) { const int r = row0 + 128 * ai + 16 * m; __VA_ARGS__ }
; template <class Epi, class Sched, bool ALIGN_EPI = false, bool SP2 = false>
; __device__ __forceinline__ void gemm_phase(PG8_LAS unsigned char* lds, const Gemm g, const Sched& S, const Epi& E) {
;     ...
;         if constexpr (ALIGN_EPI) { if (wr == 0) PG8_BAR; }
;         if constexpr (!Epi::AFTER_DRAIN) { E(acc, cur, wr, wc, fr, fq); S.done(cur); }
;         if (!has_next) break;
; #pragma unroll
;         for (int a = 0; a < 2; ++a)
; #pragma unroll
;             for (int b = 0; b < 2; ++b)
; #pragma unroll
;                 for (int m = 0; m < 4; ++m)
; #pragma unroll
;                     for (int n = 0; n < 2; ++n) acc[a][b][m][n] = (f32x4){0.f, 0.f, 0.f, 0.f};
;         cur = nxt; cA = nA; cB = nB; ++ui;
;         if constexpr (ALIGN_EPI) { if (wr == 1) PG8_BAR; }
;     }
; __device__ __forceinline__ float sigm(float x) { return 1.f / (1.f + __builtin_amdgcn_exp2f(-LOG2E * x)); }
; __device__ __forceinline__ f32x4 ld4bf(const bf16* p) { const u32x2 w = *(const u32x2*)p; return (f32x4){bflo(w.x), bfhi(w.x), bflo(w.y), bfhi(w.y)}; }
;     __device__ __forceinline__ void operator()(const f32x4 (&acc)[2][2][4][2], const Unit& u, int wr, int wc, int fr, int fq) const {
;         const int row0 = u.pm * 256 + wr * 64 + fr, c0 = u.pn * 256 + 64 * wc + 8 * fq;
;         EP_ROWS(
; _Pragma("unroll")
;             for (int bj = 0; bj < 2; ++bj) { const int c = c0 + 32 * bj; const f32x4 g0 = ld4bf(Gb + (size_t)r * 512 + c), g1 = ld4bf(Gb + (size_t)r * 512 + c + 4);
;                 f32x4 v0, v1;
; _Pragma("unroll")
;                 for (int j = 0; j < 4; ++j) { v0[j] = g0[j] * sigm(acc[ai][bj][m][0][j]); v1[j] = g1[j] * sigm(acc[ai][bj][m][1][j]); }
;                 *(u32x4*)(MIX + (size_t)r * 1024 + c) = pack8(v0, v1); } )
;     }
	v_lshlrev_b32_e32 v28, 16, v34
	v_and_b32_e32 v29, 0xffff0000, v34
	v_rcp_f32_e32 v23, v23
	v_mul_f32_e32 v18, 0xbfb8aa3b, v18
	v_mul_f32_e32 v19, 0xbfb8aa3b, v19
	v_exp_f32_e32 v18, v18
	v_exp_f32_e32 v19, v19
	s_nop 0
	v_pk_add_f32 v[18:19], v[18:19], 1.0 op_sel_hi:[1,0]
	v_rcp_f32_e32 v22, v22
	v_cvt_pk_bf16_f32 v38, v42, v43
	v_lshl_add_u64 v[26:27], v[26:27], 0, v[150:151]
	global_store_dwordx4 v[26:27], v[38:41], off
	v_rcp_f32_e32 v19, v19
	v_mul_f32_e32 v24, 0xbfb8aa3b, v24
	v_mul_f32_e32 v25, 0xbfb8aa3b, v25
	v_add_u32_e32 v38, 0xb0, v152
	v_pk_mul_f32 v[28:29], v[22:23], v[28:29]
	v_lshlrev_b32_e32 v22, 16, v36
	v_and_b32_e32 v23, 0xffff0000, v36
	v_rcp_f32_e32 v18, v18
	v_exp_f32_e32 v24, v24
	v_exp_f32_e32 v25, v25
	v_ashrrev_i32_e32 v39, 31, v38
	v_pk_mul_f32 v[30:31], v[18:19], v[22:23]
	v_lshlrev_b64 v[22:23], 10, v[38:39]
	v_lshl_add_u64 v[22:23], s[14:15], 0, v[22:23]
	v_lshl_add_u64 v[40:41], v[22:23], 0, v[150:151]
	v_pk_add_f32 v[32:33], v[24:25], 1.0 op_sel_hi:[1,0]
	global_load_dwordx4 v[22:25], v[40:41], off
	v_mul_f32_e32 v18, 0xbfb8aa3b, v20
	v_exp_f32_e32 v18, v18
	v_lshlrev_b32_e32 v34, 16, v35
	v_and_b32_e32 v35, 0xffff0000, v35
	v_rcp_f32_e32 v33, v33
	v_mul_f32_e32 v14, 0xbfb8aa3b, v14
	v_mul_f32_e32 v19, 0xbfb8aa3b, v21
	v_exp_f32_e32 v19, v19
	v_rcp_f32_e32 v32, v32
	s_nop 0
	v_pk_mul_f32 v[20:21], v[32:33], v[34:35]
	v_pk_add_f32 v[18:19], v[18:19], 1.0 op_sel_hi:[1,0]
	v_lshlrev_b32_e32 v32, 16, v37
	v_and_b32_e32 v33, 0xffff0000, v37
	v_mul_f32_e32 v10, 0xbfb8aa3b, v10
	v_mul_f32_e32 v11, 0xbfb8aa3b, v11
	v_rcp_f32_e32 v19, v19
	v_exp_f32_e32 v10, v10
	v_rcp_f32_e32 v18, v18
	s_nop 0
	v_pk_mul_f32 v[32:33], v[18:19], v[32:33]
	v_cvt_pk_bf16_f32 v18, v28, v29
	v_cvt_pk_bf16_f32 v19, v20, v21
	v_cvt_pk_bf16_f32 v20, v30, v31
	v_cvt_pk_bf16_f32 v21, v32, v33
	global_store_dwordx4 v[26:27], v[18:21], off offset:64
	v_exp_f32_e32 v11, v11
	v_mul_f32_e32 v16, 0xbfb8aa3b, v16
	v_exp_f32_e32 v18, v14
	v_mul_f32_e32 v14, 0xbfb8aa3b, v15
	v_exp_f32_e32 v19, v14
	v_pk_add_f32 v[10:11], v[10:11], 1.0 op_sel_hi:[1,0]
	v_mul_f32_e32 v17, 0xbfb8aa3b, v17
	v_exp_f32_e32 v16, v16
	v_pk_add_f32 v[26:27], v[18:19], 1.0 op_sel_hi:[1,0]
	global_load_dwordx4 v[18:21], v[40:41], off offset:64
	s_waitcnt vmcnt(2)
	v_lshlrev_b32_e32 v28, 16, v22
	v_and_b32_e32 v29, 0xffff0000, v22
	v_exp_f32_e32 v17, v17
	v_rcp_f32_e32 v27, v27
	v_mul_f32_e32 v12, 0xbfb8aa3b, v12
	v_rcp_f32_e32 v26, v26
	s_nop 0
	v_pk_mul_f32 v[26:27], v[26:27], v[28:29]
	v_lshlrev_b32_e32 v28, 16, v24
	v_and_b32_e32 v29, 0xffff0000, v24
	v_rcp_f32_e32 v11, v11
	v_mul_f32_e32 v13, 0xbfb8aa3b, v13
	v_rcp_f32_e32 v10, v10
	s_nop 0
	v_pk_mul_f32 v[28:29], v[10:11], v[28:29]
	v_pk_add_f32 v[10:11], v[16:17], 1.0 op_sel_hi:[1,0]
	v_lshlrev_b32_e32 v16, 16, v23
	v_and_b32_e32 v17, 0xffff0000, v23
	v_exp_f32_e32 v12, v12
	v_exp_f32_e32 v13, v13
	v_rcp_f32_e32 v11, v11
	v_pk_add_f32 v[12:13], v[12:13], 1.0 op_sel_hi:[1,0]
	v_rcp_f32_e32 v10, v10
	s_nop 0
	v_pk_mul_f32 v[16:17], v[10:11], v[16:17]
	v_lshlrev_b32_e32 v10, 16, v25
	v_and_b32_e32 v11, 0xffff0000, v25
	v_rcp_f32_e32 v13, v13
	v_mul_f32_e32 v6, 0xbfb8aa3b, v6
	v_mul_f32_e32 v7, 0xbfb8aa3b, v7
	v_exp_f32_e32 v6, v6
	v_exp_f32_e32 v7, v7
	v_lshlrev_b64 v[14:15], 11, v[38:39]
	v_rcp_f32_e32 v12, v12
	s_nop 0
	v_pk_mul_f32 v[22:23], v[12:13], v[10:11]
	v_lshl_add_u64 v[14:15], s[16:17], 0, v[14:15]
	v_cvt_pk_bf16_f32 v10, v26, v27
	v_cvt_pk_bf16_f32 v11, v16, v17
	v_cvt_pk_bf16_f32 v12, v28, v29
	v_cvt_pk_bf16_f32 v13, v22, v23
	v_lshl_add_u64 v[14:15], v[14:15], 0, v[150:151]
	v_pk_add_f32 v[6:7], v[6:7], 1.0 op_sel_hi:[1,0]
	global_store_dwordx4 v[14:15], v[10:13], off
	v_mul_f32_e32 v2, 0xbfb8aa3b, v2
	v_mul_f32_e32 v3, 0xbfb8aa3b, v3
	s_waitcnt vmcnt(1)
	v_lshlrev_b32_e32 v10, 16, v18
	v_and_b32_e32 v11, 0xffff0000, v18
	v_exp_f32_e32 v2, v2
	v_rcp_f32_e32 v7, v7
	v_exp_f32_e32 v3, v3
	s_nop 0
	v_pk_add_f32 v[2:3], v[2:3], 1.0 op_sel_hi:[1,0]
	v_rcp_f32_e32 v6, v6
	v_mul_f32_e32 v8, 0xbfb8aa3b, v8
	v_mul_f32_e32 v9, 0xbfb8aa3b, v9
	v_exp_f32_e32 v8, v8
	v_rcp_f32_e32 v3, v3
	v_exp_f32_e32 v9, v9
	v_pk_mul_f32 v[6:7], v[6:7], v[10:11]
	v_lshlrev_b32_e32 v10, 16, v20
	v_and_b32_e32 v11, 0xffff0000, v20
	v_rcp_f32_e32 v2, v2
	s_nop 0
	v_pk_mul_f32 v[10:11], v[2:3], v[10:11]
	v_pk_add_f32 v[2:3], v[8:9], 1.0 op_sel_hi:[1,0]
	v_mul_f32_e32 v4, 0xbfb8aa3b, v4
	v_mul_f32_e32 v5, 0xbfb8aa3b, v5
	v_exp_f32_e32 v4, v4
	v_exp_f32_e32 v5, v5
	v_rcp_f32_e32 v3, v3
	v_pk_add_f32 v[4:5], v[4:5], 1.0 op_sel_hi:[1,0]
	v_rcp_f32_e32 v2, v2
	v_lshlrev_b32_e32 v8, 16, v19
	v_and_b32_e32 v9, 0xffff0000, v19
	v_pk_mul_f32 v[8:9], v[2:3], v[8:9]
	v_rcp_f32_e32 v5, v5
	v_lshlrev_b32_e32 v2, 16, v21
	v_and_b32_e32 v3, 0xffff0000, v21
	v_rcp_f32_e32 v4, v4
	s_nop 0
	v_pk_mul_f32 v[12:13], v[4:5], v[2:3]
	v_cvt_pk_bf16_f32 v2, v6, v7
	v_cvt_pk_bf16_f32 v3, v8, v9
	v_cvt_pk_bf16_f32 v4, v10, v11
	v_cvt_pk_bf16_f32 v5, v12, v13
	s_andn2_b64 vcc, exec, s[2:3]
	s_mov_b64 s[0:1], -1
	global_store_dwordx4 v[14:15], v[2:5], off offset:64
	s_cbranch_vccnz .LBB0_591
	s_andn2_b64 vcc, exec, s[8:9]
	s_cbranch_vccnz .LBB0_590
	s_barrier
	s_branch .LBB0_590

; template <int NKS, bool ATILED = false, bool FFN = false, bool HALF = false, class EF> ...
;     ...
;     for (int pc = bid - first;; pc += ncu) {
;         if (qctr) { __syncthreads(); if (tid == 0) qslot[0] = (int)atomicAdd(qctr, 1u); __syncthreads(); pc = __builtin_amdgcn_readfirstlane(qslot[0]); }
;         if (pc >= npieces) break;
;         const int rb = pc / ncb, cb = pc - rb * ncb;
;         const bf16* a0 = ATILED ? A + (size_t)(MP + RB * rb + c16) * 64 : A + (size_t)(RB * rb + c16) * K + w * kw + 8 * kq;
;         const bf16* b0 = Wt + (size_t)((cb >> 2) * 256 + 32 * (cb & 3) + c16) * K + w * kw + 8 * kq;
;         f32x4 acc[MI][4];
; #pragma unroll
;         for (int mi = 0; mi < MI; ++mi)
; #pragma unroll
;             for (int ni = 0; ni < 4; ++ni) acc[mi][ni] = (f32x4){0.f, 0.f, 0.f, 0.f};
;         constexpr int SB = NS < 4 ? NS : 4;
; #pragma unroll 1
;         for (int s0 = 0; s0 < NS; s0 += SB) {
;             bf16x8 Af[SB][MI], Bf[SB][4];
; #pragma unroll
;             for (int j = 0; j < SB; ++j) if (s0 + j < NS) { const int s = s0 + j;
;                 if (ATILED) { const int kk = w * kw + 32 * s + 8 * kq; const bf16* at = a0 + (size_t)(kk >> 6) * MTOT * 64 + (kk & 63);
; #pragma unroll
;                     for (int mi = 0; mi < MI; ++mi) Af[j][mi] = *(const bf16x8*)(at + 16 * mi * 64); }
;                 else {
; #pragma unroll
;                     for (int mi = 0; mi < MI; ++mi) Af[j][mi] = *(const bf16x8*)(a0 + (size_t)(16 * mi) * K + 32 * s); }
; #pragma unroll
;                 for (int ni = 0; ni < 4; ++ni) Bf[j][ni] = *(const bf16x8*)(b0 + (size_t)(16 * (ni & 1) + 128 * (ni >> 1)) * K + 32 * s); }
;             asm volatile("s_waitcnt vmcnt(0)" ::: "memory");
; #pragma unroll
;             for (int j = 0; j < SB; ++j) if (s0 + j < NS) {
; #pragma unroll
;                 for (int mi = 0; mi < MI; ++mi)
; #pragma unroll
;                     for (int ni = 0; ni < 4; ++ni) acc[mi][ni] = __builtin_amdgcn_mfma_f32_16x16x32_bf16(Af[j][mi], Bf[j][ni], acc[mi][ni], 0, 0, 0); }
;         }
;         LAS float* part = lf + w * 4096;
; #pragma unroll
;         for (int mi = 0; mi < MI; ++mi)
; #pragma unroll
;             for (int ni = 0; ni < 4; ++ni)
; #pragma unroll
;                 for (int i = 0; i < 4; ++i) part[(16 * mi + 4 * kq + i) * 64 + 16 * ni + c16] = acc[mi][ni][i];
;         __syncthreads();
.LBB0_609:
	s_ashr_i32 s0, s18, 31
	s_lshr_b32 s0, s0, 29
	s_add_i32 s0, s18, s0
	s_ashr_i32 s1, s0, 3
	s_lshl_b32 s0, s1, 6
	s_lshl_b32 s1, s1, 9
	s_sub_i32 s1, s23, s1
	s_and_b32 s2, s21, 0x60
	v_or_b32_e32 v2, s0, v1
	s_and_b32 s3, s1, 0xffffff00
	v_ashrrev_i32_e32 v3, 31, v2
	s_or_b32 s2, s2, s3
	v_lshlrev_b64 v[2:3], 10, v[2:3]
	v_or_b32_e32 v4, s2, v1
	v_lshl_add_u64 v[58:59], v[90:91], 0, v[2:3]
	v_ashrrev_i32_e32 v5, 31, v4
	v_add_co_u32_e32 v60, vcc, s20, v58
	v_lshlrev_b64 v[2:3], 10, v[4:5]
	s_nop 0
	v_addc_co_u32_e32 v61, vcc, 0, v59, vcc
	v_lshl_add_u64 v[2:3], v[92:93], 0, v[2:3]
	v_add_co_u32_e32 v6, vcc, s20, v2
	global_load_dwordx4 v[18:21], v[58:59], off
	global_load_dwordx4 v[22:25], v[58:59], off offset:64
	v_addc_co_u32_e32 v7, vcc, 0, v3, vcc
	v_add_co_u32_e32 v8, vcc, s27, v2
	global_load_dwordx4 v[26:29], v[2:3], off
	s_nop 0
	v_addc_co_u32_e32 v9, vcc, 0, v3, vcc
	v_add_co_u32_e32 v46, vcc, s28, v2
	s_add_i32 s21, s21, s22
	s_nop 0
	v_addc_co_u32_e32 v47, vcc, 0, v3, vcc
	global_load_dwordx4 v[2:5], v[2:3], off offset:64
	s_nop 0
	global_load_dwordx4 v[34:37], v[6:7], off
	global_load_dwordx4 v[14:17], v[6:7], off offset:64
	global_load_dwordx4 v[42:45], v[8:9], off
	global_load_dwordx4 v[10:13], v[8:9], off offset:64
	global_load_dwordx4 v[54:57], v[46:47], off
	s_nop 0
	global_load_dwordx4 v[6:9], v[46:47], off offset:64
	s_nop 0
	global_load_dwordx4 v[46:49], v[60:61], off
	global_load_dwordx4 v[110:113], v[60:61], off offset:64
	v_add_co_u32_e32 v60, vcc, s25, v58
	s_add_i32 s18, s18, s19
	s_nop 0
	v_addc_co_u32_e32 v61, vcc, 0, v59, vcc
	v_add_co_u32_e32 v62, vcc, s26, v58
	s_add_i32 s23, s23, s24
	s_nop 0
	v_addc_co_u32_e32 v63, vcc, 0, v59, vcc
	s_cmp_lt_i32 s18, 64
	s_waitcnt vmcnt(9)
	v_mfma_f32_16x16x32_bf16 v[30:33], v[18:21], v[26:29], 0
	s_waitcnt vmcnt(1)
	v_mfma_f32_16x16x32_bf16 v[114:117], v[46:49], v[26:29], 0
	v_mfma_f32_16x16x32_bf16 v[118:121], v[46:49], v[34:37], 0
	v_mfma_f32_16x16x32_bf16 v[122:125], v[46:49], v[42:45], 0
	v_mfma_f32_16x16x32_bf16 v[126:129], v[46:49], v[54:57], 0
	global_load_dwordx4 v[46:49], v[60:61], off
	global_load_dwordx4 v[70:73], v[60:61], off offset:64
	s_nop 0
	global_load_dwordx4 v[58:61], v[62:63], off
	v_mfma_f32_16x16x32_bf16 v[38:41], v[18:21], v[34:37], 0
	v_mfma_f32_16x16x32_bf16 v[50:53], v[18:21], v[42:45], 0
	v_mfma_f32_16x16x32_bf16 v[18:21], v[18:21], v[54:57], 0
	s_waitcnt vmcnt(2)
	v_mfma_f32_16x16x32_bf16 v[130:133], v[46:49], v[26:29], 0
	v_mfma_f32_16x16x32_bf16 v[134:137], v[46:49], v[34:37], 0
	v_mfma_f32_16x16x32_bf16 v[86:89], v[46:49], v[42:45], 0
	v_mfma_f32_16x16x32_bf16 v[82:85], v[46:49], v[54:57], 0
	global_load_dwordx4 v[46:49], v[62:63], off offset:64
	s_waitcnt vmcnt(0)
	s_waitcnt vmcnt(1)
	v_mfma_f32_16x16x32_bf16 v[78:81], v[58:61], v[26:29], 0
	v_mfma_f32_16x16x32_bf16 v[74:77], v[58:61], v[34:37], 0
	v_mfma_f32_16x16x32_bf16 v[66:69], v[58:61], v[42:45], 0
	v_mfma_f32_16x16x32_bf16 v[62:65], v[58:61], v[54:57], 0
	v_mfma_f32_16x16x32_bf16 v[54:57], v[22:25], v[2:5], v[30:33]
	v_mfma_f32_16x16x32_bf16 v[58:61], v[22:25], v[14:17], v[38:41]
	v_mfma_f32_16x16x32_bf16 v[34:37], v[110:113], v[2:5], v[114:117]
	v_mfma_f32_16x16x32_bf16 v[38:41], v[110:113], v[14:17], v[118:121]
	v_mfma_f32_16x16x32_bf16 v[26:29], v[110:113], v[10:13], v[122:125]
	v_mfma_f32_16x16x32_bf16 v[30:33], v[110:113], v[6:9], v[126:129]
	v_add_u32_e32 v110, s0, v96
	v_ashrrev_i32_e32 v111, 31, v110
	v_mfma_f32_16x16x32_bf16 v[42:45], v[22:25], v[10:13], v[50:53]
	v_mfma_f32_16x16x32_bf16 v[50:53], v[22:25], v[6:9], v[18:21]
	v_mfma_f32_16x16x32_bf16 v[18:21], v[70:73], v[2:5], v[130:133]
	v_mfma_f32_16x16x32_bf16 v[22:25], v[70:73], v[14:17], v[134:137]
	v_mfma_f32_16x16x32_bf16 v[86:89], v[70:73], v[10:13], v[86:89]
	v_mfma_f32_16x16x32_bf16 v[70:73], v[70:73], v[6:9], v[82:85]
	s_nop 2
	v_add_u32_e32 v82, s1, v94
	v_lshlrev_b64 v[84:85], 10, v[110:111]
	v_ashrrev_i32_e32 v83, 31, v82
	s_waitcnt vmcnt(0)
	v_mfma_f32_16x16x32_bf16 v[2:5], v[46:49], v[2:5], v[78:81]
	s_nop 2
	v_lshl_add_u64 v[80:81], s[14:15], 0, v[84:85]
	v_lshlrev_b64 v[78:79], 11, v[110:111]
	v_mfma_f32_16x16x32_bf16 v[14:17], v[46:49], v[14:17], v[74:77]
	s_nop 2
	v_lshlrev_b64 v[74:75], 1, v[82:83]
	v_mfma_f32_16x16x32_bf16 v[10:13], v[46:49], v[10:13], v[66:69]
	v_lshl_add_u64 v[76:77], s[16:17], 0, v[78:79]
	s_nop 1
	v_lshl_add_u64 v[66:67], v[80:81], 0, v[74:75]
	v_mfma_f32_16x16x32_bf16 v[6:9], v[46:49], v[6:9], v[62:65]
	ds_write2_b32 v97, v54, v58 offset1:16
	ds_write2_b32 v97, v55, v59 offset0:64 offset1:80
	ds_write2_b32 v97, v56, v60 offset0:128 offset1:144
	ds_write2_b32 v97, v57, v61 offset0:192 offset1:208
	ds_write2_b32 v97, v42, v50 offset0:32 offset1:48
	ds_write2_b32 v97, v43, v51 offset0:96 offset1:112
	ds_write2_b32 v97, v44, v52 offset0:160 offset1:176
	ds_write2_b32 v97, v45, v53 offset0:224 offset1:240
	ds_write2_b32 v106, v34, v38 offset1:16
	ds_write2_b32 v106, v35, v39 offset0:64 offset1:80
	ds_write2_b32 v106, v36, v40 offset0:128 offset1:144
	ds_write2_b32 v106, v37, v41 offset0:192 offset1:208
	ds_write2_b32 v106, v26, v30 offset0:32 offset1:48
	ds_write2_b32 v106, v27, v31 offset0:96 offset1:112
	ds_write2_b32 v106, v28, v32 offset0:160 offset1:176
	ds_write2_b32 v106, v29, v33 offset0:224 offset1:240
	ds_write2_b32 v107, v18, v22 offset1:16
	ds_write2_b32 v107, v19, v23 offset0:64 offset1:80
	ds_write2_b32 v107, v20, v24 offset0:128 offset1:144
	ds_write2_b32 v107, v21, v25 offset0:192 offset1:208
	ds_write2_b32 v107, v86, v70 offset0:32 offset1:48
	ds_write2_b32 v107, v87, v71 offset0:96 offset1:112
	ds_write2_b32 v107, v88, v72 offset0:160 offset1:176
	ds_write2_b32 v107, v89, v73 offset0:224 offset1:240
	ds_write2_b32 v108, v2, v14 offset1:16
	ds_write2_b32 v108, v3, v15 offset0:64 offset1:80
	ds_write2_b32 v108, v4, v16 offset0:128 offset1:144
	ds_write2_b32 v108, v5, v17 offset0:192 offset1:208
	ds_write2_b32 v108, v10, v6 offset0:32 offset1:48
	ds_write2_b32 v108, v11, v7 offset0:96 offset1:112
	ds_write2_b32 v108, v12, v8 offset0:160 offset1:176
	ds_write2_b32 v108, v13, v9 offset0:224 offset1:240
	s_waitcnt lgkmcnt(0)
	s_barrier
; #define LAS __attribute__((address_space(3)))
; template <int NKS, bool ATILED = false, bool FFN = false, bool HALF = false, class EF> ...
;     ...
;         const int row = tid >> 3, c8 = (tid & 7) * 8; float v[8];
;         if (!HALF || tid < 256) {
; #pragma unroll
;         for (int i = 0; i < 8; ++i) v[i] = 0.f;
; #pragma unroll
;         for (int w2 = 0; w2 < 8; ++w2) { const f32x4 x = *(const LAS f32x4*)(lf + w2 * 4096 + row * 64 + c8), y = *(const LAS f32x4*)(lf + w2 * 4096 + row * 64 + c8 + 4);
;             v[0] += x[0]; v[1] += x[1]; v[2] += x[2]; v[3] += x[3]; v[4] += y[0]; v[5] += y[1]; v[6] += y[2]; v[7] += y[3]; }
;         }
;         if constexpr (FFN) ef.ffn(lf, 64 * rb + row, row, cb, c8, v);
;         else if (!HALF || tid < 256) ef(RB * rb + row, 64 * cb + c8, v, lane);
	ds_read_b128 v[2:5], v95
	ds_read_b128 v[6:9], v95 offset:16
	ds_read_b128 v[10:13], v95 offset:16384
	ds_read_b128 v[14:17], v95 offset:16400
	ds_read_b128 v[18:21], v95 offset:32768
	ds_read_b128 v[22:25], v95 offset:32784
	ds_read_b128 v[26:29], v95 offset:49152
	ds_read_b128 v[30:33], v95 offset:49168
	ds_read_b128 v[34:37], v98
	ds_read_b128 v[38:41], v99
	ds_read_b128 v[42:45], v100
	ds_read_b128 v[46:49], v101
	ds_read_b128 v[50:53], v102
	ds_read_b128 v[54:57], v103
	ds_read_b128 v[58:61], v104
	ds_read_b128 v[62:65], v105
	global_load_dwordx4 v[66:69], v[66:67], off
	s_waitcnt lgkmcnt(14)
	v_add_f32_e32 v2, 0, v2
	v_add_f32_e32 v3, 0, v3
	s_waitcnt lgkmcnt(13)
	v_add_f32_e32 v2, v2, v10
	v_add_f32_e32 v3, v3, v11
	v_add_f32_e32 v4, 0, v4
	v_add_f32_e32 v5, 0, v5
	s_waitcnt lgkmcnt(11)
	v_add_f32_e32 v2, v2, v18
	v_add_f32_e32 v3, v3, v19
	v_add_f32_e32 v4, v4, v12
	v_add_f32_e32 v5, v5, v13
	s_waitcnt lgkmcnt(9)
	v_add_f32_e32 v2, v2, v26
	v_add_f32_e32 v3, v3, v27
	v_add_f32_e32 v6, 0, v6
	v_add_f32_e32 v7, 0, v7
	v_add_f32_e32 v4, v4, v20
	v_add_f32_e32 v5, v5, v21
	s_waitcnt lgkmcnt(7)
	v_add_f32_e32 v2, v2, v34
	v_add_f32_e32 v3, v3, v35
	v_add_f32_e32 v6, v6, v14
	v_add_f32_e32 v7, v7, v15
	v_add_f32_e32 v4, v4, v28
	v_add_f32_e32 v5, v5, v29
	s_waitcnt lgkmcnt(5)
	v_add_f32_e32 v2, v2, v42
	v_add_f32_e32 v3, v3, v43
	v_add_f32_e32 v8, 0, v8
	v_add_f32_e32 v9, 0, v9
	v_add_f32_e32 v6, v6, v22
	v_add_f32_e32 v7, v7, v23
	v_add_f32_e32 v4, v4, v36
	v_add_f32_e32 v5, v5, v37
	s_waitcnt lgkmcnt(3)
	v_add_f32_e32 v2, v2, v50
	v_add_f32_e32 v3, v3, v51
	v_add_f32_e32 v8, v8, v16
	v_add_f32_e32 v9, v9, v17
	v_add_f32_e32 v6, v6, v30
	v_add_f32_e32 v7, v7, v31
	v_add_f32_e32 v4, v4, v44
	v_add_f32_e32 v5, v5, v45
	s_waitcnt lgkmcnt(1)
	v_add_f32_e32 v2, v2, v58
	v_add_f32_e32 v3, v3, v59
	v_add_f32_e32 v8, v8, v24
	v_add_f32_e32 v9, v9, v25
	v_add_f32_e32 v6, v6, v38
	v_add_f32_e32 v7, v7, v39
	v_add_f32_e32 v4, v4, v52
	v_add_f32_e32 v5, v5, v53
	v_mul_f32_e32 v2, 0xbfb8aa3b, v2
	v_mul_f32_e32 v3, 0xbfb8aa3b, v3
	v_add_f32_e32 v8, v8, v32
	v_add_f32_e32 v9, v9, v33
	v_add_f32_e32 v6, v6, v46
	v_add_f32_e32 v7, v7, v47
	v_add_f32_e32 v4, v4, v60
	v_add_f32_e32 v5, v5, v61
	v_exp_f32_e32 v2, v2
	v_exp_f32_e32 v3, v3
	v_add_f32_e32 v8, v8, v40
	v_add_f32_e32 v9, v9, v41
	v_add_f32_e32 v6, v6, v54
	v_add_f32_e32 v7, v7, v55
	v_mul_f32_e32 v4, 0xbfb8aa3b, v4
	v_mul_f32_e32 v5, 0xbfb8aa3b, v5
	v_add_f32_e32 v8, v8, v48
	v_add_f32_e32 v9, v9, v49
	s_waitcnt lgkmcnt(0)
	v_add_f32_e32 v6, v6, v62
	v_add_f32_e32 v7, v7, v63
	v_exp_f32_e32 v4, v4
	v_exp_f32_e32 v5, v5
	v_add_f32_e32 v8, v8, v56
	v_add_f32_e32 v9, v9, v57
	v_mul_f32_e32 v6, 0xbfb8aa3b, v6
	v_mul_f32_e32 v7, 0xbfb8aa3b, v7
	v_add_f32_e32 v8, v8, v64
	v_add_f32_e32 v9, v9, v65
	v_exp_f32_e32 v6, v6
	v_exp_f32_e32 v7, v7
	v_pk_add_f32 v[2:3], v[2:3], 1.0 op_sel_hi:[1,0]
	v_mul_f32_e32 v8, 0xbfb8aa3b, v8
	v_mul_f32_e32 v9, 0xbfb8aa3b, v9
	v_exp_f32_e32 v8, v8
	v_exp_f32_e32 v9, v9
	v_pk_add_f32 v[4:5], v[4:5], 1.0 op_sel_hi:[1,0]
	v_div_scale_f32 v12, s[0:1], v2, v2, 1.0
	v_div_scale_f32 v14, s[2:3], v5, v5, 1.0
	v_rcp_f32_e32 v27, v12
	v_pk_add_f32 v[6:7], v[6:7], 1.0 op_sel_hi:[1,0]
	v_div_scale_f32 v16, s[4:5], v4, v4, 1.0
	v_rcp_f32_e32 v28, v14
	v_div_scale_f32 v18, s[6:7], v7, v7, 1.0
	v_rcp_f32_e32 v29, v16
	v_pk_add_f32 v[8:9], v[8:9], 1.0 op_sel_hi:[1,0]
	v_div_scale_f32 v20, s[8:9], v6, v6, 1.0
	v_rcp_f32_e32 v30, v18
	v_div_scale_f32 v22, s[10:11], v9, v9, 1.0
	v_rcp_f32_e32 v31, v20
	v_fma_f32 v35, -v12, v27, 1.0
	v_div_scale_f32 v13, s[0:1], 1.0, v2, 1.0
	v_div_scale_f32 v24, s[12:13], v8, v8, 1.0
	v_rcp_f32_e32 v32, v22
	v_fma_f32 v36, -v14, v28, 1.0
	v_fmac_f32_e32 v27, v35, v27
	v_div_scale_f32 v15, s[2:3], 1.0, v5, 1.0
	v_rcp_f32_e32 v33, v24
	v_fma_f32 v37, -v16, v29, 1.0
	v_fmac_f32_e32 v28, v36, v28
	v_mul_f32_e32 v35, v13, v27
	v_div_scale_f32 v17, s[4:5], 1.0, v4, 1.0
	v_fma_f32 v38, -v18, v30, 1.0
	v_fmac_f32_e32 v29, v37, v29
	v_mul_f32_e32 v36, v15, v28
	v_fma_f32 v43, -v12, v35, v13
	v_div_scale_f32 v19, s[6:7], 1.0, v7, 1.0
	v_fma_f32 v39, -v20, v31, 1.0
	v_fmac_f32_e32 v30, v38, v30
	v_mul_f32_e32 v37, v17, v29
	v_fma_f32 v44, -v14, v36, v15
	v_fmac_f32_e32 v35, v43, v27
	v_div_scale_f32 v21, s[8:9], 1.0, v6, 1.0
	v_fma_f32 v40, -v22, v32, 1.0
	v_fmac_f32_e32 v31, v39, v31
	v_mul_f32_e32 v38, v19, v30
	v_fma_f32 v45, -v16, v37, v17
	v_fmac_f32_e32 v36, v44, v28
	v_fma_f32 v11, -v12, v35, v13
	s_mov_b64 vcc, s[0:1]
	v_div_scale_f32 v23, s[10:11], 1.0, v9, 1.0
	v_fma_f32 v41, -v24, v33, 1.0
	v_fmac_f32_e32 v32, v40, v32
	v_mul_f32_e32 v39, v21, v31
	v_fma_f32 v46, -v18, v38, v19
	v_fmac_f32_e32 v37, v45, v29
	v_fma_f32 v12, -v14, v36, v15
	v_rcp_f32_e32 v3, v3
	v_div_fmas_f32 v10, v11, v27, v35
	s_mov_b64 vcc, s[2:3]
	v_div_scale_f32 v25, s[12:13], 1.0, v8, 1.0
	v_fmac_f32_e32 v33, v41, v33
	v_mul_f32_e32 v40, v23, v32
	v_fma_f32 v47, -v20, v39, v21
	v_fmac_f32_e32 v38, v46, v30
	v_fma_f32 v13, -v16, v37, v17
	v_div_fixup_f32 v2, v10, v2, 1.0
	v_div_fmas_f32 v10, v12, v28, v36
	s_mov_b64 vcc, s[4:5]
	v_mul_f32_e32 v41, v25, v33
	v_fma_f32 v48, -v22, v40, v23
	v_fmac_f32_e32 v39, v47, v31
	v_fma_f32 v14, -v18, v38, v19
	v_div_fixup_f32 v5, v10, v5, 1.0
	v_div_fmas_f32 v10, v13, v29, v37
	s_mov_b64 vcc, s[6:7]
	v_fma_f32 v49, -v24, v41, v25
	v_fmac_f32_e32 v40, v48, v32
	v_fma_f32 v15, -v20, v39, v21
	v_div_fixup_f32 v4, v10, v4, 1.0
	v_div_fmas_f32 v10, v14, v30, v38
	s_mov_b64 vcc, s[8:9]
	v_fmac_f32_e32 v41, v49, v33
	v_fma_f32 v16, -v22, v40, v23
	v_div_fixup_f32 v7, v10, v7, 1.0
	v_div_fmas_f32 v10, v15, v31, v39
	s_mov_b64 vcc, s[10:11]
	v_fma_f32 v17, -v24, v41, v25
	v_div_fixup_f32 v6, v10, v6, 1.0
	v_div_fmas_f32 v10, v16, v32, v40
	s_mov_b64 vcc, s[12:13]
	v_div_fixup_f32 v9, v10, v9, 1.0
	v_div_fmas_f32 v10, v17, v33, v41
	v_div_fixup_f32 v8, v10, v8, 1.0
	s_waitcnt vmcnt(0)
	v_lshlrev_b32_e32 v10, 16, v66
	v_and_b32_e32 v11, 0xffff0000, v66
	v_lshlrev_b32_e32 v12, 16, v67
	v_and_b32_e32 v13, 0xffff0000, v67
	v_lshlrev_b32_e32 v14, 16, v68
	v_and_b32_e32 v15, 0xffff0000, v68
	v_lshlrev_b32_e32 v16, 16, v69
	v_and_b32_e32 v17, 0xffff0000, v69
	v_pk_mul_f32 v[2:3], v[2:3], v[10:11]
	v_pk_mul_f32 v[4:5], v[4:5], v[12:13]
	v_pk_mul_f32 v[6:7], v[6:7], v[14:15]
	v_pk_mul_f32 v[8:9], v[8:9], v[16:17]
	v_lshl_add_u64 v[74:75], v[76:77], 0, v[74:75]
	v_cvt_pk_bf16_f32 v2, v2, v3
	v_cvt_pk_bf16_f32 v3, v4, v5
	v_cvt_pk_bf16_f32 v4, v6, v7
	v_cvt_pk_bf16_f32 v5, v8, v9
	global_store_dwordx4 v[74:75], v[2:5], off
	s_barrier
	s_cbranch_scc1 .LBB0_609

; __device__ __forceinline__ unsigned f2bf(float f) { return pk2(f, 0.f) & 0xffffu; }
; #define LDS_WAIT() asm volatile("s_waitcnt lgkmcnt(0)" ::: "memory")
; __device__ __forceinline__ void xattn_prompt_unit2(const bf16* CQ, const bf16* MKb, const bf16* MVb, bf16* CO, int rt, int h, float mref, LAS unsigned char* lds, int tid_in) {
;     ...
;     lrow += __shfl_xor(lrow, 32);
;     if (hi == 0) mxo[r32] = lrow;
;     __syncthreads();
;     if (hi == 0) fsc[r32] = 1.f / (lrow + mxp[r32]);
;     LDS_WAIT(); asm volatile("" ::: "memory");
; #pragma unroll
;     for (int r = 0; r < 16; ++r) { const int qr = (r & 3) + 8 * (r >> 2) + 4 * hi; const float rl = fsc[qr];
;         bf16* op = CO + (size_t)(128 * rt + 32 * pr + qr) * 1024 + h * 256 + 128 * which + r32;
; #pragma unroll
;         for (int d = 0; d < 4; ++d) op[32 * d] = (bf16)f2bf(o[d][r] * rl); }
;     __syncthreads();
.LBB0_876:
	s_or_b64 exec, exec, s[0:1]
	s_waitcnt lgkmcnt(0)
	v_lshl_add_u32 v80, v185, 2, s14
	ds_read_b128 v[86:89], v80
	ds_read_b128 v[90:93], v80 offset:32
	ds_read_b128 v[94:97], v80 offset:64
	ds_read_b128 v[98:101], v80 offset:96
	s_add_u32 s0, s10, s4
	s_addc_u32 s1, s11, 0
	s_lshl_b32 s4, s15, 1
	s_add_u32 s0, s0, s4
	s_addc_u32 s1, s1, 0
	v_lshlrev_b32_e32 v66, 1, v183
	v_mov_b32_e32 v67, v181
	v_lshl_add_u64 v[66:67], s[0:1], 0, v[66:67]
	s_sub_i32 s4, s14, 0x15800
	s_lshl_b32 s4, s4, 6
	v_lshlrev_b32_e32 v102, 8, v185
	v_lshl_add_u32 v102, v183, 1, v102
	v_add_u32_e32 v102, s4, v102
	v_lshrrev_b32_e32 v103, 4, v187
	v_and_b32_e32 v104, 15, v187
	v_lshlrev_b32_e32 v105, 4, v104
	v_lshl_add_u32 v106, v103, 8, v105
	v_add_u32_e32 v106, s4, v106
	v_add_u32_e32 v103, s12, v103
	v_lshl_add_u32 v104, v103, 11, v105
	s_waitcnt lgkmcnt(0)
	v_pk_mul_f32 v[2:3], v[2:3], v[86:87]
	v_pk_mul_f32 v[4:5], v[4:5], v[88:89]
	v_pk_mul_f32 v[6:7], v[6:7], v[90:91]
	v_pk_mul_f32 v[8:9], v[8:9], v[92:93]
	v_pk_mul_f32 v[10:11], v[10:11], v[94:95]
	v_pk_mul_f32 v[12:13], v[12:13], v[96:97]
	v_pk_mul_f32 v[14:15], v[14:15], v[98:99]
	v_pk_mul_f32 v[16:17], v[16:17], v[100:101]
	v_pk_mul_f32 v[18:19], v[18:19], v[86:87]
	v_pk_mul_f32 v[20:21], v[20:21], v[88:89]
	v_pk_mul_f32 v[22:23], v[22:23], v[90:91]
	v_pk_mul_f32 v[24:25], v[24:25], v[92:93]
	v_pk_mul_f32 v[26:27], v[26:27], v[94:95]
	v_pk_mul_f32 v[28:29], v[28:29], v[96:97]
	v_pk_mul_f32 v[30:31], v[30:31], v[98:99]
	v_pk_mul_f32 v[32:33], v[32:33], v[100:101]
	v_pk_mul_f32 v[34:35], v[34:35], v[86:87]
	v_pk_mul_f32 v[36:37], v[36:37], v[88:89]
	v_pk_mul_f32 v[38:39], v[38:39], v[90:91]
	v_pk_mul_f32 v[40:41], v[40:41], v[92:93]
	v_pk_mul_f32 v[42:43], v[42:43], v[94:95]
	v_pk_mul_f32 v[44:45], v[44:45], v[96:97]
	v_pk_mul_f32 v[46:47], v[46:47], v[98:99]
	v_pk_mul_f32 v[48:49], v[48:49], v[100:101]
	v_pk_mul_f32 v[50:51], v[50:51], v[86:87]
	v_pk_mul_f32 v[52:53], v[52:53], v[88:89]
	v_pk_mul_f32 v[54:55], v[54:55], v[90:91]
	v_pk_mul_f32 v[56:57], v[56:57], v[92:93]
	v_pk_mul_f32 v[58:59], v[58:59], v[94:95]
	v_pk_mul_f32 v[60:61], v[60:61], v[96:97]
	v_pk_mul_f32 v[62:63], v[62:63], v[98:99]
	v_pk_mul_f32 v[64:65], v[64:65], v[100:101]
	v_cvt_pk_bf16_f32 v2, v2, v3
	ds_write_b16 v102, v2 offset:0
	ds_write_b16_d16_hi v102, v2 offset:256
	v_cvt_pk_bf16_f32 v4, v4, v5
	ds_write_b16 v102, v4 offset:512
	ds_write_b16_d16_hi v102, v4 offset:768
	v_cvt_pk_bf16_f32 v6, v6, v7
	ds_write_b16 v102, v6 offset:2048
	ds_write_b16_d16_hi v102, v6 offset:2304
	v_cvt_pk_bf16_f32 v8, v8, v9
	ds_write_b16 v102, v8 offset:2560
	ds_write_b16_d16_hi v102, v8 offset:2816
	v_cvt_pk_bf16_f32 v10, v10, v11
	ds_write_b16 v102, v10 offset:4096
	ds_write_b16_d16_hi v102, v10 offset:4352
	v_cvt_pk_bf16_f32 v12, v12, v13
	ds_write_b16 v102, v12 offset:4608
	ds_write_b16_d16_hi v102, v12 offset:4864
	v_cvt_pk_bf16_f32 v14, v14, v15
	ds_write_b16 v102, v14 offset:6144
	ds_write_b16_d16_hi v102, v14 offset:6400
	v_cvt_pk_bf16_f32 v16, v16, v17
	ds_write_b16 v102, v16 offset:6656
	ds_write_b16_d16_hi v102, v16 offset:6912
	v_cvt_pk_bf16_f32 v18, v18, v19
	ds_write_b16 v102, v18 offset:64
	ds_write_b16_d16_hi v102, v18 offset:320
	v_cvt_pk_bf16_f32 v20, v20, v21
	ds_write_b16 v102, v20 offset:576
	ds_write_b16_d16_hi v102, v20 offset:832
	v_cvt_pk_bf16_f32 v22, v22, v23
	ds_write_b16 v102, v22 offset:2112
	ds_write_b16_d16_hi v102, v22 offset:2368
	v_cvt_pk_bf16_f32 v24, v24, v25
	ds_write_b16 v102, v24 offset:2624
	ds_write_b16_d16_hi v102, v24 offset:2880
	v_cvt_pk_bf16_f32 v26, v26, v27
	ds_write_b16 v102, v26 offset:4160
	ds_write_b16_d16_hi v102, v26 offset:4416
	v_cvt_pk_bf16_f32 v28, v28, v29
	ds_write_b16 v102, v28 offset:4672
	ds_write_b16_d16_hi v102, v28 offset:4928
	v_cvt_pk_bf16_f32 v30, v30, v31
	ds_write_b16 v102, v30 offset:6208
	ds_write_b16_d16_hi v102, v30 offset:6464
	v_cvt_pk_bf16_f32 v32, v32, v33
	ds_write_b16 v102, v32 offset:6720
	ds_write_b16_d16_hi v102, v32 offset:6976
	v_cvt_pk_bf16_f32 v34, v34, v35
	ds_write_b16 v102, v34 offset:128
	ds_write_b16_d16_hi v102, v34 offset:384
	v_cvt_pk_bf16_f32 v36, v36, v37
	ds_write_b16 v102, v36 offset:640
	ds_write_b16_d16_hi v102, v36 offset:896
	v_cvt_pk_bf16_f32 v38, v38, v39
	ds_write_b16 v102, v38 offset:2176
	ds_write_b16_d16_hi v102, v38 offset:2432
	v_cvt_pk_bf16_f32 v40, v40, v41
	ds_write_b16 v102, v40 offset:2688
	ds_write_b16_d16_hi v102, v40 offset:2944
	v_cvt_pk_bf16_f32 v42, v42, v43
	ds_write_b16 v102, v42 offset:4224
	ds_write_b16_d16_hi v102, v42 offset:4480
	v_cvt_pk_bf16_f32 v44, v44, v45
	ds_write_b16 v102, v44 offset:4736
	ds_write_b16_d16_hi v102, v44 offset:4992
	v_cvt_pk_bf16_f32 v46, v46, v47
	ds_write_b16 v102, v46 offset:6272
	ds_write_b16_d16_hi v102, v46 offset:6528
	v_cvt_pk_bf16_f32 v48, v48, v49
	ds_write_b16 v102, v48 offset:6784
	ds_write_b16_d16_hi v102, v48 offset:7040
	v_cvt_pk_bf16_f32 v50, v50, v51
	ds_write_b16 v102, v50 offset:192
	ds_write_b16_d16_hi v102, v50 offset:448
	v_cvt_pk_bf16_f32 v52, v52, v53
	ds_write_b16 v102, v52 offset:704
	ds_write_b16_d16_hi v102, v52 offset:960
	v_cvt_pk_bf16_f32 v54, v54, v55
	ds_write_b16 v102, v54 offset:2240
	ds_write_b16_d16_hi v102, v54 offset:2496
	v_cvt_pk_bf16_f32 v56, v56, v57
	ds_write_b16 v102, v56 offset:2752
	ds_write_b16_d16_hi v102, v56 offset:3008
	v_cvt_pk_bf16_f32 v58, v58, v59
	ds_write_b16 v102, v58 offset:4288
	ds_write_b16_d16_hi v102, v58 offset:4544
	v_cvt_pk_bf16_f32 v60, v60, v61
	ds_write_b16 v102, v60 offset:4800
	ds_write_b16_d16_hi v102, v60 offset:5056
	v_cvt_pk_bf16_f32 v62, v62, v63
	ds_write_b16 v102, v62 offset:6336
	ds_write_b16_d16_hi v102, v62 offset:6592
	v_cvt_pk_bf16_f32 v64, v64, v65
	ds_write_b16 v102, v64 offset:6848
	ds_write_b16_d16_hi v102, v64 offset:7104
	s_waitcnt lgkmcnt(0)
	ds_read_b128 v[2:5], v106 offset:0
	ds_read_b128 v[6:9], v106 offset:1024
	ds_read_b128 v[10:13], v106 offset:2048
	ds_read_b128 v[14:17], v106 offset:3072
	ds_read_b128 v[18:21], v106 offset:4096
	ds_read_b128 v[22:25], v106 offset:5120
	ds_read_b128 v[26:29], v106 offset:6144
	ds_read_b128 v[30:33], v106 offset:7168
	s_waitcnt lgkmcnt(7)
	global_store_dwordx4 v104, v[2:5], s[0:1]
	v_add_u32_e32 v104, 0x2000, v104
	s_waitcnt lgkmcnt(6)
	global_store_dwordx4 v104, v[6:9], s[0:1]
	v_add_u32_e32 v104, 0x2000, v104
	s_waitcnt lgkmcnt(5)
	global_store_dwordx4 v104, v[10:13], s[0:1]
	v_add_u32_e32 v104, 0x2000, v104
	s_waitcnt lgkmcnt(4)
	global_store_dwordx4 v104, v[14:17], s[0:1]
	v_add_u32_e32 v104, 0x2000, v104
	s_waitcnt lgkmcnt(3)
	global_store_dwordx4 v104, v[18:21], s[0:1]
	v_add_u32_e32 v104, 0x2000, v104
	s_waitcnt lgkmcnt(2)
	global_store_dwordx4 v104, v[22:25], s[0:1]
	v_add_u32_e32 v104, 0x2000, v104
	s_waitcnt lgkmcnt(1)
	global_store_dwordx4 v104, v[26:29], s[0:1]
	v_add_u32_e32 v104, 0x2000, v104
	s_waitcnt lgkmcnt(0)
	global_store_dwordx4 v104, v[30:33], s[0:1]
	s_waitcnt vmcnt(63) expcnt(7) lgkmcnt(15)
	s_barrier

; #define LAS __attribute__((address_space(3)))
;     __device__ __forceinline__ void operator()(const f32x4 (&acc)[2][2][4][2], const Unit& u, int wr, int wc, int fr, int fq) const {
;         const int row0 = u.pm * 256 + wr * 64 + fr, ci0 = 8 * fq, ch0 = u.pn * 128 + 32 * wc + ci0;
;         tile_rs(SS, u.pm, rsl);
;         f32x4 gs[2][4][2];
; _Pragma("unroll")
;         for (int ai = 0; ai < 2; ++ai)
; _Pragma("unroll")
;             for (int m = 0; m < 4; ++m) { const float rs = rsl[128 * ai + 64 * wr + 16 * m + fr]; gs[ai][m][0] = acc[ai][0][m][0] * rs; gs[ai][m][1] = acc[ai][0][m][1] * rs; }
;         if (fr >= 14) {
;             const bool seq_end = (u.pm & 15) == 15;
; _Pragma("unroll")
;             for (int ai = 0; ai < 2; ++ai) { const int q = 2 * ai + wr + 1; const int slot = q < 4 ? q : 4 + ((u.pm + 1) & 1); const bool zero = (q == 4) && seq_end;
; _Pragma("unroll")
;                 for (int n = 0; n < 2; ++n) *(LAS f32x4*)(hal + halo_idx(slot, wc, fr - 14, ci0 + 4 * n)) = zero ? (f32x4){0.f, 0.f, 0.f, 0.f} : gs[ai][3][n];
;                 if (seq_end && ai == 1 && wr == 1) {
;                     float* co = out + O_CP + (size_t)((u.pm >> 4) * 2 + (fr - 14)) * FF + ch0; *(f32x4*)co = gs[1][3][0]; *(f32x4*)(co + 4) = gs[1][3][1]; } }
;         }
;         asm volatile("s_waitcnt lgkmcnt(0)" ::: "memory"); __builtin_amdgcn_s_barrier(); asm volatile("" ::: "memory");
;         f32x4 w0[2], w1[2], w2[2], bb[2];
; _Pragma("unroll")
;         for (int n = 0; n < 2; ++n) { w0[n] = *(const f32x4*)(cw_ + ch0 + 4 * n); w1[n] = *(const f32x4*)(cw_ + FF + ch0 + 4 * n); w2[n] = *(const f32x4*)(cw_ + 2 * FF + ch0 + 4 * n); bb[n] = *(const f32x4*)(cb_ + ch0 + 4 * n); }
; _Pragma("unroll")
;         for (int ai = 0; ai < 2; ++ai)
; _Pragma("unroll")
;             for (int m = 0; m < 4; ++m) { const int r = row0 + 128 * ai + 16 * m; const float rs = rsl[128 * ai + 64 * wr + 16 * m + fr]; f32x4 o[2];
; _Pragma("unroll")
;                 for (int n = 0; n < 2; ++n) { f32x4 p1, p2, q1, q2;
;                     if (m > 0) {
; _Pragma("unroll")
;                         for (int j = 0; j < 4; ++j) { q1[j] = row_from_below<1>(gs[ai][m - 1][n][j]); q2[j] = row_from_below<2>(gs[ai][m - 1][n][j]); } }
;                     else { const int slot = (2 * ai + wr) ? (2 * ai + wr) : 4 + (u.pm & 1);
.LBB0_1086:
	s_or_b64 exec, exec, s[0:1]
	s_waitcnt lgkmcnt(0)
	s_barrier
	global_load_dwordx4 v[58:61], v[158:159], off
	global_load_dwordx4 v[70:73], v[164:165], off
	global_load_dwordx4 v[62:65], v[160:161], off
	global_load_dwordx4 v[66:69], v[162:163], off
	v_pk_mul_f32 v[166:167], v[44:45], v[172:173] op_sel_hi:[1,0]
	v_pk_mul_f32 v[168:169], v[42:43], v[172:173] op_sel_hi:[1,0]
	v_pk_mul_f32 v[170:171], v[48:49], v[172:173] op_sel_hi:[1,0]
	v_pk_mul_f32 v[172:173], v[46:47], v[172:173] op_sel_hi:[1,0]
	v_mov_b32_e32 v218, v185
	v_pk_mul_f32 v[174:175], v[52:53], v[184:185] op_sel_hi:[1,0]
	v_pk_mul_f32 v[176:177], v[50:51], v[184:185] op_sel_hi:[1,0]
	v_pk_mul_f32 v[182:183], v[56:57], v[184:185] op_sel_hi:[1,0]
	v_pk_mul_f32 v[184:185], v[54:55], v[184:185] op_sel_hi:[1,0]
	global_load_dwordx4 v[42:45], v[158:159], off offset:16
	global_load_dwordx4 v[46:49], v[160:161], off offset:16
	global_load_dwordx4 v[50:53], v[162:163], off offset:16
	global_load_dwordx4 v[54:57], v[164:165], off offset:16
	v_pk_mul_f32 v[190:191], v[122:123], v[194:195] op_sel_hi:[1,0]
	v_pk_mul_f32 v[230:231], v[134:135], v[192:193] op_sel_hi:[1,0]
	v_or_b32_e32 v123, 4, v195
	v_mov_b32_e32 v134, s64
	v_cndmask_b32_e64 v123, v134, v123, s[12:13]
	v_lshl_or_b32 v123, v123, 3, s72
	v_pk_mul_f32 v[132:133], v[132:133], v[192:193] op_sel_hi:[1,0]
	v_pk_mul_f32 v[226:227], v[130:131], v[192:193] op_sel_hi:[1,0]
	v_pk_mul_f32 v[228:229], v[136:137], v[192:193] op_sel_hi:[1,0]
	v_or_b32_e32 v192, v123, v203
	v_pk_mul_f32 v[124:125], v[124:125], v[194:195] op_sel_hi:[1,0]
	v_pk_mul_f32 v[128:129], v[128:129], v[194:195] op_sel_hi:[1,0]
	v_pk_mul_f32 v[126:127], v[126:127], v[194:195] op_sel_hi:[1,0]
	v_mov_b32_e32 v194, v193
	v_lshl_add_u32 v123, v123, 7, v204
	v_lshl_add_u32 v222, v192, 7, v204
	v_pk_mul_f32 v[108:109], v[108:109], v[218:219] op_sel_hi:[1,0]
	v_pk_mul_f32 v[106:107], v[106:107], v[218:219] op_sel_hi:[1,0]
	v_pk_mul_f32 v[112:113], v[112:113], v[218:219] op_sel_hi:[1,0]
	v_pk_mul_f32 v[110:111], v[110:111], v[218:219] op_sel_hi:[1,0]
	v_pk_mul_f32 v[116:117], v[116:117], v[194:195] op_sel_hi:[1,0]
	v_pk_mul_f32 v[114:115], v[114:115], v[194:195] op_sel_hi:[1,0]
	v_pk_mul_f32 v[120:121], v[120:121], v[194:195] op_sel_hi:[1,0]
	v_pk_mul_f32 v[130:131], v[118:119], v[194:195] op_sel_hi:[1,0]
	ds_read2_b32 v[118:119], v214 offset1:16
	ds_read_b128 v[134:137], v123 offset:128
	ds_read_b128 v[192:195], v123 offset:144
	ds_read_b128 v[218:221], v222
	ds_read_b128 v[222:225], v222 offset:16
	v_mov_b32_e32 v233, 0
	v_mov_b32_e32 v235, 0
	v_mov_b32_e32 v232, 0
	v_mov_b32_e32 v234, 0
	v_mov_b32_dpp v233, v230 row_ror:2 row_mask:0xf bank_mask:0xf
	v_mov_b32_dpp v235, v231 row_ror:2 row_mask:0xf bank_mask:0xf
	v_mov_b32_dpp v232, v230 row_ror:1 row_mask:0xf bank_mask:0xf
	v_mov_b32_dpp v234, v231 row_ror:1 row_mask:0xf bank_mask:0xf
	s_waitcnt lgkmcnt(0)
	v_cndmask_b32_e64 v219, v219, v235, s[10:11]
	v_cndmask_b32_e64 v218, v218, v233, s[10:11]
	v_cndmask_b32_e64 v135, v234, v135, s[8:9]
	v_cndmask_b32_e64 v134, v232, v134, s[8:9]
	v_mov_b32_e32 v237, 0
	v_mov_b32_e32 v239, 0
	v_mov_b32_e32 v236, 0
	v_mov_b32_e32 v238, 0
	v_mov_b32_dpp v237, v228 row_ror:2 row_mask:0xf bank_mask:0xf
	v_mov_b32_dpp v239, v229 row_ror:2 row_mask:0xf bank_mask:0xf
	v_mov_b32_dpp v236, v228 row_ror:1 row_mask:0xf bank_mask:0xf
	v_mov_b32_dpp v238, v229 row_ror:1 row_mask:0xf bank_mask:0xf
	v_cndmask_b32_e64 v221, v221, v239, s[10:11]
	v_cndmask_b32_e64 v220, v220, v237, s[10:11]
	v_cndmask_b32_e64 v137, v238, v137, s[8:9]
	v_cndmask_b32_e64 v136, v236, v136, s[8:9]
	v_pk_mul_f32 v[102:103], v[102:103], v[118:119] op_sel_hi:[1,0]
	v_pk_mul_f32 v[104:105], v[104:105], v[118:119] op_sel_hi:[1,0]
	v_pk_mul_f32 v[98:99], v[98:99], v[118:119] op_sel_hi:[1,0]
	v_add_u32_e32 v122, s30, v212
	v_pk_mul_f32 v[100:101], v[100:101], v[118:119] op_sel_hi:[1,0]
	v_mov_b32_e32 v118, 0
	s_cmp_eq_u32 s78, s75
	s_waitcnt vmcnt(0)
	v_pk_fma_f32 v[218:219], v[58:59], v[218:219], v[70:71]
	s_nop 0
	v_pk_fma_f32 v[134:135], v[62:63], v[134:135], v[218:219]
	v_pk_fma_f32 v[220:221], v[60:61], v[220:221], v[72:73]
	v_pk_fma_f32 v[134:135], v[230:231], v[66:67], v[134:135]
	v_pk_fma_f32 v[136:137], v[64:65], v[136:137], v[220:221]
	v_mul_f32_e32 v123, 0xbfb8aa3b, v134
	v_mul_f32_e32 v219, 0xbfb8aa3b, v135
	v_exp_f32_e32 v218, v123
	v_exp_f32_e32 v219, v219
	v_pk_fma_f32 v[136:137], v[228:229], v[68:69], v[136:137]
	v_mov_b32_dpp v118, v130 row_ror:1 row_mask:0xf bank_mask:0xf
	v_pk_add_f32 v[218:219], v[218:219], 1.0 op_sel_hi:[1,0]
	s_nop 0
	v_rcp_f32_e32 v219, v219
	v_mul_f32_e32 v220, 0xbfb8aa3b, v136
	v_mul_f32_e32 v221, 0xbfb8aa3b, v137
	v_exp_f32_e32 v220, v220
	v_exp_f32_e32 v221, v221
	v_rcp_f32_e32 v218, v218
	s_nop 0
	v_pk_mul_f32 v[134:135], v[134:135], v[218:219]
	v_pk_add_f32 v[220:221], v[220:221], 1.0 op_sel_hi:[1,0]
	v_pk_mul_f32 v[102:103], v[102:103], v[134:135]
	v_mov_b32_e32 v229, 0
	v_mov_b32_e32 v230, 0
	v_mov_b32_e32 v231, 0
	v_rcp_f32_e32 v135, v221
	v_mov_b32_e32 v228, 0
	v_rcp_f32_e32 v134, v220
	v_mov_b32_e32 v218, 0
	v_mov_b32_e32 v219, 0
	v_mov_b32_e32 v220, 0
	v_mov_b32_e32 v221, 0
	v_mov_b32_dpp v218, v226 row_ror:1 row_mask:0xf bank_mask:0xf
	v_mov_b32_dpp v219, v226 row_ror:2 row_mask:0xf bank_mask:0xf
	v_mov_b32_dpp v220, v227 row_ror:1 row_mask:0xf bank_mask:0xf
	v_mov_b32_dpp v221, v227 row_ror:2 row_mask:0xf bank_mask:0xf
	v_pk_mul_f32 v[134:135], v[136:137], v[134:135]
	v_cndmask_b32_e64 v137, v220, v193, s[8:9]
	v_cndmask_b32_e64 v136, v218, v192, s[8:9]
	v_cndmask_b32_e64 v193, v223, v221, s[10:11]
	v_cndmask_b32_e64 v192, v222, v219, s[10:11]
; #define LAS __attribute__((address_space(3)))
; __device__ __forceinline__ size_t hidx(size_t r, int c) { return ((size_t)(c >> 6) * MTOT + r) * 64 + (c & 63); }
; __device__ __forceinline__ u32x4 pack8(const f32x4 a, const f32x4 b) { u32x4 w; w.x = cvt_pk_bf16(a[0], a[1]); w.y = cvt_pk_bf16(a[2], a[3]); w.z = cvt_pk_bf16(b[0], b[1]); w.w = cvt_pk_bf16(b[2], b[3]); return w; }
; __device__ __forceinline__ int halo_idx(int slot, int wc, int row, int ci) { return ((slot * 4 + wc) * 2 + row) * 32 + ci; }
; __device__ __forceinline__ float sigm(float x) { return 1.f / (1.f + __builtin_amdgcn_exp2f(-LOG2E * x)); }
;     __device__ __forceinline__ void operator()(const f32x4 (&acc)[2][2][4][2], const Unit& u, int wr, int wc, int fr, int fq) const {
;     ...
;             for (int m = 0; m < 4; ++m) { const int r = row0 + 128 * ai + 16 * m; const float rs = rsl[128 * ai + 64 * wr + 16 * m + fr]; f32x4 o[2];
; _Pragma("unroll")
;                 for (int n = 0; n < 2; ++n) { f32x4 p1, p2, q1, q2;
;                     if (m > 0) {
; _Pragma("unroll")
;                         for (int j = 0; j < 4; ++j) { q1[j] = row_from_below<1>(gs[ai][m - 1][n][j]); q2[j] = row_from_below<2>(gs[ai][m - 1][n][j]); } }
;                     else { const int slot = (2 * ai + wr) ? (2 * ai + wr) : 4 + (u.pm & 1);
;                         q1 = *(const LAS f32x4*)(hal + halo_idx(slot, wc, 1, ci0 + 4 * n)); q2 = *(const LAS f32x4*)(hal + halo_idx(slot, wc, fr == 0 ? 0 : 1, ci0 + 4 * n)); }
; _Pragma("unroll")
;                     for (int j = 0; j < 4; ++j) { p1[j] = row_from_below<1>(gs[ai][m][n][j]); p2[j] = row_from_below<2>(gs[ai][m][n][j]); }
;                     const f32x4 h1 = fr >= 1 ? p1 : q1, h0 = fr >= 2 ? p2 : q2;
;                     const f32x4 cv = bb[n] + w0[n] * h0 + w1[n] * h1 + w2[n] * gs[ai][m][n];
; _Pragma("unroll")
;                     for (int j = 0; j < 4; ++j) o[n][j] = cv[j] * sigm(cv[j]) * (acc[ai][1][m][n][j] * rs); }
;                 *(u32x4*)(H + hidx(r, ch0)) = pack8(o[0], o[1]); }
	v_pk_fma_f32 v[192:193], v[42:43], v[192:193], v[54:55]
	v_mov_b32_dpp v228, v132 row_ror:1 row_mask:0xf bank_mask:0xf
	v_pk_fma_f32 v[136:137], v[46:47], v[136:137], v[192:193]
	v_mov_b32_dpp v229, v132 row_ror:2 row_mask:0xf bank_mask:0xf
	v_pk_fma_f32 v[136:137], v[226:227], v[50:51], v[136:137]
	v_mov_b32_dpp v230, v133 row_ror:1 row_mask:0xf bank_mask:0xf
	v_mul_f32_e32 v123, 0xbfb8aa3b, v136
	v_exp_f32_e32 v192, v123
	v_mul_f32_e32 v123, 0xbfb8aa3b, v137
	v_exp_f32_e32 v193, v123
	v_mov_b32_dpp v231, v133 row_ror:2 row_mask:0xf bank_mask:0xf
	v_pk_mul_f32 v[104:105], v[104:105], v[134:135]
	v_cndmask_b32_e64 v135, v230, v195, s[8:9]
	v_pk_add_f32 v[192:193], v[192:193], 1.0 op_sel_hi:[1,0]
	v_cndmask_b32_e64 v134, v228, v194, s[8:9]
	v_cndmask_b32_e64 v195, v225, v231, s[10:11]
	v_cndmask_b32_e64 v194, v224, v229, s[10:11]
	v_pk_fma_f32 v[194:195], v[44:45], v[194:195], v[56:57]
	s_nop 0
	v_pk_fma_f32 v[134:135], v[48:49], v[134:135], v[194:195]
	s_nop 0
	v_pk_fma_f32 v[132:133], v[132:133], v[52:53], v[134:135]
	v_rcp_f32_e32 v135, v193
	v_mul_f32_e32 v134, 0xbfb8aa3b, v132
	v_exp_f32_e32 v194, v134
	v_mul_f32_e32 v134, 0xbfb8aa3b, v133
	v_exp_f32_e32 v195, v134
	v_rcp_f32_e32 v134, v192
	s_nop 0
	v_pk_mul_f32 v[134:135], v[136:137], v[134:135]
	v_pk_add_f32 v[192:193], v[194:195], 1.0 op_sel_hi:[1,0]
	v_pk_mul_f32 v[134:135], v[98:99], v[134:135]
	s_nop 0
	v_rcp_f32_e32 v99, v193
	v_rcp_f32_e32 v98, v192
	s_nop 0
	v_pk_mul_f32 v[98:99], v[132:133], v[98:99]
	v_ashrrev_i32_e32 v123, 31, v122
	v_pk_mul_f32 v[132:133], v[100:101], v[98:99]
	v_cvt_pk_bf16_f32 v98, v102, v103
	v_lshl_add_u64 v[102:103], s[48:49], 0, v[122:123]
	v_cvt_pk_bf16_f32 v101, v132, v133
	v_lshlrev_b64 v[102:103], 7, v[102:103]
	v_mov_b32_e32 v123, 0
	v_mov_b32_e32 v133, 0
	v_cvt_pk_bf16_f32 v99, v104, v105
	v_cvt_pk_bf16_f32 v100, v134, v135
	v_lshl_add_u64 v[102:103], v[156:157], 0, v[102:103]
	v_mov_b32_dpp v123, v130 row_ror:2 row_mask:0xf bank_mask:0xf
	v_mov_b32_e32 v132, 0
	v_mov_b32_dpp v133, v131 row_ror:2 row_mask:0xf bank_mask:0xf
	global_store_dwordx4 v[102:103], v[98:101], off
	v_mov_b32_dpp v132, v131 row_ror:1 row_mask:0xf bank_mask:0xf
	v_cndmask_b32_e64 v103, v235, v133, s[10:11]
	v_cndmask_b32_e64 v102, v233, v123, s[10:11]
	v_cndmask_b32_e64 v101, v132, v234, s[8:9]
	v_cndmask_b32_e64 v100, v118, v232, s[8:9]
	v_pk_fma_f32 v[102:103], v[58:59], v[102:103], v[70:71]
	v_mov_b32_e32 v135, 0
	v_pk_fma_f32 v[100:101], v[62:63], v[100:101], v[102:103]
	v_mov_b32_e32 v137, 0
	v_pk_fma_f32 v[100:101], v[130:131], v[66:67], v[100:101]
	v_mov_b32_e32 v134, 0
	v_mul_f32_e32 v98, 0xbfb8aa3b, v100
	v_exp_f32_e32 v102, v98
	v_mul_f32_e32 v98, 0xbfb8aa3b, v101
	v_exp_f32_e32 v103, v98
	v_mov_b32_dpp v135, v120 row_ror:2 row_mask:0xf bank_mask:0xf
	v_mov_b32_e32 v136, 0
	v_mov_b32_dpp v137, v121 row_ror:2 row_mask:0xf bank_mask:0xf
	v_pk_add_f32 v[102:103], v[102:103], 1.0 op_sel_hi:[1,0]
	v_mov_b32_dpp v134, v120 row_ror:1 row_mask:0xf bank_mask:0xf
	v_mov_b32_dpp v136, v121 row_ror:1 row_mask:0xf bank_mask:0xf
	v_cndmask_b32_e64 v105, v239, v137, s[10:11]
	v_cndmask_b32_e64 v104, v237, v135, s[10:11]
	v_cndmask_b32_e64 v99, v136, v238, s[8:9]
	v_cndmask_b32_e64 v98, v134, v236, s[8:9]
	v_pk_fma_f32 v[104:105], v[60:61], v[104:105], v[72:73]
	v_mov_b32_e32 v193, 0
	v_pk_fma_f32 v[98:99], v[64:65], v[98:99], v[104:105]
	s_nop 0
	v_pk_fma_f32 v[98:99], v[120:121], v[68:69], v[98:99]
	v_rcp_f32_e32 v103, v103
	v_mul_f32_e32 v104, 0xbfb8aa3b, v98
	v_mul_f32_e32 v105, 0xbfb8aa3b, v99
	v_exp_f32_e32 v104, v104
	v_exp_f32_e32 v105, v105
	v_rcp_f32_e32 v102, v102
	s_nop 0
	v_pk_mul_f32 v[100:101], v[100:101], v[102:103]
	v_pk_add_f32 v[102:103], v[104:105], 1.0 op_sel_hi:[1,0]
	v_mov_b32_e32 v104, v119
	v_div_scale_f32 v105, s[0:1], v103, v103, 1.0
	v_rcp_f32_e32 v120, v105
	v_pk_mul_f32 v[94:95], v[94:95], v[104:105] op_sel_hi:[1,0]
	v_mov_b32_e32 v121, 0
	v_pk_mul_f32 v[94:95], v[94:95], v[100:101]
	v_fma_f32 v100, -v105, v120, 1.0
	v_fmac_f32_e32 v120, v100, v120
	v_div_scale_f32 v100, vcc, 1.0, v103, 1.0
	v_mul_f32_e32 v101, v100, v120
	v_fma_f32 v119, -v105, v101, v100
	v_fmac_f32_e32 v101, v119, v120
	v_fma_f32 v100, -v105, v101, v100
	v_div_scale_f32 v105, s[0:1], v102, v102, 1.0
	v_rcp_f32_e32 v119, v105
	v_div_fmas_f32 v100, v100, v120, v101
	v_div_fixup_f32 v101, v100, v103, 1.0
	v_pk_mul_f32 v[96:97], v[96:97], v[104:105] op_sel_hi:[1,0]
	v_fma_f32 v100, -v105, v119, 1.0
	v_fmac_f32_e32 v119, v100, v119
	v_div_scale_f32 v100, vcc, 1.0, v102, 1.0
	v_mul_f32_e32 v103, v100, v119
	v_fma_f32 v120, -v105, v103, v100
	v_fmac_f32_e32 v103, v120, v119
	v_fma_f32 v100, -v105, v103, v100
	v_div_fmas_f32 v100, v100, v119, v103
	v_mov_b32_e32 v119, 0
	v_mov_b32_e32 v105, 0
	v_mov_b32_e32 v120, 0
	v_mov_b32_dpp v119, v114 row_ror:2 row_mask:0xf bank_mask:0xf
	v_mov_b32_dpp v121, v115 row_ror:2 row_mask:0xf bank_mask:0xf
	v_div_fixup_f32 v100, v100, v102, 1.0
	v_mov_b32_dpp v105, v114 row_ror:1 row_mask:0xf bank_mask:0xf
	v_mov_b32_dpp v120, v115 row_ror:1 row_mask:0xf bank_mask:0xf
	v_cndmask_b32_e64 v103, v221, v121, s[10:11]
	v_cndmask_b32_e64 v102, v219, v119, s[10:11]
	v_pk_mul_f32 v[98:99], v[98:99], v[100:101]
	v_cndmask_b32_e64 v101, v120, v220, s[8:9]
	v_cndmask_b32_e64 v100, v105, v218, s[8:9]
	v_pk_fma_f32 v[102:103], v[42:43], v[102:103], v[54:55]
	v_pk_mul_f32 v[96:97], v[96:97], v[98:99]
	v_pk_fma_f32 v[100:101], v[46:47], v[100:101], v[102:103]
	v_mov_b32_e32 v131, 0
	v_pk_fma_f32 v[100:101], v[114:115], v[50:51], v[100:101]
	v_mov_b32_e32 v130, 0
	v_mul_f32_e32 v98, 0xbfb8aa3b, v100
	v_exp_f32_e32 v102, v98
	v_mul_f32_e32 v98, 0xbfb8aa3b, v101
; #define LAS __attribute__((address_space(3)))
; __device__ __forceinline__ size_t hidx(size_t r, int c) { return ((size_t)(c >> 6) * MTOT + r) * 64 + (c & 63); }
; __device__ __forceinline__ u32x4 pack8(const f32x4 a, const f32x4 b) { u32x4 w; w.x = cvt_pk_bf16(a[0], a[1]); w.y = cvt_pk_bf16(a[2], a[3]); w.z = cvt_pk_bf16(b[0], b[1]); w.w = cvt_pk_bf16(b[2], b[3]); return w; }
; __device__ __forceinline__ int halo_idx(int slot, int wc, int row, int ci) { return ((slot * 4 + wc) * 2 + row) * 32 + ci; }
; __device__ __forceinline__ float sigm(float x) { return 1.f / (1.f + __builtin_amdgcn_exp2f(-LOG2E * x)); }
;     __device__ __forceinline__ void operator()(const f32x4 (&acc)[2][2][4][2], const Unit& u, int wr, int wc, int fr, int fq) const {
;     ...
;             for (int m = 0; m < 4; ++m) { const int r = row0 + 128 * ai + 16 * m; const float rs = rsl[128 * ai + 64 * wr + 16 * m + fr]; f32x4 o[2];
; _Pragma("unroll")
;                 for (int n = 0; n < 2; ++n) { f32x4 p1, p2, q1, q2;
;                     if (m > 0) {
; _Pragma("unroll")
;                         for (int j = 0; j < 4; ++j) { q1[j] = row_from_below<1>(gs[ai][m - 1][n][j]); q2[j] = row_from_below<2>(gs[ai][m - 1][n][j]); } }
;                     else { const int slot = (2 * ai + wr) ? (2 * ai + wr) : 4 + (u.pm & 1);
;                         q1 = *(const LAS f32x4*)(hal + halo_idx(slot, wc, 1, ci0 + 4 * n)); q2 = *(const LAS f32x4*)(hal + halo_idx(slot, wc, fr == 0 ? 0 : 1, ci0 + 4 * n)); }
; _Pragma("unroll")
;                     for (int j = 0; j < 4; ++j) { p1[j] = row_from_below<1>(gs[ai][m][n][j]); p2[j] = row_from_below<2>(gs[ai][m][n][j]); }
;                     const f32x4 h1 = fr >= 1 ? p1 : q1, h0 = fr >= 2 ? p2 : q2;
;                     const f32x4 cv = bb[n] + w0[n] * h0 + w1[n] * h1 + w2[n] * gs[ai][m][n];
; _Pragma("unroll")
;                     for (int j = 0; j < 4; ++j) o[n][j] = cv[j] * sigm(cv[j]) * (acc[ai][1][m][n][j] * rs); }
;                 *(u32x4*)(H + hidx(r, ch0)) = pack8(o[0], o[1]); }
	v_exp_f32_e32 v103, v98
	v_mov_b32_dpp v131, v116 row_ror:2 row_mask:0xf bank_mask:0xf
	v_mov_b32_e32 v192, 0
	v_mov_b32_dpp v193, v117 row_ror:2 row_mask:0xf bank_mask:0xf
	v_pk_add_f32 v[102:103], v[102:103], 1.0 op_sel_hi:[1,0]
	v_mov_b32_dpp v130, v116 row_ror:1 row_mask:0xf bank_mask:0xf
	v_mov_b32_dpp v192, v117 row_ror:1 row_mask:0xf bank_mask:0xf
	v_cndmask_b32_e64 v115, v231, v193, s[10:11]
	v_cndmask_b32_e64 v114, v229, v131, s[10:11]
	v_cndmask_b32_e64 v99, v192, v230, s[8:9]
	v_cndmask_b32_e64 v98, v130, v228, s[8:9]
	v_pk_fma_f32 v[114:115], v[44:45], v[114:115], v[56:57]
	v_pk_mul_f32 v[90:91], v[90:91], v[104:105] op_sel_hi:[1,0]
	v_pk_fma_f32 v[98:99], v[48:49], v[98:99], v[114:115]
	s_nop 0
	v_pk_fma_f32 v[98:99], v[116:117], v[52:53], v[98:99]
	v_rcp_f32_e32 v103, v103
	v_mul_f32_e32 v114, 0xbfb8aa3b, v98
	v_mul_f32_e32 v115, 0xbfb8aa3b, v99
	v_exp_f32_e32 v114, v114
	v_exp_f32_e32 v115, v115
	v_rcp_f32_e32 v102, v102
	s_nop 0
	v_pk_mul_f32 v[100:101], v[100:101], v[102:103]
	v_pk_add_f32 v[114:115], v[114:115], 1.0 op_sel_hi:[1,0]
	v_pk_mul_f32 v[100:101], v[90:91], v[100:101]
	v_pk_mul_f32 v[92:93], v[92:93], v[104:105] op_sel_hi:[1,0]
	v_mov_b32_e32 v104, 0
	v_rcp_f32_e32 v91, v115
	v_rcp_f32_e32 v90, v114
	v_or_b32_e32 v102, 16, v122
	v_pk_mul_f32 v[90:91], v[98:99], v[90:91]
	v_ashrrev_i32_e32 v103, 31, v102
	v_pk_mul_f32 v[98:99], v[92:93], v[90:91]
	v_cvt_pk_bf16_f32 v90, v94, v95
	v_cvt_pk_bf16_f32 v92, v100, v101
	v_lshl_add_u64 v[94:95], s[48:49], 0, v[102:103]
	v_mov_b32_e32 v101, 0
	v_mov_b32_e32 v103, 0
	v_lshlrev_b64 v[94:95], 7, v[94:95]
	v_mov_b32_e32 v100, 0
	v_mov_b32_dpp v101, v126 row_ror:2 row_mask:0xf bank_mask:0xf
	v_mov_b32_e32 v102, 0
	v_mov_b32_dpp v103, v127 row_ror:2 row_mask:0xf bank_mask:0xf
	v_cvt_pk_bf16_f32 v91, v96, v97
	v_cvt_pk_bf16_f32 v93, v98, v99
	v_lshl_add_u64 v[94:95], v[156:157], 0, v[94:95]
	v_mov_b32_dpp v100, v126 row_ror:1 row_mask:0xf bank_mask:0xf
	v_mov_b32_dpp v102, v127 row_ror:1 row_mask:0xf bank_mask:0xf
	v_cndmask_b32_e64 v97, v133, v103, s[10:11]
	v_cndmask_b32_e64 v96, v123, v101, s[10:11]
	global_store_dwordx4 v[94:95], v[90:93], off
	v_cndmask_b32_e64 v95, v102, v132, s[8:9]
	v_cndmask_b32_e64 v94, v100, v118, s[8:9]
	v_pk_fma_f32 v[96:97], v[58:59], v[96:97], v[70:71]
	v_mov_b32_e32 v114, 0
	v_pk_fma_f32 v[94:95], v[62:63], v[94:95], v[96:97]
	v_mov_b32_e32 v116, 0
	v_pk_fma_f32 v[94:95], v[126:127], v[66:67], v[94:95]
	v_mov_b32_dpp v114, v128 row_ror:2 row_mask:0xf bank_mask:0xf
	v_mul_f32_e32 v92, 0xbfb8aa3b, v94
	v_exp_f32_e32 v96, v92
	v_mul_f32_e32 v92, 0xbfb8aa3b, v95
	v_exp_f32_e32 v97, v92
	v_mov_b32_e32 v115, 0
	v_mov_b32_dpp v116, v129 row_ror:2 row_mask:0xf bank_mask:0xf
	v_mov_b32_dpp v104, v128 row_ror:1 row_mask:0xf bank_mask:0xf
	v_pk_add_f32 v[96:97], v[96:97], 1.0 op_sel_hi:[1,0]
	v_mov_b32_dpp v115, v129 row_ror:1 row_mask:0xf bank_mask:0xf
	v_cndmask_b32_e64 v99, v137, v116, s[10:11]
	v_cndmask_b32_e64 v98, v135, v114, s[10:11]
	v_cndmask_b32_e64 v93, v115, v136, s[8:9]
	v_cndmask_b32_e64 v92, v104, v134, s[8:9]
	v_pk_fma_f32 v[98:99], v[60:61], v[98:99], v[72:73]
	ds_read2_b32 v[90:91], v214 offset0:32 offset1:48
	v_pk_fma_f32 v[92:93], v[64:65], v[92:93], v[98:99]
	v_rcp_f32_e32 v97, v97
	v_pk_fma_f32 v[92:93], v[128:129], v[68:69], v[92:93]
	s_nop 0
	v_mul_f32_e32 v98, 0xbfb8aa3b, v92
	v_mul_f32_e32 v99, 0xbfb8aa3b, v93
	v_exp_f32_e32 v98, v98
	v_exp_f32_e32 v99, v99
	v_rcp_f32_e32 v96, v96
	s_nop 0
	v_pk_mul_f32 v[94:95], v[94:95], v[96:97]
	v_pk_add_f32 v[98:99], v[98:99], 1.0 op_sel_hi:[1,0]
	s_waitcnt lgkmcnt(0)
	v_pk_mul_f32 v[86:87], v[86:87], v[90:91] op_sel_hi:[1,0]
	s_nop 0
	v_pk_mul_f32 v[86:87], v[86:87], v[94:95]
	v_mov_b32_e32 v126, 0
	v_mov_b32_e32 v123, 0
	v_rcp_f32_e32 v95, v99
	v_mov_b32_e32 v118, 0
	v_mov_b32_e32 v117, 0
	s_nop 0
	v_mov_b32_dpp v118, v190 row_ror:2 row_mask:0xf bank_mask:0xf
	v_mov_b32_dpp v126, v191 row_ror:2 row_mask:0xf bank_mask:0xf
	v_rcp_f32_e32 v94, v98
	v_mov_b32_dpp v117, v190 row_ror:1 row_mask:0xf bank_mask:0xf
	v_mov_b32_dpp v123, v191 row_ror:1 row_mask:0xf bank_mask:0xf
	v_cndmask_b32_e64 v97, v121, v126, s[10:11]
	v_cndmask_b32_e64 v96, v119, v118, s[10:11]
	v_pk_mul_f32 v[92:93], v[92:93], v[94:95]
	v_cndmask_b32_e64 v95, v123, v120, s[8:9]
	v_cndmask_b32_e64 v94, v117, v105, s[8:9]
	v_pk_fma_f32 v[96:97], v[42:43], v[96:97], v[54:55]
	v_pk_mul_f32 v[88:89], v[88:89], v[90:91] op_sel_hi:[1,0]
	v_pk_fma_f32 v[94:95], v[46:47], v[94:95], v[96:97]
	v_pk_mul_f32 v[88:89], v[88:89], v[92:93]
	v_pk_fma_f32 v[94:95], v[190:191], v[50:51], v[94:95]
	v_mov_b32_e32 v128, 0
	v_mul_f32_e32 v92, 0xbfb8aa3b, v94
	v_exp_f32_e32 v96, v92
	v_mul_f32_e32 v92, 0xbfb8aa3b, v95
	v_exp_f32_e32 v97, v92
	v_mov_b32_e32 v132, 0
	v_mov_b32_e32 v127, 0
	v_mov_b32_dpp v128, v124 row_ror:2 row_mask:0xf bank_mask:0xf
	v_pk_add_f32 v[96:97], v[96:97], 1.0 op_sel_hi:[1,0]
	v_mov_b32_e32 v129, 0
	v_mov_b32_dpp v132, v125 row_ror:2 row_mask:0xf bank_mask:0xf
	v_mov_b32_dpp v127, v124 row_ror:1 row_mask:0xf bank_mask:0xf
	v_mov_b32_dpp v129, v125 row_ror:1 row_mask:0xf bank_mask:0xf
	v_cndmask_b32_e64 v99, v193, v132, s[10:11]
	v_cndmask_b32_e64 v98, v131, v128, s[10:11]
	v_cndmask_b32_e64 v93, v129, v192, s[8:9]
	v_cndmask_b32_e64 v92, v127, v130, s[8:9]
	v_pk_fma_f32 v[98:99], v[44:45], v[98:99], v[56:57]
	v_pk_mul_f32 v[82:83], v[82:83], v[90:91] op_sel_hi:[1,0]
	v_pk_fma_f32 v[92:93], v[48:49], v[92:93], v[98:99]
	v_rcp_f32_e32 v97, v97
	v_pk_fma_f32 v[92:93], v[124:125], v[52:53], v[92:93]
	s_nop 0
	v_mul_f32_e32 v98, 0xbfb8aa3b, v92
	v_mul_f32_e32 v99, 0xbfb8aa3b, v93
	v_exp_f32_e32 v98, v98
	v_exp_f32_e32 v99, v99
; #define LAS __attribute__((address_space(3)))
; __device__ __forceinline__ size_t hidx(size_t r, int c) { return ((size_t)(c >> 6) * MTOT + r) * 64 + (c & 63); }
; __device__ __forceinline__ u32x4 pack8(const f32x4 a, const f32x4 b) { u32x4 w; w.x = cvt_pk_bf16(a[0], a[1]); w.y = cvt_pk_bf16(a[2], a[3]); w.z = cvt_pk_bf16(b[0], b[1]); w.w = cvt_pk_bf16(b[2], b[3]); return w; }
; __device__ __forceinline__ int halo_idx(int slot, int wc, int row, int ci) { return ((slot * 4 + wc) * 2 + row) * 32 + ci; }
; __device__ __forceinline__ float sigm(float x) { return 1.f / (1.f + __builtin_amdgcn_exp2f(-LOG2E * x)); }
;     __device__ __forceinline__ void operator()(const f32x4 (&acc)[2][2][4][2], const Unit& u, int wr, int wc, int fr, int fq) const {
;     ...
;             for (int m = 0; m < 4; ++m) { const int r = row0 + 128 * ai + 16 * m; const float rs = rsl[128 * ai + 64 * wr + 16 * m + fr]; f32x4 o[2];
; _Pragma("unroll")
;                 for (int n = 0; n < 2; ++n) { f32x4 p1, p2, q1, q2;
;                     if (m > 0) {
; _Pragma("unroll")
;                         for (int j = 0; j < 4; ++j) { q1[j] = row_from_below<1>(gs[ai][m - 1][n][j]); q2[j] = row_from_below<2>(gs[ai][m - 1][n][j]); } }
;                     else { const int slot = (2 * ai + wr) ? (2 * ai + wr) : 4 + (u.pm & 1);
;                         q1 = *(const LAS f32x4*)(hal + halo_idx(slot, wc, 1, ci0 + 4 * n)); q2 = *(const LAS f32x4*)(hal + halo_idx(slot, wc, fr == 0 ? 0 : 1, ci0 + 4 * n)); }
; _Pragma("unroll")
;                     for (int j = 0; j < 4; ++j) { p1[j] = row_from_below<1>(gs[ai][m][n][j]); p2[j] = row_from_below<2>(gs[ai][m][n][j]); }
;                     const f32x4 h1 = fr >= 1 ? p1 : q1, h0 = fr >= 2 ? p2 : q2;
;                     const f32x4 cv = bb[n] + w0[n] * h0 + w1[n] * h1 + w2[n] * gs[ai][m][n];
; _Pragma("unroll")
;                     for (int j = 0; j < 4; ++j) o[n][j] = cv[j] * sigm(cv[j]) * (acc[ai][1][m][n][j] * rs); }
;                 *(u32x4*)(H + hidx(r, ch0)) = pack8(o[0], o[1]); }
	v_rcp_f32_e32 v96, v96
	s_nop 0
	v_pk_mul_f32 v[94:95], v[94:95], v[96:97]
	v_pk_add_f32 v[98:99], v[98:99], 1.0 op_sel_hi:[1,0]
	v_pk_mul_f32 v[94:95], v[82:83], v[94:95]
	v_pk_mul_f32 v[84:85], v[84:85], v[90:91] op_sel_hi:[1,0]
	v_mov_b32_e32 v90, 0
	v_rcp_f32_e32 v83, v99
	v_rcp_f32_e32 v82, v98
	v_or_b32_e32 v96, 32, v122
	v_pk_mul_f32 v[82:83], v[92:93], v[82:83]
	v_ashrrev_i32_e32 v97, 31, v96
	v_pk_mul_f32 v[92:93], v[84:85], v[82:83]
	v_cvt_pk_bf16_f32 v82, v86, v87
	v_lshl_add_u64 v[86:87], s[48:49], 0, v[96:97]
	v_lshlrev_b64 v[86:87], 7, v[86:87]
	v_cvt_pk_bf16_f32 v83, v88, v89
	v_cvt_pk_bf16_f32 v84, v94, v95
	v_cvt_pk_bf16_f32 v85, v92, v93
	v_lshl_add_u64 v[86:87], v[156:157], 0, v[86:87]
	global_store_dwordx4 v[86:87], v[82:85], off
	v_mov_b32_e32 v86, 0
	v_mov_b32_e32 v87, 0
	v_mov_b32_e32 v82, 0
	v_mov_b32_dpp v86, v188 row_ror:2 row_mask:0xf bank_mask:0xf
	v_mov_b32_e32 v84, 0
	v_mov_b32_dpp v87, v189 row_ror:2 row_mask:0xf bank_mask:0xf
	v_mov_b32_dpp v82, v188 row_ror:1 row_mask:0xf bank_mask:0xf
	v_mov_b32_dpp v84, v189 row_ror:1 row_mask:0xf bank_mask:0xf
	v_cndmask_b32_e64 v87, v103, v87, s[10:11]
	v_cndmask_b32_e64 v86, v101, v86, s[10:11]
	v_cndmask_b32_e64 v85, v84, v102, s[8:9]
	v_cndmask_b32_e64 v84, v82, v100, s[8:9]
	v_pk_fma_f32 v[86:87], v[58:59], v[86:87], v[70:71]
	v_mov_b32_e32 v88, 0
	v_pk_fma_f32 v[84:85], v[62:63], v[84:85], v[86:87]
	v_mov_b32_dpp v90, v186 row_ror:2 row_mask:0xf bank_mask:0xf
	v_pk_fma_f32 v[84:85], v[188:189], v[66:67], v[84:85]
	v_mov_b32_dpp v88, v186 row_ror:1 row_mask:0xf bank_mask:0xf
	v_mul_f32_e32 v82, 0xbfb8aa3b, v84
	v_exp_f32_e32 v86, v82
	v_mul_f32_e32 v82, 0xbfb8aa3b, v85
	v_exp_f32_e32 v87, v82
	v_cndmask_b32_e64 v82, v88, v104, s[8:9]
	v_cndmask_b32_e64 v88, v114, v90, s[10:11]
	v_mov_b32_e32 v89, 0
	v_pk_add_f32 v[86:87], v[86:87], 1.0 op_sel_hi:[1,0]
	v_mov_b32_e32 v83, 0
	v_mov_b32_dpp v89, v187 row_ror:2 row_mask:0xf bank_mask:0xf
	s_nop 0
	v_mov_b32_dpp v83, v187 row_ror:1 row_mask:0xf bank_mask:0xf
	v_cndmask_b32_e64 v89, v116, v89, s[10:11]
	v_cndmask_b32_e64 v83, v83, v115, s[8:9]
	v_pk_fma_f32 v[88:89], v[60:61], v[88:89], v[72:73]
	v_mov_b32_e32 v95, 0
	v_pk_fma_f32 v[82:83], v[64:65], v[82:83], v[88:89]
	v_rcp_f32_e32 v87, v87
	v_pk_fma_f32 v[82:83], v[186:187], v[68:69], v[82:83]
	s_nop 0
	v_mul_f32_e32 v88, 0xbfb8aa3b, v82
	v_mul_f32_e32 v89, 0xbfb8aa3b, v83
	v_exp_f32_e32 v88, v88
	v_exp_f32_e32 v89, v89
	v_rcp_f32_e32 v86, v86
	s_nop 0
	v_pk_mul_f32 v[84:85], v[84:85], v[86:87]
	v_pk_add_f32 v[86:87], v[88:89], 1.0 op_sel_hi:[1,0]
	v_mov_b32_e32 v88, v91
	v_div_scale_f32 v89, s[0:1], v87, v87, 1.0
	v_rcp_f32_e32 v90, v89
	v_pk_mul_f32 v[78:79], v[78:79], v[88:89] op_sel_hi:[1,0]
	v_mov_b32_e32 v97, 0
	v_pk_mul_f32 v[78:79], v[78:79], v[84:85]
	v_fma_f32 v84, -v89, v90, 1.0
	v_fmac_f32_e32 v90, v84, v90
	v_div_scale_f32 v84, vcc, 1.0, v87, 1.0
	v_mul_f32_e32 v85, v84, v90
	v_fma_f32 v91, -v89, v85, v84
	v_fmac_f32_e32 v85, v91, v90
	v_fma_f32 v84, -v89, v85, v84
	v_div_scale_f32 v89, s[0:1], v86, v86, 1.0
	v_rcp_f32_e32 v91, v89
	v_div_fmas_f32 v84, v84, v90, v85
	v_div_fixup_f32 v85, v84, v87, 1.0
	v_pk_mul_f32 v[80:81], v[80:81], v[88:89] op_sel_hi:[1,0]
	v_fma_f32 v84, -v89, v91, 1.0
	v_fmac_f32_e32 v91, v84, v91
	v_div_scale_f32 v84, vcc, 1.0, v86, 1.0
	v_mul_f32_e32 v87, v84, v91
	v_fma_f32 v90, -v89, v87, v84
	v_fmac_f32_e32 v87, v90, v91
	v_fma_f32 v84, -v89, v87, v84
	v_div_fmas_f32 v84, v84, v91, v87
	v_div_fixup_f32 v84, v84, v86, 1.0
	v_pk_mul_f32 v[82:83], v[82:83], v[84:85]
	v_mov_b32_e32 v86, 0
	v_mov_b32_e32 v87, 0
	v_pk_mul_f32 v[80:81], v[80:81], v[82:83]
	v_mov_b32_e32 v82, 0
	v_mov_b32_dpp v86, v180 row_ror:2 row_mask:0xf bank_mask:0xf
	v_mov_b32_e32 v84, 0
	v_mov_b32_dpp v87, v181 row_ror:2 row_mask:0xf bank_mask:0xf
	v_mov_b32_dpp v82, v180 row_ror:1 row_mask:0xf bank_mask:0xf
	v_mov_b32_dpp v84, v181 row_ror:1 row_mask:0xf bank_mask:0xf
	v_cndmask_b32_e64 v87, v126, v87, s[10:11]
	v_cndmask_b32_e64 v86, v118, v86, s[10:11]
	v_cndmask_b32_e64 v85, v84, v123, s[8:9]
	v_cndmask_b32_e64 v84, v82, v117, s[8:9]
	v_pk_fma_f32 v[86:87], v[42:43], v[86:87], v[54:55]
	v_mov_b32_e32 v89, 0
	v_pk_fma_f32 v[84:85], v[46:47], v[84:85], v[86:87]
	v_mov_b32_e32 v90, 0
	v_pk_fma_f32 v[84:85], v[180:181], v[50:51], v[84:85]
	v_mov_b32_dpp v89, v178 row_ror:1 row_mask:0xf bank_mask:0xf
	v_mul_f32_e32 v82, 0xbfb8aa3b, v84
	v_exp_f32_e32 v86, v82
	v_mul_f32_e32 v82, 0xbfb8aa3b, v85
	v_exp_f32_e32 v87, v82
	v_cndmask_b32_e64 v82, v89, v127, s[8:9]
	v_mov_b32_e32 v91, 0
	v_mov_b32_dpp v90, v178 row_ror:2 row_mask:0xf bank_mask:0xf
	v_pk_add_f32 v[86:87], v[86:87], 1.0 op_sel_hi:[1,0]
	v_mov_b32_e32 v83, 0
	v_mov_b32_dpp v91, v179 row_ror:2 row_mask:0xf bank_mask:0xf
	s_nop 0
	v_mov_b32_dpp v83, v179 row_ror:1 row_mask:0xf bank_mask:0xf
	v_cndmask_b32_e64 v91, v132, v91, s[10:11]
	v_cndmask_b32_e64 v90, v128, v90, s[10:11]
	v_cndmask_b32_e64 v83, v83, v129, s[8:9]
	v_pk_fma_f32 v[90:91], v[44:45], v[90:91], v[56:57]
	v_mov_b32_e32 v94, 0
	v_pk_fma_f32 v[82:83], v[48:49], v[82:83], v[90:91]
	v_rcp_f32_e32 v87, v87
	v_pk_fma_f32 v[82:83], v[178:179], v[52:53], v[82:83]
	s_nop 0
	v_mul_f32_e32 v90, 0xbfb8aa3b, v82
	v_mul_f32_e32 v91, 0xbfb8aa3b, v83
	v_exp_f32_e32 v90, v90
	v_exp_f32_e32 v91, v91
	v_rcp_f32_e32 v86, v86
	s_nop 0
	v_pk_mul_f32 v[84:85], v[84:85], v[86:87]
	v_pk_add_f32 v[90:91], v[90:91], 1.0 op_sel_hi:[1,0]
	v_mov_b32_dpp v95, v184 row_ror:2 row_mask:0xf bank_mask:0xf
	v_div_scale_f32 v89, s[0:1], v91, v91, 1.0
	v_rcp_f32_e32 v92, v89
	v_pk_mul_f32 v[74:75], v[74:75], v[88:89] op_sel_hi:[1,0]
	v_mov_b32_e32 v96, 0
; #define LAS __attribute__((address_space(3)))
; __device__ __forceinline__ size_t hidx(size_t r, int c) { return ((size_t)(c >> 6) * MTOT + r) * 64 + (c & 63); }
; __device__ __forceinline__ u32x4 pack8(const f32x4 a, const f32x4 b) { u32x4 w; w.x = cvt_pk_bf16(a[0], a[1]); w.y = cvt_pk_bf16(a[2], a[3]); w.z = cvt_pk_bf16(b[0], b[1]); w.w = cvt_pk_bf16(b[2], b[3]); return w; }
; __device__ __forceinline__ int halo_idx(int slot, int wc, int row, int ci) { return ((slot * 4 + wc) * 2 + row) * 32 + ci; }
; __device__ __forceinline__ float sigm(float x) { return 1.f / (1.f + __builtin_amdgcn_exp2f(-LOG2E * x)); }
;     __device__ __forceinline__ void operator()(const f32x4 (&acc)[2][2][4][2], const Unit& u, int wr, int wc, int fr, int fq) const {
;     ...
;             for (int m = 0; m < 4; ++m) { const int r = row0 + 128 * ai + 16 * m; const float rs = rsl[128 * ai + 64 * wr + 16 * m + fr]; f32x4 o[2];
; _Pragma("unroll")
;                 for (int n = 0; n < 2; ++n) { f32x4 p1, p2, q1, q2;
;                     if (m > 0) {
; _Pragma("unroll")
;                         for (int j = 0; j < 4; ++j) { q1[j] = row_from_below<1>(gs[ai][m - 1][n][j]); q2[j] = row_from_below<2>(gs[ai][m - 1][n][j]); } }
;                     else { const int slot = (2 * ai + wr) ? (2 * ai + wr) : 4 + (u.pm & 1);
;                         q1 = *(const LAS f32x4*)(hal + halo_idx(slot, wc, 1, ci0 + 4 * n)); q2 = *(const LAS f32x4*)(hal + halo_idx(slot, wc, fr == 0 ? 0 : 1, ci0 + 4 * n)); }
; _Pragma("unroll")
;                     for (int j = 0; j < 4; ++j) { p1[j] = row_from_below<1>(gs[ai][m][n][j]); p2[j] = row_from_below<2>(gs[ai][m][n][j]); }
;                     const f32x4 h1 = fr >= 1 ? p1 : q1, h0 = fr >= 2 ? p2 : q2;
;                     const f32x4 cv = bb[n] + w0[n] * h0 + w1[n] * h1 + w2[n] * gs[ai][m][n];
; _Pragma("unroll")
;                     for (int j = 0; j < 4; ++j) o[n][j] = cv[j] * sigm(cv[j]) * (acc[ai][1][m][n][j] * rs); }
;                 *(u32x4*)(H + hidx(r, ch0)) = pack8(o[0], o[1]); }
	v_pk_mul_f32 v[84:85], v[74:75], v[84:85]
	v_fma_f32 v74, -v89, v92, 1.0
	v_fmac_f32_e32 v92, v74, v92
	v_div_scale_f32 v74, vcc, 1.0, v91, 1.0
	v_mul_f32_e32 v75, v74, v92
	v_fma_f32 v86, -v89, v75, v74
	v_fmac_f32_e32 v75, v86, v92
	v_div_scale_f32 v86, s[0:1], v90, v90, 1.0
	v_rcp_f32_e32 v87, v86
	v_fma_f32 v74, -v89, v75, v74
	v_div_fmas_f32 v74, v74, v92, v75
	v_div_fixup_f32 v75, v74, v91, 1.0
	v_fma_f32 v74, -v86, v87, 1.0
	v_fmac_f32_e32 v87, v74, v87
	v_div_scale_f32 v74, vcc, 1.0, v90, 1.0
	v_mul_f32_e32 v89, v74, v87
	v_fma_f32 v91, -v86, v89, v74
	v_fmac_f32_e32 v89, v91, v87
	v_fma_f32 v74, -v86, v89, v74
	v_div_fmas_f32 v74, v74, v87, v89
	v_div_fixup_f32 v74, v74, v90, 1.0
	v_or_b32_e32 v86, 48, v122
	v_pk_mul_f32 v[74:75], v[82:83], v[74:75]
	v_pk_mul_f32 v[76:77], v[76:77], v[88:89] op_sel_hi:[1,0]
	v_ashrrev_i32_e32 v87, 31, v86
	v_pk_mul_f32 v[82:83], v[76:77], v[74:75]
	v_cvt_pk_bf16_f32 v74, v78, v79
	v_lshl_add_u64 v[78:79], s[48:49], 0, v[86:87]
	v_lshlrev_b64 v[78:79], 7, v[78:79]
	v_cvt_pk_bf16_f32 v75, v80, v81
	v_cvt_pk_bf16_f32 v76, v84, v85
	v_cvt_pk_bf16_f32 v77, v82, v83
	v_lshl_add_u64 v[78:79], v[156:157], 0, v[78:79]
	global_store_dwordx4 v[78:79], v[74:77], off
	ds_read_b32 v84, v146
	v_mov_b32_dpp v97, v185 row_ror:2 row_mask:0xf bank_mask:0xf
	v_add_u32_e32 v74, s74, v204
	ds_read_b128 v[88:91], v74 offset:128
	ds_read_b128 v[74:77], v74 offset:144
	ds_read_b128 v[100:103], v217
	v_mov_b32_dpp v94, v184 row_ror:1 row_mask:0xf bank_mask:0xf
	v_mov_b32_dpp v96, v185 row_ror:1 row_mask:0xf bank_mask:0xf
	v_mov_b32_e32 v87, 0
	s_waitcnt lgkmcnt(2)
	v_cndmask_b32_e64 v89, v96, v89, s[8:9]
	s_waitcnt lgkmcnt(0)
	v_cndmask_b32_e64 v93, v101, v97, s[10:11]
	v_cndmask_b32_e64 v92, v100, v95, s[10:11]
	v_cndmask_b32_e64 v88, v94, v88, s[8:9]
	v_pk_fma_f32 v[92:93], v[58:59], v[92:93], v[70:71]
	v_mov_b32_e32 v98, 0
	v_pk_fma_f32 v[88:89], v[62:63], v[88:89], v[92:93]
	v_mov_b32_dpp v87, v182 row_ror:2 row_mask:0xf bank_mask:0xf
	v_pk_fma_f32 v[92:93], v[184:185], v[66:67], v[88:89]
	v_mov_b32_dpp v98, v183 row_ror:2 row_mask:0xf bank_mask:0xf
	v_mul_f32_e32 v83, 0xbfb8aa3b, v92
	v_exp_f32_e32 v88, v83
	v_mul_f32_e32 v83, 0xbfb8aa3b, v93
	v_exp_f32_e32 v89, v83
	v_cndmask_b32_e64 v101, v103, v98, s[10:11]
	v_cndmask_b32_e64 v100, v102, v87, s[10:11]
	v_mov_b32_e32 v85, 0
	v_pk_add_f32 v[102:103], v[88:89], 1.0 op_sel_hi:[1,0]
	v_mov_b32_e32 v99, 0
	v_mov_b32_dpp v85, v182 row_ror:1 row_mask:0xf bank_mask:0xf
	s_nop 0
	v_mov_b32_dpp v99, v183 row_ror:1 row_mask:0xf bank_mask:0xf
	v_cndmask_b32_e64 v91, v99, v91, s[8:9]
	v_cndmask_b32_e64 v90, v85, v90, s[8:9]
	v_pk_fma_f32 v[88:89], v[60:61], v[100:101], v[72:73]
	v_pk_mul_f32 v[30:31], v[30:31], v[84:85] op_sel_hi:[1,0]
	v_pk_fma_f32 v[88:89], v[64:65], v[90:91], v[88:89]
	v_rcp_f32_e32 v91, v103
	v_pk_fma_f32 v[88:89], v[182:183], v[68:69], v[88:89]
	s_nop 0
	v_mul_f32_e32 v90, 0xbfb8aa3b, v88
	v_exp_f32_e32 v100, v90
	v_mul_f32_e32 v90, 0xbfb8aa3b, v89
	v_exp_f32_e32 v101, v90
	v_rcp_f32_e32 v90, v102
	s_nop 0
	v_pk_mul_f32 v[92:93], v[92:93], v[90:91]
	v_pk_add_f32 v[90:91], v[100:101], 1.0 op_sel_hi:[1,0]
	v_pk_mul_f32 v[30:31], v[30:31], v[92:93]
	ds_read_b128 v[78:81], v217 offset:16
	ds_read_b32 v86, v214 offset:704
	v_pk_mul_f32 v[32:33], v[32:33], v[84:85] op_sel_hi:[1,0]
	v_rcp_f32_e32 v91, v91
	v_pk_mul_f32 v[26:27], v[26:27], v[84:85] op_sel_hi:[1,0]
	v_rcp_f32_e32 v90, v90
	s_nop 0
	v_pk_mul_f32 v[88:89], v[88:89], v[90:91]
	v_mov_b32_e32 v91, 0
	v_pk_mul_f32 v[32:33], v[32:33], v[88:89]
	v_mov_b32_e32 v89, 0
	v_mov_b32_e32 v88, 0
	v_mov_b32_e32 v90, 0
	v_mov_b32_dpp v89, v176 row_ror:2 row_mask:0xf bank_mask:0xf
	v_mov_b32_dpp v91, v177 row_ror:2 row_mask:0xf bank_mask:0xf
	v_mov_b32_dpp v88, v176 row_ror:1 row_mask:0xf bank_mask:0xf
	v_mov_b32_dpp v90, v177 row_ror:1 row_mask:0xf bank_mask:0xf
	s_waitcnt lgkmcnt(1)
	v_cndmask_b32_e64 v79, v79, v91, s[10:11]
	v_cndmask_b32_e64 v78, v78, v89, s[10:11]
	v_cndmask_b32_e64 v75, v90, v75, s[8:9]
	v_cndmask_b32_e64 v74, v88, v74, s[8:9]
	v_pk_fma_f32 v[78:79], v[42:43], v[78:79], v[54:55]
	v_mov_b32_e32 v93, 0
	v_pk_fma_f32 v[74:75], v[46:47], v[74:75], v[78:79]
	v_mov_b32_e32 v101, 0
	v_pk_fma_f32 v[74:75], v[176:177], v[50:51], v[74:75]
	v_mov_b32_e32 v92, 0
	v_mul_f32_e32 v78, 0xbfb8aa3b, v74
	v_mul_f32_e32 v79, 0xbfb8aa3b, v75
	v_exp_f32_e32 v78, v78
	v_exp_f32_e32 v79, v79
	v_mov_b32_dpp v93, v174 row_ror:2 row_mask:0xf bank_mask:0xf
	v_mov_b32_e32 v100, 0
	v_mov_b32_dpp v101, v175 row_ror:2 row_mask:0xf bank_mask:0xf
	v_pk_add_f32 v[78:79], v[78:79], 1.0 op_sel_hi:[1,0]
	v_mov_b32_dpp v92, v174 row_ror:1 row_mask:0xf bank_mask:0xf
	v_mov_b32_dpp v100, v175 row_ror:1 row_mask:0xf bank_mask:0xf
	v_cndmask_b32_e64 v81, v81, v101, s[10:11]
	v_cndmask_b32_e64 v80, v80, v93, s[10:11]
	v_cndmask_b32_e64 v77, v100, v77, s[8:9]
	v_cndmask_b32_e64 v76, v92, v76, s[8:9]
	v_pk_fma_f32 v[80:81], v[44:45], v[80:81], v[56:57]
	v_add_u32_e32 v82, 0x80, v122
	v_pk_fma_f32 v[76:77], v[48:49], v[76:77], v[80:81]
	v_rcp_f32_e32 v79, v79
	v_pk_fma_f32 v[76:77], v[174:175], v[52:53], v[76:77]
	s_nop 0
	v_mul_f32_e32 v80, 0xbfb8aa3b, v76
	v_mul_f32_e32 v81, 0xbfb8aa3b, v77
	v_exp_f32_e32 v80, v80
	v_exp_f32_e32 v81, v81
	v_rcp_f32_e32 v78, v78
	s_nop 0
	v_pk_mul_f32 v[74:75], v[74:75], v[78:79]
	v_pk_add_f32 v[80:81], v[80:81], 1.0 op_sel_hi:[1,0]
	v_pk_mul_f32 v[74:75], v[26:27], v[74:75]
	v_pk_mul_f32 v[28:29], v[28:29], v[84:85] op_sel_hi:[1,0]
	v_rcp_f32_e32 v27, v81
	v_rcp_f32_e32 v26, v80
	s_nop 0
	v_pk_mul_f32 v[26:27], v[76:77], v[26:27]
	v_ashrrev_i32_e32 v83, 31, v82
	v_pk_mul_f32 v[76:77], v[28:29], v[26:27]
; #define LAS __attribute__((address_space(3)))
; __device__ __forceinline__ size_t hidx(size_t r, int c) { return ((size_t)(c >> 6) * MTOT + r) * 64 + (c & 63); }
; __device__ __forceinline__ u32x4 pack8(const f32x4 a, const f32x4 b) { u32x4 w; w.x = cvt_pk_bf16(a[0], a[1]); w.y = cvt_pk_bf16(a[2], a[3]); w.z = cvt_pk_bf16(b[0], b[1]); w.w = cvt_pk_bf16(b[2], b[3]); return w; }
; __device__ __forceinline__ int halo_idx(int slot, int wc, int row, int ci) { return ((slot * 4 + wc) * 2 + row) * 32 + ci; }
; __device__ __forceinline__ float sigm(float x) { return 1.f / (1.f + __builtin_amdgcn_exp2f(-LOG2E * x)); }
;     __device__ __forceinline__ void operator()(const f32x4 (&acc)[2][2][4][2], const Unit& u, int wr, int wc, int fr, int fq) const {
;     ...
;             for (int m = 0; m < 4; ++m) { const int r = row0 + 128 * ai + 16 * m; const float rs = rsl[128 * ai + 64 * wr + 16 * m + fr]; f32x4 o[2];
; _Pragma("unroll")
;                 for (int n = 0; n < 2; ++n) { f32x4 p1, p2, q1, q2;
;                     if (m > 0) {
; _Pragma("unroll")
;                         for (int j = 0; j < 4; ++j) { q1[j] = row_from_below<1>(gs[ai][m - 1][n][j]); q2[j] = row_from_below<2>(gs[ai][m - 1][n][j]); } }
;                     else { const int slot = (2 * ai + wr) ? (2 * ai + wr) : 4 + (u.pm & 1);
;                         q1 = *(const LAS f32x4*)(hal + halo_idx(slot, wc, 1, ci0 + 4 * n)); q2 = *(const LAS f32x4*)(hal + halo_idx(slot, wc, fr == 0 ? 0 : 1, ci0 + 4 * n)); }
; _Pragma("unroll")
;                     for (int j = 0; j < 4; ++j) { p1[j] = row_from_below<1>(gs[ai][m][n][j]); p2[j] = row_from_below<2>(gs[ai][m][n][j]); }
;                     const f32x4 h1 = fr >= 1 ? p1 : q1, h0 = fr >= 2 ? p2 : q2;
;                     const f32x4 cv = bb[n] + w0[n] * h0 + w1[n] * h1 + w2[n] * gs[ai][m][n];
; _Pragma("unroll")
;                     for (int j = 0; j < 4; ++j) o[n][j] = cv[j] * sigm(cv[j]) * (acc[ai][1][m][n][j] * rs); }
;                 *(u32x4*)(H + hidx(r, ch0)) = pack8(o[0], o[1]); }
	v_cvt_pk_bf16_f32 v26, v30, v31
	v_cvt_pk_bf16_f32 v29, v76, v77
	v_lshl_add_u64 v[30:31], s[48:49], 0, v[82:83]
	v_mov_b32_e32 v77, 0
	v_mov_b32_e32 v79, 0
	v_lshlrev_b64 v[30:31], 7, v[30:31]
	v_mov_b32_e32 v76, 0
	v_mov_b32_dpp v77, v110 row_ror:2 row_mask:0xf bank_mask:0xf
	v_mov_b32_e32 v78, 0
	v_mov_b32_dpp v79, v111 row_ror:2 row_mask:0xf bank_mask:0xf
	v_cvt_pk_bf16_f32 v27, v32, v33
	v_cvt_pk_bf16_f32 v28, v74, v75
	v_lshl_add_u64 v[30:31], v[156:157], 0, v[30:31]
	v_mov_b32_dpp v76, v110 row_ror:1 row_mask:0xf bank_mask:0xf
	v_mov_b32_dpp v78, v111 row_ror:1 row_mask:0xf bank_mask:0xf
	v_cndmask_b32_e64 v33, v97, v79, s[10:11]
	v_cndmask_b32_e64 v32, v95, v77, s[10:11]
	global_store_dwordx4 v[30:31], v[26:29], off
	v_cndmask_b32_e64 v31, v78, v96, s[8:9]
	v_cndmask_b32_e64 v30, v76, v94, s[8:9]
	v_pk_fma_f32 v[32:33], v[58:59], v[32:33], v[70:71]
	v_mov_b32_e32 v80, 0
	v_pk_fma_f32 v[30:31], v[62:63], v[30:31], v[32:33]
	v_mov_b32_e32 v81, 0
	v_pk_fma_f32 v[30:31], v[110:111], v[66:67], v[30:31]
	v_mov_b32_dpp v80, v112 row_ror:1 row_mask:0xf bank_mask:0xf
	v_mul_f32_e32 v28, 0xbfb8aa3b, v30
	v_exp_f32_e32 v32, v28
	v_mul_f32_e32 v28, 0xbfb8aa3b, v31
	v_exp_f32_e32 v33, v28
	v_mov_b32_e32 v83, 0
	v_cndmask_b32_e64 v28, v80, v85, s[8:9]
	v_mov_b32_dpp v81, v112 row_ror:2 row_mask:0xf bank_mask:0xf
	v_pk_add_f32 v[32:33], v[32:33], 1.0 op_sel_hi:[1,0]
	v_mov_b32_e32 v82, 0
	v_mov_b32_dpp v83, v113 row_ror:2 row_mask:0xf bank_mask:0xf
	s_nop 0
	v_mov_b32_dpp v82, v113 row_ror:1 row_mask:0xf bank_mask:0xf
	v_cndmask_b32_e64 v75, v98, v83, s[10:11]
	v_cndmask_b32_e64 v74, v87, v81, s[10:11]
	v_cndmask_b32_e64 v29, v82, v99, s[8:9]
	v_pk_fma_f32 v[74:75], v[60:61], v[74:75], v[72:73]
	ds_read2_b32 v[26:27], v214 offset0:144 offset1:160
	v_pk_fma_f32 v[28:29], v[64:65], v[28:29], v[74:75]
	v_rcp_f32_e32 v33, v33
	v_pk_fma_f32 v[28:29], v[112:113], v[68:69], v[28:29]
	s_nop 0
	v_mul_f32_e32 v74, 0xbfb8aa3b, v28
	v_mul_f32_e32 v75, 0xbfb8aa3b, v29
	v_exp_f32_e32 v74, v74
	v_exp_f32_e32 v75, v75
	v_rcp_f32_e32 v32, v32
	s_nop 0
	v_pk_mul_f32 v[30:31], v[30:31], v[32:33]
	v_pk_add_f32 v[74:75], v[74:75], 1.0 op_sel_hi:[1,0]
	s_waitcnt lgkmcnt(0)
	v_pk_mul_f32 v[22:23], v[22:23], v[26:27] op_sel_hi:[1,0]
	s_nop 0
	v_pk_mul_f32 v[22:23], v[22:23], v[30:31]
	v_mov_b32_e32 v94, 0
	v_mov_b32_e32 v87, 0
	v_rcp_f32_e32 v31, v75
	v_mov_b32_e32 v85, 0
	v_mov_b32_e32 v84, 0
	s_nop 0
	v_mov_b32_dpp v85, v106 row_ror:2 row_mask:0xf bank_mask:0xf
	v_mov_b32_dpp v94, v107 row_ror:2 row_mask:0xf bank_mask:0xf
	v_rcp_f32_e32 v30, v74
	v_mov_b32_dpp v84, v106 row_ror:1 row_mask:0xf bank_mask:0xf
	v_mov_b32_dpp v87, v107 row_ror:1 row_mask:0xf bank_mask:0xf
	v_cndmask_b32_e64 v33, v91, v94, s[10:11]
	v_cndmask_b32_e64 v32, v89, v85, s[10:11]
	v_pk_mul_f32 v[28:29], v[28:29], v[30:31]
	v_cndmask_b32_e64 v31, v87, v90, s[8:9]
	v_cndmask_b32_e64 v30, v84, v88, s[8:9]
	v_pk_fma_f32 v[32:33], v[42:43], v[32:33], v[54:55]
	v_pk_mul_f32 v[24:25], v[24:25], v[26:27] op_sel_hi:[1,0]
	v_pk_fma_f32 v[30:31], v[46:47], v[30:31], v[32:33]
	v_pk_mul_f32 v[24:25], v[24:25], v[28:29]
	v_pk_fma_f32 v[30:31], v[106:107], v[50:51], v[30:31]
	v_mov_b32_e32 v96, 0
	v_mul_f32_e32 v28, 0xbfb8aa3b, v30
	v_exp_f32_e32 v32, v28
	v_mul_f32_e32 v28, 0xbfb8aa3b, v31
	v_exp_f32_e32 v33, v28
	v_mov_b32_e32 v98, 0
	v_mov_b32_e32 v95, 0
	v_mov_b32_dpp v96, v108 row_ror:2 row_mask:0xf bank_mask:0xf
	v_pk_add_f32 v[32:33], v[32:33], 1.0 op_sel_hi:[1,0]
	v_mov_b32_e32 v97, 0
	v_mov_b32_dpp v98, v109 row_ror:2 row_mask:0xf bank_mask:0xf
	v_mov_b32_dpp v95, v108 row_ror:1 row_mask:0xf bank_mask:0xf
	v_mov_b32_dpp v97, v109 row_ror:1 row_mask:0xf bank_mask:0xf
	v_cndmask_b32_e64 v75, v101, v98, s[10:11]
	v_cndmask_b32_e64 v74, v93, v96, s[10:11]
	v_cndmask_b32_e64 v29, v97, v100, s[8:9]
	v_cndmask_b32_e64 v28, v95, v92, s[8:9]
	v_pk_fma_f32 v[74:75], v[44:45], v[74:75], v[56:57]
	v_pk_mul_f32 v[18:19], v[18:19], v[26:27] op_sel_hi:[1,0]
	v_pk_fma_f32 v[28:29], v[48:49], v[28:29], v[74:75]
	v_rcp_f32_e32 v33, v33
	v_pk_fma_f32 v[28:29], v[108:109], v[52:53], v[28:29]
	s_nop 0
	v_mul_f32_e32 v74, 0xbfb8aa3b, v28
	v_mul_f32_e32 v75, 0xbfb8aa3b, v29
	v_exp_f32_e32 v74, v74
	v_exp_f32_e32 v75, v75
	v_rcp_f32_e32 v32, v32
	s_nop 0
	v_pk_mul_f32 v[30:31], v[30:31], v[32:33]
	v_pk_add_f32 v[74:75], v[74:75], 1.0 op_sel_hi:[1,0]
	v_pk_mul_f32 v[30:31], v[18:19], v[30:31]
	v_pk_mul_f32 v[20:21], v[20:21], v[26:27] op_sel_hi:[1,0]
	v_pk_mul_f32 v[6:7], v[6:7], v[86:87] op_sel_hi:[1,0]
	v_pk_mul_f32 v[8:9], v[8:9], v[86:87] op_sel_hi:[1,0]
	v_rcp_f32_e32 v19, v75
	v_rcp_f32_e32 v18, v74
	v_add_u32_e32 v32, 0x90, v122
	v_pk_mul_f32 v[18:19], v[28:29], v[18:19]
	v_ashrrev_i32_e32 v33, 31, v32
	v_pk_mul_f32 v[28:29], v[20:21], v[18:19]
	v_cvt_pk_bf16_f32 v18, v22, v23
	v_lshl_add_u64 v[22:23], s[48:49], 0, v[32:33]
	v_cvt_pk_bf16_f32 v20, v30, v31
	v_cvt_pk_bf16_f32 v21, v28, v29
	v_lshlrev_b64 v[22:23], 7, v[22:23]
	v_mov_b32_e32 v29, 0
	v_mov_b32_e32 v31, 0
	v_cvt_pk_bf16_f32 v19, v24, v25
	v_lshl_add_u64 v[22:23], v[156:157], 0, v[22:23]
	v_mov_b32_e32 v28, 0
	v_mov_b32_dpp v29, v172 row_ror:2 row_mask:0xf bank_mask:0xf
	v_mov_b32_e32 v30, 0
	v_mov_b32_dpp v31, v173 row_ror:2 row_mask:0xf bank_mask:0xf
	global_store_dwordx4 v[22:23], v[18:21], off
	v_mov_b32_dpp v28, v172 row_ror:1 row_mask:0xf bank_mask:0xf
	v_mov_b32_dpp v30, v173 row_ror:1 row_mask:0xf bank_mask:0xf
	v_cndmask_b32_e64 v23, v79, v31, s[10:11]
	v_cndmask_b32_e64 v22, v77, v29, s[10:11]
	v_cndmask_b32_e64 v21, v30, v78, s[8:9]
	v_cndmask_b32_e64 v20, v28, v76, s[8:9]
	v_pk_fma_f32 v[22:23], v[58:59], v[22:23], v[70:71]
	v_mov_b32_e32 v33, 0
; #define LAS __attribute__((address_space(3)))
; __device__ __forceinline__ size_t hidx(size_t r, int c) { return ((size_t)(c >> 6) * MTOT + r) * 64 + (c & 63); }
; __device__ __forceinline__ u32x4 pack8(const f32x4 a, const f32x4 b) { u32x4 w; w.x = cvt_pk_bf16(a[0], a[1]); w.y = cvt_pk_bf16(a[2], a[3]); w.z = cvt_pk_bf16(b[0], b[1]); w.w = cvt_pk_bf16(b[2], b[3]); return w; }
; __device__ __forceinline__ float sigm(float x) { return 1.f / (1.f + __builtin_amdgcn_exp2f(-LOG2E * x)); }
; __device__ __forceinline__ int halo_idx(int slot, int wc, int row, int ci) { return ((slot * 4 + wc) * 2 + row) * 32 + ci; }
;     __device__ __forceinline__ void operator()(const f32x4 (&acc)[2][2][4][2], const Unit& u, int wr, int wc, int fr, int fq) const {
;     ...
;             for (int m = 0; m < 4; ++m) { const int r = row0 + 128 * ai + 16 * m; const float rs = rsl[128 * ai + 64 * wr + 16 * m + fr]; f32x4 o[2];
; _Pragma("unroll")
;                 for (int n = 0; n < 2; ++n) { f32x4 p1, p2, q1, q2;
;                     if (m > 0) {
; _Pragma("unroll")
;                         for (int j = 0; j < 4; ++j) { q1[j] = row_from_below<1>(gs[ai][m - 1][n][j]); q2[j] = row_from_below<2>(gs[ai][m - 1][n][j]); } }
;                     else { const int slot = (2 * ai + wr) ? (2 * ai + wr) : 4 + (u.pm & 1);
;                         q1 = *(const LAS f32x4*)(hal + halo_idx(slot, wc, 1, ci0 + 4 * n)); q2 = *(const LAS f32x4*)(hal + halo_idx(slot, wc, fr == 0 ? 0 : 1, ci0 + 4 * n)); }
; _Pragma("unroll")
;                     for (int j = 0; j < 4; ++j) { p1[j] = row_from_below<1>(gs[ai][m][n][j]); p2[j] = row_from_below<2>(gs[ai][m][n][j]); }
;                     const f32x4 h1 = fr >= 1 ? p1 : q1, h0 = fr >= 2 ? p2 : q2;
;                     const f32x4 cv = bb[n] + w0[n] * h0 + w1[n] * h1 + w2[n] * gs[ai][m][n];
; _Pragma("unroll")
;                     for (int j = 0; j < 4; ++j) o[n][j] = cv[j] * sigm(cv[j]) * (acc[ai][1][m][n][j] * rs); }
;                 *(u32x4*)(H + hidx(r, ch0)) = pack8(o[0], o[1]); }
	v_pk_fma_f32 v[20:21], v[62:63], v[20:21], v[22:23]
	v_mov_b32_e32 v75, 0
	v_pk_fma_f32 v[20:21], v[172:173], v[66:67], v[20:21]
	v_mov_b32_e32 v32, 0
	v_mul_f32_e32 v18, 0xbfb8aa3b, v20
	v_exp_f32_e32 v22, v18
	v_mul_f32_e32 v18, 0xbfb8aa3b, v21
	v_exp_f32_e32 v23, v18
	v_mov_b32_dpp v33, v170 row_ror:2 row_mask:0xf bank_mask:0xf
	v_mov_b32_e32 v74, 0
	v_mov_b32_dpp v75, v171 row_ror:2 row_mask:0xf bank_mask:0xf
	v_pk_add_f32 v[22:23], v[22:23], 1.0 op_sel_hi:[1,0]
	v_mov_b32_dpp v32, v170 row_ror:1 row_mask:0xf bank_mask:0xf
	v_mov_b32_dpp v74, v171 row_ror:1 row_mask:0xf bank_mask:0xf
	v_cndmask_b32_e64 v25, v83, v75, s[10:11]
	v_cndmask_b32_e64 v24, v81, v33, s[10:11]
	v_cndmask_b32_e64 v19, v74, v82, s[8:9]
	v_cndmask_b32_e64 v18, v32, v80, s[8:9]
	v_pk_fma_f32 v[24:25], v[60:61], v[24:25], v[72:73]
	v_mov_b32_e32 v78, 0
	v_pk_fma_f32 v[18:19], v[64:65], v[18:19], v[24:25]
	v_rcp_f32_e32 v23, v23
	v_pk_fma_f32 v[18:19], v[170:171], v[68:69], v[18:19]
	s_nop 0
	v_mul_f32_e32 v24, 0xbfb8aa3b, v18
	v_mul_f32_e32 v25, 0xbfb8aa3b, v19
	v_exp_f32_e32 v24, v24
	v_exp_f32_e32 v25, v25
	v_rcp_f32_e32 v22, v22
	s_nop 0
	v_pk_mul_f32 v[20:21], v[20:21], v[22:23]
	v_pk_add_f32 v[22:23], v[24:25], 1.0 op_sel_hi:[1,0]
	v_mov_b32_e32 v24, v27
	v_div_scale_f32 v25, s[0:1], v23, v23, 1.0
	v_rcp_f32_e32 v26, v25
	v_pk_mul_f32 v[14:15], v[14:15], v[24:25] op_sel_hi:[1,0]
	v_mov_b32_e32 v76, 0
	v_pk_mul_f32 v[14:15], v[14:15], v[20:21]
	v_fma_f32 v20, -v25, v26, 1.0
	v_fmac_f32_e32 v26, v20, v26
	v_div_scale_f32 v20, vcc, 1.0, v23, 1.0
	v_mul_f32_e32 v21, v20, v26
	v_fma_f32 v27, -v25, v21, v20
	v_fmac_f32_e32 v21, v27, v26
	v_fma_f32 v20, -v25, v21, v20
	v_div_scale_f32 v25, s[0:1], v22, v22, 1.0
	v_rcp_f32_e32 v27, v25
	v_div_fmas_f32 v20, v20, v26, v21
	v_div_fixup_f32 v21, v20, v23, 1.0
	v_pk_mul_f32 v[16:17], v[16:17], v[24:25] op_sel_hi:[1,0]
	v_fma_f32 v20, -v25, v27, 1.0
	v_fmac_f32_e32 v27, v20, v27
	v_div_scale_f32 v20, vcc, 1.0, v22, 1.0
	v_mul_f32_e32 v23, v20, v27
	v_fma_f32 v26, -v25, v23, v20
	v_fmac_f32_e32 v23, v26, v27
	v_fma_f32 v20, -v25, v23, v20
	v_div_fmas_f32 v20, v20, v27, v23
	v_mov_b32_e32 v25, 0
	v_mov_b32_dpp v76, v168 row_ror:2 row_mask:0xf bank_mask:0xf
	v_mov_b32_e32 v77, 0
	v_mov_b32_dpp v78, v169 row_ror:2 row_mask:0xf bank_mask:0xf
	v_div_fixup_f32 v20, v20, v22, 1.0
	v_mov_b32_dpp v25, v168 row_ror:1 row_mask:0xf bank_mask:0xf
	v_mov_b32_dpp v77, v169 row_ror:1 row_mask:0xf bank_mask:0xf
	v_cndmask_b32_e64 v23, v94, v78, s[10:11]
	v_cndmask_b32_e64 v22, v85, v76, s[10:11]
	v_pk_mul_f32 v[18:19], v[18:19], v[20:21]
	v_cndmask_b32_e64 v21, v77, v87, s[8:9]
	v_cndmask_b32_e64 v20, v25, v84, s[8:9]
	v_pk_fma_f32 v[22:23], v[42:43], v[22:23], v[54:55]
	v_pk_mul_f32 v[16:17], v[16:17], v[18:19]
	v_pk_fma_f32 v[20:21], v[46:47], v[20:21], v[22:23]
	v_mov_b32_e32 v80, 0
	v_pk_fma_f32 v[20:21], v[168:169], v[50:51], v[20:21]
	v_mov_b32_e32 v82, 0
	v_mul_f32_e32 v18, 0xbfb8aa3b, v20
	v_exp_f32_e32 v22, v18
	v_mul_f32_e32 v18, 0xbfb8aa3b, v21
	v_exp_f32_e32 v23, v18
	v_mov_b32_e32 v79, 0
	v_mov_b32_dpp v80, v166 row_ror:2 row_mask:0xf bank_mask:0xf
	v_mov_b32_e32 v81, 0
	v_pk_add_f32 v[22:23], v[22:23], 1.0 op_sel_hi:[1,0]
	v_mov_b32_dpp v82, v167 row_ror:2 row_mask:0xf bank_mask:0xf
	v_mov_b32_dpp v79, v166 row_ror:1 row_mask:0xf bank_mask:0xf
	v_mov_b32_dpp v81, v167 row_ror:1 row_mask:0xf bank_mask:0xf
	v_cndmask_b32_e64 v27, v98, v82, s[10:11]
	v_cndmask_b32_e64 v26, v96, v80, s[10:11]
	v_cndmask_b32_e64 v19, v81, v97, s[8:9]
	v_cndmask_b32_e64 v18, v79, v95, s[8:9]
	v_pk_fma_f32 v[26:27], v[44:45], v[26:27], v[56:57]
	v_pk_mul_f32 v[10:11], v[10:11], v[24:25] op_sel_hi:[1,0]
	v_pk_fma_f32 v[18:19], v[48:49], v[18:19], v[26:27]
	v_rcp_f32_e32 v23, v23
	v_pk_fma_f32 v[18:19], v[166:167], v[52:53], v[18:19]
	s_nop 0
	v_mul_f32_e32 v26, 0xbfb8aa3b, v18
	v_mul_f32_e32 v27, 0xbfb8aa3b, v19
	v_exp_f32_e32 v26, v26
	v_exp_f32_e32 v27, v27
	v_rcp_f32_e32 v22, v22
	s_nop 0
	v_pk_mul_f32 v[20:21], v[20:21], v[22:23]
	v_pk_add_f32 v[26:27], v[26:27], 1.0 op_sel_hi:[1,0]
	v_pk_mul_f32 v[20:21], v[10:11], v[20:21]
	v_pk_mul_f32 v[12:13], v[12:13], v[24:25] op_sel_hi:[1,0]
	v_pk_mul_f32 v[2:3], v[2:3], v[86:87] op_sel_hi:[1,0]
	v_pk_mul_f32 v[4:5], v[4:5], v[86:87] op_sel_hi:[1,0]
	v_div_scale_f32 v22, s[0:1], v26, v26, 1.0
	v_rcp_f32_e32 v23, v22
	v_rcp_f32_e32 v11, v27
	v_fma_f32 v10, -v22, v23, 1.0
	v_fmac_f32_e32 v23, v10, v23
	v_div_scale_f32 v10, vcc, 1.0, v26, 1.0
	v_mul_f32_e32 v27, v10, v23
	v_fma_f32 v83, -v22, v27, v10
	v_fmac_f32_e32 v27, v83, v23
	v_fma_f32 v10, -v22, v27, v10
	v_div_fmas_f32 v10, v10, v23, v27
	v_div_fixup_f32 v10, v10, v26, 1.0
	v_add_u32_e32 v22, 0xa0, v122
	v_pk_mul_f32 v[10:11], v[18:19], v[10:11]
	v_ashrrev_i32_e32 v23, 31, v22
	v_pk_mul_f32 v[18:19], v[12:13], v[10:11]
	v_cvt_pk_bf16_f32 v10, v14, v15
	v_lshl_add_u64 v[14:15], s[48:49], 0, v[22:23]
	v_lshlrev_b64 v[14:15], 7, v[14:15]
	v_cvt_pk_bf16_f32 v11, v16, v17
	v_cvt_pk_bf16_f32 v12, v20, v21
	v_cvt_pk_bf16_f32 v13, v18, v19
	v_lshl_add_u64 v[14:15], v[156:157], 0, v[14:15]
	global_store_dwordx4 v[14:15], v[10:13], off
	v_mov_b32_e32 v14, 0
	v_mov_b32_e32 v15, 0
	v_mov_b32_e32 v10, 0
	v_mov_b32_dpp v14, v38 row_ror:2 row_mask:0xf bank_mask:0xf
	v_mov_b32_e32 v12, 0
; #define LAS __attribute__((address_space(3)))
; __device__ __forceinline__ size_t hidx(size_t r, int c) { return ((size_t)(c >> 6) * MTOT + r) * 64 + (c & 63); }
; __device__ __forceinline__ u32x4 pack8(const f32x4 a, const f32x4 b) { u32x4 w; w.x = cvt_pk_bf16(a[0], a[1]); w.y = cvt_pk_bf16(a[2], a[3]); w.z = cvt_pk_bf16(b[0], b[1]); w.w = cvt_pk_bf16(b[2], b[3]); return w; }
; __device__ __forceinline__ float sigm(float x) { return 1.f / (1.f + __builtin_amdgcn_exp2f(-LOG2E * x)); }
; __device__ __forceinline__ int halo_idx(int slot, int wc, int row, int ci) { return ((slot * 4 + wc) * 2 + row) * 32 + ci; }
;     __device__ __forceinline__ void operator()(const f32x4 (&acc)[2][2][4][2], const Unit& u, int wr, int wc, int fr, int fq) const {
;     ...
;             for (int m = 0; m < 4; ++m) { const int r = row0 + 128 * ai + 16 * m; const float rs = rsl[128 * ai + 64 * wr + 16 * m + fr]; f32x4 o[2];
; _Pragma("unroll")
;                 for (int n = 0; n < 2; ++n) { f32x4 p1, p2, q1, q2;
;                     if (m > 0) {
; _Pragma("unroll")
;                         for (int j = 0; j < 4; ++j) { q1[j] = row_from_below<1>(gs[ai][m - 1][n][j]); q2[j] = row_from_below<2>(gs[ai][m - 1][n][j]); } }
;                     else { const int slot = (2 * ai + wr) ? (2 * ai + wr) : 4 + (u.pm & 1);
;                         q1 = *(const LAS f32x4*)(hal + halo_idx(slot, wc, 1, ci0 + 4 * n)); q2 = *(const LAS f32x4*)(hal + halo_idx(slot, wc, fr == 0 ? 0 : 1, ci0 + 4 * n)); }
; _Pragma("unroll")
;                     for (int j = 0; j < 4; ++j) { p1[j] = row_from_below<1>(gs[ai][m][n][j]); p2[j] = row_from_below<2>(gs[ai][m][n][j]); }
;                     const f32x4 h1 = fr >= 1 ? p1 : q1, h0 = fr >= 2 ? p2 : q2;
;                     const f32x4 cv = bb[n] + w0[n] * h0 + w1[n] * h1 + w2[n] * gs[ai][m][n];
; _Pragma("unroll")
;                     for (int j = 0; j < 4; ++j) o[n][j] = cv[j] * sigm(cv[j]) * (acc[ai][1][m][n][j] * rs); }
;                 *(u32x4*)(H + hidx(r, ch0)) = pack8(o[0], o[1]); }
	v_mov_b32_dpp v15, v39 row_ror:2 row_mask:0xf bank_mask:0xf
	v_mov_b32_dpp v10, v38 row_ror:1 row_mask:0xf bank_mask:0xf
	v_mov_b32_dpp v12, v39 row_ror:1 row_mask:0xf bank_mask:0xf
	v_cndmask_b32_e64 v15, v31, v15, s[10:11]
	v_cndmask_b32_e64 v14, v29, v14, s[10:11]
	v_cndmask_b32_e64 v13, v12, v30, s[8:9]
	v_cndmask_b32_e64 v12, v10, v28, s[8:9]
	v_pk_fma_f32 v[14:15], v[58:59], v[14:15], v[70:71]
	v_mov_b32_e32 v16, 0
	v_pk_fma_f32 v[12:13], v[62:63], v[12:13], v[14:15]
	v_mov_b32_e32 v18, 0
	v_pk_fma_f32 v[12:13], v[38:39], v[66:67], v[12:13]
	v_mov_b32_dpp v16, v40 row_ror:1 row_mask:0xf bank_mask:0xf
	v_mul_f32_e32 v10, 0xbfb8aa3b, v12
	v_exp_f32_e32 v14, v10
	v_mul_f32_e32 v10, 0xbfb8aa3b, v13
	v_exp_f32_e32 v15, v10
	v_mov_b32_dpp v18, v40 row_ror:2 row_mask:0xf bank_mask:0xf
	v_cndmask_b32_e64 v10, v16, v32, s[8:9]
	v_cndmask_b32_e64 v16, v33, v18, s[10:11]
	v_pk_add_f32 v[14:15], v[14:15], 1.0 op_sel_hi:[1,0]
	v_mov_b32_e32 v17, 0
	v_mov_b32_e32 v11, 0
	s_nop 0
	v_mov_b32_dpp v17, v41 row_ror:2 row_mask:0xf bank_mask:0xf
	v_cndmask_b32_e64 v17, v75, v17, s[10:11]
	v_mov_b32_dpp v11, v41 row_ror:1 row_mask:0xf bank_mask:0xf
	v_cndmask_b32_e64 v11, v11, v74, s[8:9]
	v_pk_fma_f32 v[16:17], v[60:61], v[16:17], v[72:73]
	s_nop 0
	v_pk_fma_f32 v[10:11], v[64:65], v[10:11], v[16:17]
	v_rcp_f32_e32 v15, v15
	v_pk_fma_f32 v[10:11], v[40:41], v[68:69], v[10:11]
	s_nop 0
	v_mul_f32_e32 v16, 0xbfb8aa3b, v10
	v_mul_f32_e32 v17, 0xbfb8aa3b, v11
	v_exp_f32_e32 v16, v16
	v_exp_f32_e32 v17, v17
	v_rcp_f32_e32 v14, v14
	s_nop 0
	v_pk_mul_f32 v[12:13], v[12:13], v[14:15]
	v_pk_add_f32 v[16:17], v[16:17], 1.0 op_sel_hi:[1,0]
	v_pk_mul_f32 v[6:7], v[6:7], v[12:13]
	s_nop 0
	v_rcp_f32_e32 v13, v17
	v_rcp_f32_e32 v12, v16
	s_nop 0
	v_pk_mul_f32 v[10:11], v[10:11], v[12:13]
	v_mov_b32_e32 v14, 0
	v_mov_b32_e32 v15, 0
	v_pk_mul_f32 v[8:9], v[8:9], v[10:11]
	v_mov_b32_e32 v10, 0
	v_mov_b32_dpp v14, v34 row_ror:2 row_mask:0xf bank_mask:0xf
	v_mov_b32_e32 v12, 0
	v_mov_b32_dpp v15, v35 row_ror:2 row_mask:0xf bank_mask:0xf
	v_mov_b32_dpp v10, v34 row_ror:1 row_mask:0xf bank_mask:0xf
	v_mov_b32_dpp v12, v35 row_ror:1 row_mask:0xf bank_mask:0xf
	v_cndmask_b32_e64 v15, v78, v15, s[10:11]
	v_cndmask_b32_e64 v14, v76, v14, s[10:11]
	v_cndmask_b32_e64 v13, v12, v77, s[8:9]
	v_cndmask_b32_e64 v12, v10, v25, s[8:9]
	v_pk_fma_f32 v[14:15], v[42:43], v[14:15], v[54:55]
	v_mov_b32_e32 v16, 0
	v_pk_fma_f32 v[12:13], v[46:47], v[12:13], v[14:15]
	v_mov_b32_e32 v18, 0
	v_pk_fma_f32 v[12:13], v[34:35], v[50:51], v[12:13]
	v_mov_b32_dpp v16, v36 row_ror:1 row_mask:0xf bank_mask:0xf
	v_mul_f32_e32 v10, 0xbfb8aa3b, v12
	v_exp_f32_e32 v14, v10
	v_mul_f32_e32 v10, 0xbfb8aa3b, v13
	v_exp_f32_e32 v15, v10
	v_mov_b32_dpp v18, v36 row_ror:2 row_mask:0xf bank_mask:0xf
	v_cndmask_b32_e64 v10, v16, v79, s[8:9]
	v_cndmask_b32_e64 v16, v80, v18, s[10:11]
	v_pk_add_f32 v[14:15], v[14:15], 1.0 op_sel_hi:[1,0]
	v_mov_b32_e32 v17, 0
	v_mov_b32_e32 v11, 0
	s_nop 0
	v_mov_b32_dpp v17, v37 row_ror:2 row_mask:0xf bank_mask:0xf
	v_cndmask_b32_e64 v17, v82, v17, s[10:11]
	v_mov_b32_dpp v11, v37 row_ror:1 row_mask:0xf bank_mask:0xf
	v_cndmask_b32_e64 v11, v11, v81, s[8:9]
	v_pk_fma_f32 v[16:17], v[44:45], v[16:17], v[56:57]
	s_nop 0
	v_pk_fma_f32 v[10:11], v[48:49], v[10:11], v[16:17]
	v_div_scale_f32 v18, s[0:1], v14, v14, 1.0
	v_rcp_f32_e32 v20, v18
	v_rcp_f32_e32 v15, v15
	v_pk_fma_f32 v[10:11], v[36:37], v[52:53], v[10:11]
	v_fma_f32 v16, -v18, v20, 1.0
	v_fmac_f32_e32 v20, v16, v20
	v_div_scale_f32 v16, vcc, 1.0, v14, 1.0
	v_mul_f32_e32 v19, v16, v20
	v_fma_f32 v17, -v18, v19, v16
	v_fmac_f32_e32 v19, v17, v20
	v_fma_f32 v18, -v18, v19, v16
	v_mul_f32_e32 v16, 0xbfb8aa3b, v10
	v_mul_f32_e32 v17, 0xbfb8aa3b, v11
	v_exp_f32_e32 v16, v16
	v_exp_f32_e32 v17, v17
	v_div_fmas_f32 v18, v18, v20, v19
	v_div_fixup_f32 v14, v18, v14, 1.0
	v_pk_mul_f32 v[12:13], v[12:13], v[14:15]
	v_pk_add_f32 v[16:17], v[16:17], 1.0 op_sel_hi:[1,0]
	v_pk_mul_f32 v[12:13], v[2:3], v[12:13]
	v_div_scale_f32 v18, s[0:1], v17, v17, 1.0
	v_rcp_f32_e32 v19, v18
	s_nop 0
	v_fma_f32 v2, -v18, v19, 1.0
	v_fmac_f32_e32 v19, v2, v19
	v_div_scale_f32 v2, vcc, 1.0, v17, 1.0
	v_mul_f32_e32 v3, v2, v19
	v_fma_f32 v14, -v18, v3, v2
	v_fmac_f32_e32 v3, v14, v19
	v_div_scale_f32 v14, s[0:1], v16, v16, 1.0
	v_rcp_f32_e32 v15, v14
	v_fma_f32 v2, -v18, v3, v2
	v_div_fmas_f32 v2, v2, v19, v3
	v_div_fixup_f32 v3, v2, v17, 1.0
	v_fma_f32 v2, -v14, v15, 1.0
	v_fmac_f32_e32 v15, v2, v15
	v_div_scale_f32 v2, vcc, 1.0, v16, 1.0
	v_mul_f32_e32 v17, v2, v15
	v_fma_f32 v18, -v14, v17, v2
	v_fmac_f32_e32 v17, v18, v15
	v_fma_f32 v2, -v14, v17, v2
	v_div_fmas_f32 v2, v2, v15, v17
	v_div_fixup_f32 v2, v2, v16, 1.0
	v_add_u32_e32 v14, 0xb0, v122
	v_pk_mul_f32 v[2:3], v[10:11], v[2:3]
	v_ashrrev_i32_e32 v15, 31, v14
	v_pk_mul_f32 v[10:11], v[4:5], v[2:3]
	v_cvt_pk_bf16_f32 v2, v6, v7
	v_lshl_add_u64 v[6:7], s[48:49], 0, v[14:15]
	v_lshlrev_b64 v[6:7], 7, v[6:7]
	v_cvt_pk_bf16_f32 v3, v8, v9
	v_cvt_pk_bf16_f32 v4, v12, v13
	v_cvt_pk_bf16_f32 v5, v10, v11
	v_lshl_add_u64 v[6:7], v[156:157], 0, v[6:7]
	s_mov_b64 s[0:1], -1
	global_store_dwordx4 v[6:7], v[2:5], off
	s_cbranch_scc1 .LBB0_1073
	s_andn2_b64 vcc, exec, s[42:43]
	s_cbranch_vccnz .LBB0_1072
	s_barrier
	s_branch .LBB0_1072

.LBB0_1094:
	s_or_b64 exec, exec, s[22:23]
	s_waitcnt vmcnt(0) lgkmcnt(1)
	v_pk_fma_f32 v[46:47], v[46:47], v[58:59], v[62:63]
	s_waitcnt lgkmcnt(0)
	v_pk_fma_f32 v[22:23], v[22:23], v[34:35], v[42:43]
	v_pk_fma_f32 v[26:27], v[26:27], v[50:51], v[46:47]
	v_pk_fma_f32 v[10:11], v[10:11], v[30:31], v[22:23]
	v_pk_fma_f32 v[18:19], v[18:19], v[54:55], v[26:27]
	v_pk_fma_f32 v[6:7], v[6:7], v[38:39], v[10:11]
	v_mul_f32_e32 v26, 0xbfb8aa3b, v18
	v_mul_f32_e32 v27, 0xbfb8aa3b, v19
	v_exp_f32_e32 v26, v26
	v_exp_f32_e32 v27, v27
	v_mul_f32_e32 v10, 0xbfb8aa3b, v6
	v_mul_f32_e32 v11, 0xbfb8aa3b, v7
	v_exp_f32_e32 v10, v10
	v_pk_add_f32 v[26:27], v[26:27], 1.0 op_sel_hi:[1,0]
	v_exp_f32_e32 v11, v11
	s_nop 0
	v_pk_add_f32 v[10:11], v[10:11], 1.0 op_sel_hi:[1,0]
	v_rcp_f32_e32 v27, v27
	v_pk_fma_f32 v[46:47], v[48:49], v[60:61], v[64:65]
	s_nop 0
	v_pk_fma_f32 v[28:29], v[28:29], v[52:53], v[46:47]
	s_nop 0
	v_pk_fma_f32 v[20:21], v[20:21], v[56:57], v[28:29]
	s_nop 0
	v_mul_f32_e32 v28, 0xbfb8aa3b, v20
	v_mul_f32_e32 v29, 0xbfb8aa3b, v21
	v_exp_f32_e32 v28, v28
	v_exp_f32_e32 v29, v29
	v_rcp_f32_e32 v26, v26
	s_nop 0
	v_pk_mul_f32 v[18:19], v[18:19], v[26:27]
	v_pk_add_f32 v[28:29], v[28:29], 1.0 op_sel_hi:[1,0]
	v_pk_mul_f32 v[14:15], v[14:15], v[18:19]
	s_nop 0
	v_rcp_f32_e32 v19, v29
	v_rcp_f32_e32 v18, v28
	s_nop 0
	v_pk_mul_f32 v[18:19], v[20:21], v[18:19]
	s_nop 0
	v_pk_mul_f32 v[16:17], v[16:17], v[18:19]
	v_rcp_f32_e32 v11, v11
	v_pk_fma_f32 v[18:19], v[24:25], v[36:37], v[44:45]
	s_nop 0
	v_pk_fma_f32 v[12:13], v[12:13], v[32:33], v[18:19]
	s_nop 0
	v_pk_fma_f32 v[8:9], v[8:9], v[40:41], v[12:13]
	s_nop 0
	v_mul_f32_e32 v12, 0xbfb8aa3b, v8
	v_mul_f32_e32 v13, 0xbfb8aa3b, v9
	v_exp_f32_e32 v12, v12
	v_exp_f32_e32 v13, v13
	v_rcp_f32_e32 v10, v10
	s_nop 0
	v_pk_mul_f32 v[6:7], v[6:7], v[10:11]
	v_pk_add_f32 v[12:13], v[12:13], 1.0 op_sel_hi:[1,0]
	s_nop 0
	v_pk_mul_f32 v[6:7], v[2:3], v[6:7]
	v_rcp_f32_e32 v3, v13
	v_rcp_f32_e32 v2, v12
	s_nop 0
	v_pk_mul_f32 v[2:3], v[8:9], v[2:3]
	s_ashr_i32 s22, s24, 6
	v_pk_mul_f32 v[8:9], v[4:5], v[2:3]
	v_cvt_pk_bf16_f32 v4, v6, v7
	v_mad_i64_i32 v[6:7], s[22:23], s22, v99, v[74:75]
	v_cvt_pk_bf16_f32 v5, v8, v9
	v_and_b32_e32 v8, 56, v76
	v_lshlrev_b64 v[6:7], 7, v[6:7]
	v_lshl_add_u64 v[6:7], s[12:13], 0, v[6:7]
	v_lshlrev_b32_e32 v66, 1, v8
	v_cvt_pk_bf16_f32 v2, v14, v15
	v_cvt_pk_bf16_f32 v3, v16, v17
	v_lshl_add_u64 v[6:7], v[6:7], 0, v[66:67]
	global_store_dwordx4 v[6:7], v[2:5], off
